# speedup vs baseline: 1.0042x; 1.0042x over previous
; #define LAS __attribute__((address_space(3)))
; __device__ __forceinline__ void build_rtab(unsigned char* ws, LAS float* rtab, int pm) {
;     int t = threadIdx.x; asm volatile("" : "+v"(t));
;     if (t < 256) { const float* sp = (const float*)(ws + WS_SSQ) + (size_t)(pm * 256 + t) * 32; float a = 0.f;
; #pragma unroll
;         for (int j = 0; j < 8; ++j) { const f32x4 v = *(const f32x4*)(sp + 4 * j); a += (v[0] + v[1]) + (v[2] + v[3]); }
;         rtab[t] = __builtin_amdgcn_rsqf(a * (1.0f / DM) + RMS_EPS); }
.LBB0_68:
	v_readlane_b32 s8, v255, 33
	v_mov_b32_e32 v128, v210
	v_mov_b32_e32 v136, v211
	s_mov_b64 s[6:7], s[94:95]
	v_mov_b32_e32 v129, s8
	ds_read_b32 v129, v129
	s_lshl_b32 s41, s22, 8
	s_waitcnt lgkmcnt(0)
	v_cmp_eq_u32_e32 vcc, s22, v129
	s_cbranch_vccnz .LBB0_74
	s_waitcnt lgkmcnt(0)
	v_mov_b32_e32 v129, v230
	s_movk_i32 s8, 0x100
	s_barrier
	s_nop 0
	v_cmp_gt_i32_e32 vcc, s8, v129
	s_and_saveexec_b64 s[8:9], vcc
	s_cbranch_execz .LBB0_71
	v_add_u32_e32 v130, s41, v129
	v_ashrrev_i32_e32 v131, 31, v130
	v_lshlrev_b64 v[130:131], 7, v[130:131]
	v_lshl_add_u64 v[130:131], s[6:7], 0, v[130:131]
	s_mov_b64 s[74:75], 0x1a400000
	v_lshl_add_u64 v[134:135], v[130:131], 0, s[74:75]
	v_add_co_u32_e32 v130, vcc, 0x1a400000, v130
	v_lshl_add_u32 v129, v129, 2, 0
	s_nop 0
	v_addc_co_u32_e32 v131, vcc, 0, v131, vcc
	global_load_dwordx4 v[130:133], v[130:131], off
	s_nop 0
	global_load_dwordx4 v[138:141], v[134:135], off offset:16
	global_load_dwordx4 v[178:181], v[134:135], off offset:32
	global_load_dwordx4 v[184:187], v[134:135], off offset:48
	v_add_u32_e32 v129, 0x22100, v129
	s_waitcnt vmcnt(0) lgkmcnt(0)
	v_mov_b32_e32 v142, v130
	v_mov_b32_e32 v143, v138
	v_mov_b32_e32 v138, v131
	v_pk_add_f32 v[130:131], v[142:143], v[138:139]
	v_mov_b32_e32 v138, v132
	v_mov_b32_e32 v139, v140
	v_mov_b32_e32 v140, v133
	v_pk_add_f32 v[132:133], v[138:139], v[140:141]
	s_nop 0
	v_pk_add_f32 v[130:131], v[130:131], v[132:133]
	s_nop 0
	v_add_f32_e32 v130, 0, v130
	v_add_f32_e32 v138, v130, v131
	v_mov_b32_e32 v130, v178
	v_mov_b32_e32 v131, v179
	v_mov_b32_e32 v132, v180
	v_mov_b32_e32 v133, v181
	v_mov_b32_e32 v140, v131
	v_mov_b32_e32 v141, v132
	v_mov_b32_e32 v131, v133
	v_pk_add_f32 v[130:131], v[140:141], v[130:131]
	s_nop 0
	v_pk_add_f32 v[140:141], v[130:131], v[130:131] op_sel:[0,1] op_sel_hi:[1,0]
	v_mov_b32_e32 v130, v184
	v_mov_b32_e32 v131, v185
	v_mov_b32_e32 v132, v186
	v_mov_b32_e32 v133, v187
	v_add_f32_e32 v142, v130, v131
	v_add_f32_e32 v144, v132, v133
	global_load_dwordx4 v[130:133], v[134:135], off offset:64
	global_load_dwordx4 v[178:181], v[134:135], off offset:80
	global_load_dwordx4 v[184:187], v[134:135], off offset:96
	s_waitcnt vmcnt(0) lgkmcnt(0)
	v_mov_b32_e32 v139, v130
	v_mov_b32_e32 v141, v131
	v_mov_b32_e32 v143, v132
	v_mov_b32_e32 v145, v133
	v_pk_add_f32 v[130:131], v[138:139], v[140:141]
	v_pk_add_f32 v[132:133], v[142:143], v[144:145]
	s_nop 0
	v_pk_add_f32 v[130:131], v[130:131], v[132:133]
	s_nop 0
	v_pk_add_f32 v[138:139], v[130:131], v[130:131] op_sel:[0,1] op_sel_hi:[1,0]
	v_mov_b32_e32 v130, v178
	v_mov_b32_e32 v131, v179
	v_mov_b32_e32 v132, v180
	v_mov_b32_e32 v133, v181
	global_load_dwordx4 v[178:181], v[134:135], off offset:112
	v_mov_b32_e32 v140, v131
	v_mov_b32_e32 v141, v132
	v_mov_b32_e32 v131, v133
	v_pk_add_f32 v[130:131], v[140:141], v[130:131]
	s_nop 0
	v_pk_add_f32 v[140:141], v[130:131], v[130:131] op_sel:[0,1] op_sel_hi:[1,0]
	v_mov_b32_e32 v130, v184
	v_mov_b32_e32 v131, v185
	v_mov_b32_e32 v132, v186
	v_mov_b32_e32 v133, v187
	v_add_f32_e32 v142, v130, v131
	v_add_f32_e32 v144, v132, v133
	s_waitcnt vmcnt(0) lgkmcnt(0)
	v_mov_b32_e32 v130, v178
	v_mov_b32_e32 v131, v179
	v_mov_b32_e32 v132, v180
	v_mov_b32_e32 v133, v181
	v_mov_b32_e32 v139, v130
	v_mov_b32_e32 v141, v131
	v_mov_b32_e32 v143, v132
	v_mov_b32_e32 v145, v133
	v_pk_add_f32 v[130:131], v[138:139], v[140:141]
	v_pk_add_f32 v[132:133], v[142:143], v[144:145]
	s_nop 0
	v_pk_add_f32 v[130:131], v[130:131], v[132:133]
	s_nop 0
	v_add_f32_e32 v130, v130, v131
	v_fmamk_f32 v130, v130, 0x3a000000, v232
	v_rsq_f32_e32 v130, v130
	ds_write_b32 v129, v130

; __device__ __forceinline__ f32x4 sigmoid4(f32x4 v) { return (f32x4){sigmoid_f(v[0]), sigmoid_f(v[1]), sigmoid_f(v[2]), sigmoid_f(v[3])}; }
; __device__ __forceinline__ f32x4 silu4(f32x4 v) { return v * sigmoid4(v); }
;     template <int MODE, bool HEADMAJOR>
;     __device__ __forceinline__ void plain(const f32x4 (&acc)[2][2][4][2], const float (&rs)[2][4], bf16_t* base, int row0, int pl, int wc, int fq) const {
; #pragma unroll
;         for (int ai = 0; ai < 2; ++ai)
; #pragma unroll
;             for (int m = 0; m < 4; ++m) { const int row = row0 + ai * 128 + m * 16;
; #pragma unroll
;                 for (int bj = 0; bj < 2; ++bj) { f32x4 v0 = acc[ai][bj][m][0] * rs[ai][m], v1 = acc[ai][bj][m][1] * rs[ai][m];
;                     if (MODE == 1) { v0 = v0 * 0.08838834764831845f; v1 = v1 * 0.08838834764831845f; }
;                     if (MODE == 2) { v0 = silu4(v0); v1 = silu4(v1); }
;                     if (MODE == 3) { v0 = sigmoid4(v0); v1 = sigmoid4(v1); }
;                     bf16_t* ptr = HEADMAJOR ? base + ((size_t)(pl * 2 + bj) * S + row) * 128 + 32 * wc + 8 * fq
;                                             : base + (size_t)row * DM + pl * 256 + bj * 128 + 32 * wc + 8 * fq;
;                     *(u32x4*)ptr = pack8bf(v0, v1); }
;                 asm volatile("" ::: "memory"); }
;     __device__ __forceinline__ void operator()(const f32x4 (&acc)[2][2][4][2], const pg8::Unit& u, int wr, int wc, int fr_, int fq_) const {
;     ...
;         switch (seg) {
;             case 2: plain<0, true>(acc, rs, (bf16_t*)(ws + WS_VDA), row0, pl, wc, fq); break;
;             case 3: plain<2, false>(acc, rs, (bf16_t*)(ws + WS_ZDA), row0, pl, wc, fq); break;
;             case 4: plain<1, true>(acc, rs, (bf16_t*)(ws + WS_QSB), row0, pl, wc, fq); break;
;             case 5: plain<0, true>(acc, rs, (bf16_t*)(ws + WS_KSB), row0, pl, wc, fq); break;
;             case 6: plain<0, true>(acc, rs, (bf16_t*)(ws + WS_VSB), row0, pl, wc, fq); break;
;             case 7: plain<2, false>(acc, rs, (bf16_t*)(ws + WS_ZSB), row0, pl, wc, fq); break;
;             case 8: plain<3, false>(acc, rs, (bf16_t*)(ws + WS_GA), row0, pl, wc, fq); break;
;             default: plain<3, false>(acc, rs, (bf16_t*)(ws + WS_GB), row0, pl, wc, fq); break;
.LBB0_77:
	s_cmp_lt_i32 s40, 5
	s_cbranch_scc1 .LBB0_94
	s_cmp_lt_i32 s40, 7
	s_cbranch_scc1 .LBB0_88
	s_cmp_lt_i32 s40, 8
	s_cbranch_scc1 .LBB0_85
	s_cmp_lg_u32 s40, 8
	s_cbranch_scc0 .LBB0_82
	s_waitcnt lgkmcnt(0)
	v_pk_mul_f32 v[138:139], v[124:125], v[186:187] op_sel_hi:[1,0]
	v_pk_mul_f32 v[134:135], v[126:127], v[186:187] op_sel_hi:[1,0]
	v_mul_f32_e32 v133, 0xbfb8aa3b, v138
	v_mul_f32_e32 v137, 0xbfb8aa3b, v139
	v_pk_mul_f32 v[138:139], v[120:121], v[186:187] op_sel_hi:[1,0]
	v_pk_mul_f32 v[140:141], v[122:123], v[186:187] op_sel_hi:[1,0]
	v_mul_f32_e32 v138, 0xbfb8aa3b, v138
	v_exp_f32_e32 v138, v138
	v_mul_f32_e32 v139, 0xbfb8aa3b, v139
	v_exp_f32_e32 v139, v139
	v_mul_f32_e32 v134, 0xbfb8aa3b, v134
	v_add_f32_e32 v138, 1.0, v138
	v_mul_f32_e32 v135, 0xbfb8aa3b, v135
	v_rcp_f32_e32 v142, v138
	v_add_f32_e32 v138, 1.0, v139
	v_mul_f32_e32 v139, 0xbfb8aa3b, v140
	v_exp_f32_e32 v134, v134
	v_exp_f32_e32 v135, v135
	v_exp_f32_e32 v139, v139
	v_mul_f32_e32 v140, 0xbfb8aa3b, v141
	s_lshl_b32 s8, s25, 9
	v_exp_f32_e32 v133, v133
	v_exp_f32_e32 v137, v137
	v_exp_f32_e32 v140, v140
	s_add_u32 s8, s6, s8
	s_addc_u32 s9, s7, 0
	s_lshl_b32 s22, s4, 1
	s_add_u32 s8, s8, s22
	v_lshlrev_b32_e32 v128, 3, v136
	v_add_f32_e32 v134, 1.0, v134
	v_add_f32_e32 v135, 1.0, v135
	v_rcp_f32_e32 v141, v138
	v_add_f32_e32 v138, 1.0, v139
	s_addc_u32 s9, s9, 0
	v_ashrrev_i32_e32 v129, 31, v128
	v_ashrrev_i32_e32 v183, 31, v182
	v_add_f32_e32 v133, 1.0, v133
	v_add_f32_e32 v137, 1.0, v137
	v_rcp_f32_e32 v134, v134
	v_rcp_f32_e32 v135, v135
	v_rcp_f32_e32 v143, v138
	v_add_f32_e32 v138, 1.0, v140
	v_lshl_add_u64 v[128:129], v[128:129], 1, s[8:9]
	v_lshlrev_b64 v[130:131], 12, v[182:183]
	v_rcp_f32_e32 v133, v133
	v_rcp_f32_e32 v137, v137
	v_rcp_f32_e32 v144, v138
	v_lshl_add_u64 v[128:129], v[128:129], 0, v[130:131]
	s_mov_b64 s[8:9], 0x2e500000
	v_lshl_add_u64 v[130:131], v[128:129], 0, s[8:9]
	s_mov_b32 s8, 0x2e500000
	v_cvt_pk_bf16_f32 v139, v134, v135
	v_add_co_u32_e32 v134, vcc, s8, v128
	v_cvt_pk_bf16_f32 v138, v133, v137
	v_cvt_pk_bf16_f32 v140, v142, v141
	v_cvt_pk_bf16_f32 v141, v143, v144
	v_addc_co_u32_e32 v135, vcc, 0, v129, vcc
	global_store_dwordx4 v[134:135], v[138:141], off
	v_pk_mul_f32 v[134:135], v[118:119], v[186:187] op_sel_hi:[1,0]
	s_mov_b64 s[8:9], 0x2e510000
	v_pk_mul_f32 v[138:139], v[116:117], v[186:187] op_sel_hi:[1,0]
	v_pk_mul_f32 v[140:141], v[114:115], v[186:187] op_sel_hi:[1,0]
	v_mul_f32_e32 v133, 0xbfb8aa3b, v138
	v_mul_f32_e32 v137, 0xbfb8aa3b, v139
	v_pk_mul_f32 v[138:139], v[112:113], v[186:187] op_sel_hi:[1,0]
	v_mul_f32_e32 v134, 0xbfb8aa3b, v134
	v_mul_f32_e32 v138, 0xbfb8aa3b, v138
	v_exp_f32_e32 v138, v138
	v_mul_f32_e32 v139, 0xbfb8aa3b, v139
	v_exp_f32_e32 v139, v139
	v_mul_f32_e32 v135, 0xbfb8aa3b, v135
	v_add_f32_e32 v138, 1.0, v138
	v_rcp_f32_e32 v142, v138
	v_add_f32_e32 v138, 1.0, v139
	v_mul_f32_e32 v139, 0xbfb8aa3b, v140
	v_exp_f32_e32 v139, v139
	v_mul_f32_e32 v140, 0xbfb8aa3b, v141
	v_exp_f32_e32 v133, v133
	v_exp_f32_e32 v137, v137
	v_exp_f32_e32 v134, v134
	v_exp_f32_e32 v135, v135
	v_exp_f32_e32 v140, v140
	v_rcp_f32_e32 v141, v138
	v_add_f32_e32 v138, 1.0, v139
	v_add_f32_e32 v133, 1.0, v133
	v_add_f32_e32 v137, 1.0, v137
	v_add_f32_e32 v134, 1.0, v134
	v_add_f32_e32 v135, 1.0, v135
	v_rcp_f32_e32 v143, v138
	v_add_f32_e32 v138, 1.0, v140
	v_rcp_f32_e32 v133, v133
	v_rcp_f32_e32 v137, v137
	v_rcp_f32_e32 v134, v134
	v_rcp_f32_e32 v135, v135
	v_rcp_f32_e32 v144, v138
	v_cvt_pk_bf16_f32 v138, v133, v137
	v_cvt_pk_bf16_f32 v140, v142, v141
	v_cvt_pk_bf16_f32 v139, v134, v135
	v_cvt_pk_bf16_f32 v141, v143, v144
	v_mov_b32_e32 v134, v187
	global_store_dwordx4 v[130:131], v[138:141], off offset:256
	v_pk_mul_f32 v[142:143], v[106:107], v[134:135] op_sel_hi:[1,0]
	v_lshl_add_u64 v[130:131], v[128:129], 0, s[8:9]
	v_pk_mul_f32 v[140:141], v[108:109], v[134:135] op_sel_hi:[1,0]
	v_pk_mul_f32 v[138:139], v[110:111], v[134:135] op_sel_hi:[1,0]
	v_mul_f32_e32 v135, 0xbfb8aa3b, v141
	v_exp_f32_e32 v135, v135
	v_mul_f32_e32 v133, 0xbfb8aa3b, v140
	v_mul_f32_e32 v137, 0xbfb8aa3b, v138
	v_mul_f32_e32 v138, 0xbfb8aa3b, v139
	v_pk_mul_f32 v[140:141], v[104:105], v[134:135] op_sel_hi:[1,0]
	v_exp_f32_e32 v138, v138
	v_mul_f32_e32 v139, 0xbfb8aa3b, v140
	v_exp_f32_e32 v139, v139
	v_mul_f32_e32 v140, 0xbfb8aa3b, v141
	v_exp_f32_e32 v140, v140
	v_add_f32_e32 v138, 1.0, v138
	v_rcp_f32_e32 v141, v138
	v_add_f32_e32 v138, 1.0, v139
	v_mul_f32_e32 v139, 0xbfb8aa3b, v142
	v_rcp_f32_e32 v144, v138
	v_add_f32_e32 v138, 1.0, v140
	v_exp_f32_e32 v139, v139
	v_mul_f32_e32 v140, 0xbfb8aa3b, v143
	v_exp_f32_e32 v133, v133
	v_exp_f32_e32 v137, v137
	v_exp_f32_e32 v140, v140
	v_rcp_f32_e32 v142, v138
	v_add_f32_e32 v138, 1.0, v139
	v_add_f32_e32 v133, 1.0, v133
	v_add_f32_e32 v135, 1.0, v135
	v_add_f32_e32 v137, 1.0, v137
	v_rcp_f32_e32 v143, v138
	v_add_f32_e32 v138, 1.0, v140
	v_rcp_f32_e32 v133, v133
	v_rcp_f32_e32 v135, v135
	v_rcp_f32_e32 v137, v137
	v_rcp_f32_e32 v145, v138
	s_mov_b32 s8, 0x2e510000
	v_cvt_pk_bf16_f32 v140, v144, v142
	v_add_co_u32_e32 v142, vcc, s8, v128
	v_cvt_pk_bf16_f32 v138, v133, v135
	v_cvt_pk_bf16_f32 v139, v137, v141
	v_cvt_pk_bf16_f32 v141, v143, v145
	v_addc_co_u32_e32 v143, vcc, 0, v129, vcc
	global_store_dwordx4 v[142:143], v[138:141], off
	v_pk_mul_f32 v[142:143], v[98:99], v[134:135] op_sel_hi:[1,0]
	s_mov_b64 s[8:9], 0x2e520000
	v_pk_mul_f32 v[138:139], v[102:103], v[134:135] op_sel_hi:[1,0]
	v_pk_mul_f32 v[140:141], v[100:101], v[134:135] op_sel_hi:[1,0]
	v_mul_f32_e32 v138, 0xbfb8aa3b, v138
	v_exp_f32_e32 v138, v138
	v_mul_f32_e32 v139, 0xbfb8aa3b, v139
	v_exp_f32_e32 v139, v139
; __device__ __forceinline__ unsigned cvt_pk_bf16(float lo, float hi) { f32x2_t v = {lo, hi}; bf16x2_t r = __builtin_convertvector(v, bf16x2_t); return __builtin_bit_cast(unsigned, r); }
; __device__ __forceinline__ float sigmoid_f(float x) { return __builtin_amdgcn_rcpf(1.f + __expf(-x)); }
; __device__ __forceinline__ f32x4 sigmoid4(f32x4 v) { return (f32x4){sigmoid_f(v[0]), sigmoid_f(v[1]), sigmoid_f(v[2]), sigmoid_f(v[3])}; }
; __device__ __forceinline__ f32x4 silu4(f32x4 v) { return v * sigmoid4(v); }
; __device__ __forceinline__ u32x4 pack8bf(f32x4 a, f32x4 b) {
;     u32x4 w; w.x = pg8::cvt_pk_bf16(a[0], a[1]); w.y = pg8::cvt_pk_bf16(a[2], a[3]); w.z = pg8::cvt_pk_bf16(b[0], b[1]); w.w = pg8::cvt_pk_bf16(b[2], b[3]); return w;
; }
;     template <int MODE, bool HEADMAJOR>
;     __device__ __forceinline__ void plain(const f32x4 (&acc)[2][2][4][2], const float (&rs)[2][4], bf16_t* base, int row0, int pl, int wc, int fq) const {
; #pragma unroll
;         for (int ai = 0; ai < 2; ++ai)
; #pragma unroll
;             for (int m = 0; m < 4; ++m) { const int row = row0 + ai * 128 + m * 16;
; #pragma unroll
;                 for (int bj = 0; bj < 2; ++bj) { f32x4 v0 = acc[ai][bj][m][0] * rs[ai][m], v1 = acc[ai][bj][m][1] * rs[ai][m];
;                     if (MODE == 1) { v0 = v0 * 0.08838834764831845f; v1 = v1 * 0.08838834764831845f; }
;                     if (MODE == 2) { v0 = silu4(v0); v1 = silu4(v1); }
;                     if (MODE == 3) { v0 = sigmoid4(v0); v1 = sigmoid4(v1); }
;                     bf16_t* ptr = HEADMAJOR ? base + ((size_t)(pl * 2 + bj) * S + row) * 128 + 32 * wc + 8 * fq
;                                             : base + (size_t)row * DM + pl * 256 + bj * 128 + 32 * wc + 8 * fq;
;                     *(u32x4*)ptr = pack8bf(v0, v1); }
;                 asm volatile("" ::: "memory"); }
	v_mul_f32_e32 v133, 0xbfb8aa3b, v140
	v_add_f32_e32 v138, 1.0, v138
	v_mul_f32_e32 v135, 0xbfb8aa3b, v141
	v_rcp_f32_e32 v140, v138
	v_add_f32_e32 v138, 1.0, v139
	v_exp_f32_e32 v137, v135
	v_pk_mul_f32 v[134:135], v[96:97], v[134:135] op_sel_hi:[1,0]
	v_rcp_f32_e32 v139, v138
	v_mul_f32_e32 v138, 0xbfb8aa3b, v142
	v_mul_f32_e32 v134, 0xbfb8aa3b, v134
	v_mul_f32_e32 v135, 0xbfb8aa3b, v135
	v_exp_f32_e32 v138, v138
	v_mul_f32_e32 v141, 0xbfb8aa3b, v143
	v_exp_f32_e32 v133, v133
	v_exp_f32_e32 v134, v134
	v_exp_f32_e32 v135, v135
	v_exp_f32_e32 v141, v141
	v_add_f32_e32 v138, 1.0, v138
	v_add_f32_e32 v133, 1.0, v133
	v_add_f32_e32 v137, 1.0, v137
	v_add_f32_e32 v134, 1.0, v134
	v_add_f32_e32 v135, 1.0, v135
	v_rcp_f32_e32 v142, v138
	v_add_f32_e32 v138, 1.0, v141
	v_rcp_f32_e32 v133, v133
	v_rcp_f32_e32 v137, v137
	v_rcp_f32_e32 v134, v134
	v_rcp_f32_e32 v135, v135
	v_rcp_f32_e32 v141, v138
	v_cvt_pk_bf16_f32 v138, v133, v137
	v_cvt_pk_bf16_f32 v139, v140, v139
	v_cvt_pk_bf16_f32 v140, v134, v135
	v_cvt_pk_bf16_f32 v141, v142, v141
	global_store_dwordx4 v[130:131], v[138:141], off offset:256
	v_pk_mul_f32 v[134:135], v[94:95], v[184:185] op_sel_hi:[1,0]
	v_lshl_add_u64 v[130:131], v[128:129], 0, s[8:9]
	v_pk_mul_f32 v[138:139], v[92:93], v[184:185] op_sel_hi:[1,0]
	v_pk_mul_f32 v[140:141], v[90:91], v[184:185] op_sel_hi:[1,0]
	v_mul_f32_e32 v133, 0xbfb8aa3b, v138
	v_mul_f32_e32 v137, 0xbfb8aa3b, v139
	v_pk_mul_f32 v[138:139], v[88:89], v[184:185] op_sel_hi:[1,0]
	v_mul_f32_e32 v134, 0xbfb8aa3b, v134
	v_mul_f32_e32 v138, 0xbfb8aa3b, v138
	v_exp_f32_e32 v138, v138
	v_mul_f32_e32 v139, 0xbfb8aa3b, v139
	v_exp_f32_e32 v139, v139
	v_mul_f32_e32 v135, 0xbfb8aa3b, v135
	v_add_f32_e32 v138, 1.0, v138
	v_rcp_f32_e32 v142, v138
	v_add_f32_e32 v138, 1.0, v139
	v_mul_f32_e32 v139, 0xbfb8aa3b, v140
	v_exp_f32_e32 v134, v134
	v_exp_f32_e32 v135, v135
	v_exp_f32_e32 v139, v139
	v_mul_f32_e32 v140, 0xbfb8aa3b, v141
	v_exp_f32_e32 v133, v133
	v_exp_f32_e32 v137, v137
	v_exp_f32_e32 v140, v140
	v_add_f32_e32 v134, 1.0, v134
	v_add_f32_e32 v135, 1.0, v135
	v_rcp_f32_e32 v141, v138
	v_add_f32_e32 v138, 1.0, v139
	v_add_f32_e32 v133, 1.0, v133
	v_add_f32_e32 v137, 1.0, v137
	v_rcp_f32_e32 v134, v134
	v_rcp_f32_e32 v135, v135
	v_rcp_f32_e32 v143, v138
	v_add_f32_e32 v138, 1.0, v140
	v_rcp_f32_e32 v133, v133
	v_rcp_f32_e32 v137, v137
	v_rcp_f32_e32 v144, v138
	s_mov_b32 s8, 0x2e520000
	v_cvt_pk_bf16_f32 v139, v134, v135
	v_add_co_u32_e32 v134, vcc, s8, v128
	v_cvt_pk_bf16_f32 v138, v133, v137
	v_cvt_pk_bf16_f32 v140, v142, v141
	v_cvt_pk_bf16_f32 v141, v143, v144
	v_addc_co_u32_e32 v135, vcc, 0, v129, vcc
	global_store_dwordx4 v[134:135], v[138:141], off
	v_pk_mul_f32 v[134:135], v[86:87], v[184:185] op_sel_hi:[1,0]
	s_mov_b64 s[8:9], 0x2e530000
	v_pk_mul_f32 v[138:139], v[84:85], v[184:185] op_sel_hi:[1,0]
	v_pk_mul_f32 v[140:141], v[82:83], v[184:185] op_sel_hi:[1,0]
	v_mul_f32_e32 v133, 0xbfb8aa3b, v138
	v_mul_f32_e32 v137, 0xbfb8aa3b, v139
	v_pk_mul_f32 v[138:139], v[80:81], v[184:185] op_sel_hi:[1,0]
	v_mul_f32_e32 v134, 0xbfb8aa3b, v134
	v_mul_f32_e32 v138, 0xbfb8aa3b, v138
	v_exp_f32_e32 v138, v138
	v_mul_f32_e32 v139, 0xbfb8aa3b, v139
	v_exp_f32_e32 v139, v139
	v_mul_f32_e32 v135, 0xbfb8aa3b, v135
	v_add_f32_e32 v138, 1.0, v138
	v_rcp_f32_e32 v142, v138
	v_add_f32_e32 v138, 1.0, v139
	v_mul_f32_e32 v139, 0xbfb8aa3b, v140
	v_exp_f32_e32 v139, v139
	v_mul_f32_e32 v140, 0xbfb8aa3b, v141
	v_exp_f32_e32 v133, v133
	v_exp_f32_e32 v137, v137
	v_exp_f32_e32 v134, v134
	v_exp_f32_e32 v135, v135
	v_exp_f32_e32 v140, v140
	v_rcp_f32_e32 v141, v138
	v_add_f32_e32 v138, 1.0, v139
	v_add_f32_e32 v133, 1.0, v133
	v_add_f32_e32 v137, 1.0, v137
	v_add_f32_e32 v134, 1.0, v134
	v_add_f32_e32 v135, 1.0, v135
	v_rcp_f32_e32 v143, v138
	v_add_f32_e32 v138, 1.0, v140
	v_rcp_f32_e32 v133, v133
	v_rcp_f32_e32 v137, v137
	v_rcp_f32_e32 v134, v134
	v_rcp_f32_e32 v135, v135
	v_rcp_f32_e32 v144, v138
	v_cvt_pk_bf16_f32 v138, v133, v137
	v_cvt_pk_bf16_f32 v140, v142, v141
	v_cvt_pk_bf16_f32 v139, v134, v135
	v_cvt_pk_bf16_f32 v141, v143, v144
	v_mov_b32_e32 v134, v185
	global_store_dwordx4 v[130:131], v[138:141], off offset:256
	v_pk_mul_f32 v[142:143], v[74:75], v[134:135] op_sel_hi:[1,0]
	v_lshl_add_u64 v[130:131], v[128:129], 0, s[8:9]
	v_pk_mul_f32 v[140:141], v[76:77], v[134:135] op_sel_hi:[1,0]
	v_pk_mul_f32 v[138:139], v[78:79], v[134:135] op_sel_hi:[1,0]
	v_mul_f32_e32 v135, 0xbfb8aa3b, v141
	v_exp_f32_e32 v135, v135
	v_mul_f32_e32 v133, 0xbfb8aa3b, v140
	v_mul_f32_e32 v137, 0xbfb8aa3b, v138
	v_mul_f32_e32 v138, 0xbfb8aa3b, v139
	v_pk_mul_f32 v[140:141], v[72:73], v[134:135] op_sel_hi:[1,0]
	v_exp_f32_e32 v138, v138
	v_mul_f32_e32 v139, 0xbfb8aa3b, v140
	v_exp_f32_e32 v139, v139
	v_mul_f32_e32 v140, 0xbfb8aa3b, v141
	v_exp_f32_e32 v140, v140
	v_add_f32_e32 v138, 1.0, v138
	v_rcp_f32_e32 v141, v138
	v_add_f32_e32 v138, 1.0, v139
	v_mul_f32_e32 v139, 0xbfb8aa3b, v142
	v_rcp_f32_e32 v144, v138
	v_add_f32_e32 v138, 1.0, v140
	v_exp_f32_e32 v139, v139
	v_mul_f32_e32 v140, 0xbfb8aa3b, v143
	v_exp_f32_e32 v133, v133
	v_exp_f32_e32 v137, v137
	v_exp_f32_e32 v140, v140
	v_rcp_f32_e32 v142, v138
	v_add_f32_e32 v138, 1.0, v139
	v_add_f32_e32 v133, 1.0, v133
	v_add_f32_e32 v135, 1.0, v135
	v_add_f32_e32 v137, 1.0, v137
	v_rcp_f32_e32 v143, v138
	v_add_f32_e32 v138, 1.0, v140
	v_rcp_f32_e32 v133, v133
	v_rcp_f32_e32 v135, v135
	v_rcp_f32_e32 v137, v137
	v_rcp_f32_e32 v145, v138
	s_mov_b32 s8, 0x2e530000
	v_cvt_pk_bf16_f32 v140, v144, v142
	v_add_co_u32_e32 v142, vcc, s8, v128
	v_cvt_pk_bf16_f32 v138, v133, v135
	v_cvt_pk_bf16_f32 v139, v137, v141
	v_cvt_pk_bf16_f32 v141, v143, v145
; __device__ __forceinline__ unsigned cvt_pk_bf16(float lo, float hi) { f32x2_t v = {lo, hi}; bf16x2_t r = __builtin_convertvector(v, bf16x2_t); return __builtin_bit_cast(unsigned, r); }
; __device__ __forceinline__ float sigmoid_f(float x) { return __builtin_amdgcn_rcpf(1.f + __expf(-x)); }
; __device__ __forceinline__ f32x4 sigmoid4(f32x4 v) { return (f32x4){sigmoid_f(v[0]), sigmoid_f(v[1]), sigmoid_f(v[2]), sigmoid_f(v[3])}; }
; __device__ __forceinline__ f32x4 silu4(f32x4 v) { return v * sigmoid4(v); }
; __device__ __forceinline__ u32x4 pack8bf(f32x4 a, f32x4 b) {
;     u32x4 w; w.x = pg8::cvt_pk_bf16(a[0], a[1]); w.y = pg8::cvt_pk_bf16(a[2], a[3]); w.z = pg8::cvt_pk_bf16(b[0], b[1]); w.w = pg8::cvt_pk_bf16(b[2], b[3]); return w;
; }
;     template <int MODE, bool HEADMAJOR>
;     __device__ __forceinline__ void plain(const f32x4 (&acc)[2][2][4][2], const float (&rs)[2][4], bf16_t* base, int row0, int pl, int wc, int fq) const {
; #pragma unroll
;         for (int ai = 0; ai < 2; ++ai)
; #pragma unroll
;             for (int m = 0; m < 4; ++m) { const int row = row0 + ai * 128 + m * 16;
; #pragma unroll
;                 for (int bj = 0; bj < 2; ++bj) { f32x4 v0 = acc[ai][bj][m][0] * rs[ai][m], v1 = acc[ai][bj][m][1] * rs[ai][m];
;                     if (MODE == 1) { v0 = v0 * 0.08838834764831845f; v1 = v1 * 0.08838834764831845f; }
;                     if (MODE == 2) { v0 = silu4(v0); v1 = silu4(v1); }
;                     if (MODE == 3) { v0 = sigmoid4(v0); v1 = sigmoid4(v1); }
;                     bf16_t* ptr = HEADMAJOR ? base + ((size_t)(pl * 2 + bj) * S + row) * 128 + 32 * wc + 8 * fq
;                                             : base + (size_t)row * DM + pl * 256 + bj * 128 + 32 * wc + 8 * fq;
;                     *(u32x4*)ptr = pack8bf(v0, v1); }
;                 asm volatile("" ::: "memory"); }
	v_addc_co_u32_e32 v143, vcc, 0, v129, vcc
	global_store_dwordx4 v[142:143], v[138:141], off
	v_pk_mul_f32 v[142:143], v[66:67], v[134:135] op_sel_hi:[1,0]
	s_mov_b64 s[8:9], 0x2e580000
	v_pk_mul_f32 v[138:139], v[70:71], v[134:135] op_sel_hi:[1,0]
	v_pk_mul_f32 v[140:141], v[68:69], v[134:135] op_sel_hi:[1,0]
	v_mul_f32_e32 v138, 0xbfb8aa3b, v138
	v_exp_f32_e32 v138, v138
	v_mul_f32_e32 v139, 0xbfb8aa3b, v139
	v_exp_f32_e32 v139, v139
	v_mul_f32_e32 v133, 0xbfb8aa3b, v140
	v_add_f32_e32 v138, 1.0, v138
	v_mul_f32_e32 v135, 0xbfb8aa3b, v141
	v_rcp_f32_e32 v140, v138
	v_add_f32_e32 v138, 1.0, v139
	v_exp_f32_e32 v137, v135
	v_pk_mul_f32 v[134:135], v[64:65], v[134:135] op_sel_hi:[1,0]
	v_rcp_f32_e32 v139, v138
	v_mul_f32_e32 v138, 0xbfb8aa3b, v142
	v_mul_f32_e32 v134, 0xbfb8aa3b, v134
	v_mul_f32_e32 v135, 0xbfb8aa3b, v135
	v_exp_f32_e32 v138, v138
	v_mul_f32_e32 v141, 0xbfb8aa3b, v143
	v_exp_f32_e32 v133, v133
	v_exp_f32_e32 v134, v134
	v_exp_f32_e32 v135, v135
	v_exp_f32_e32 v141, v141
	v_add_f32_e32 v138, 1.0, v138
	v_add_f32_e32 v133, 1.0, v133
	v_add_f32_e32 v137, 1.0, v137
	v_add_f32_e32 v134, 1.0, v134
	v_add_f32_e32 v135, 1.0, v135
	v_rcp_f32_e32 v142, v138
	v_add_f32_e32 v138, 1.0, v141
	v_rcp_f32_e32 v133, v133
	v_rcp_f32_e32 v137, v137
	v_rcp_f32_e32 v134, v134
	v_rcp_f32_e32 v135, v135
	v_rcp_f32_e32 v141, v138
	v_cvt_pk_bf16_f32 v138, v133, v137
	v_cvt_pk_bf16_f32 v139, v140, v139
	v_cvt_pk_bf16_f32 v140, v134, v135
	v_cvt_pk_bf16_f32 v141, v142, v141
	global_store_dwordx4 v[130:131], v[138:141], off offset:256
	v_pk_mul_f32 v[134:135], v[62:63], v[180:181] op_sel_hi:[1,0]
	v_lshl_add_u64 v[130:131], v[128:129], 0, s[8:9]
	v_pk_mul_f32 v[138:139], v[60:61], v[180:181] op_sel_hi:[1,0]
	v_pk_mul_f32 v[140:141], v[58:59], v[180:181] op_sel_hi:[1,0]
	v_mul_f32_e32 v133, 0xbfb8aa3b, v138
	v_mul_f32_e32 v137, 0xbfb8aa3b, v139
	v_pk_mul_f32 v[138:139], v[56:57], v[180:181] op_sel_hi:[1,0]
	v_mul_f32_e32 v134, 0xbfb8aa3b, v134
	v_mul_f32_e32 v138, 0xbfb8aa3b, v138
	v_exp_f32_e32 v138, v138
	v_mul_f32_e32 v139, 0xbfb8aa3b, v139
	v_exp_f32_e32 v139, v139
	v_mul_f32_e32 v135, 0xbfb8aa3b, v135
	v_add_f32_e32 v138, 1.0, v138
	v_rcp_f32_e32 v142, v138
	v_add_f32_e32 v138, 1.0, v139
	v_mul_f32_e32 v139, 0xbfb8aa3b, v140
	v_exp_f32_e32 v134, v134
	v_exp_f32_e32 v135, v135
	v_exp_f32_e32 v139, v139
	v_mul_f32_e32 v140, 0xbfb8aa3b, v141
	v_exp_f32_e32 v133, v133
	v_exp_f32_e32 v137, v137
	v_exp_f32_e32 v140, v140
	v_add_f32_e32 v134, 1.0, v134
	v_add_f32_e32 v135, 1.0, v135
	v_rcp_f32_e32 v141, v138
	v_add_f32_e32 v138, 1.0, v139
	v_add_f32_e32 v133, 1.0, v133
	v_add_f32_e32 v137, 1.0, v137
	v_rcp_f32_e32 v134, v134
	v_rcp_f32_e32 v135, v135
	v_rcp_f32_e32 v143, v138
	v_add_f32_e32 v138, 1.0, v140
	v_rcp_f32_e32 v133, v133
	v_rcp_f32_e32 v137, v137
	v_rcp_f32_e32 v144, v138
	s_mov_b32 s8, 0x2e580000
	v_cvt_pk_bf16_f32 v139, v134, v135
	v_add_co_u32_e32 v134, vcc, s8, v128
	v_cvt_pk_bf16_f32 v138, v133, v137
	v_cvt_pk_bf16_f32 v140, v142, v141
	v_cvt_pk_bf16_f32 v141, v143, v144
	v_addc_co_u32_e32 v135, vcc, 0, v129, vcc
	global_store_dwordx4 v[134:135], v[138:141], off
	v_pk_mul_f32 v[134:135], v[54:55], v[180:181] op_sel_hi:[1,0]
	s_mov_b64 s[8:9], 0x2e590000
	v_pk_mul_f32 v[138:139], v[52:53], v[180:181] op_sel_hi:[1,0]
	v_pk_mul_f32 v[140:141], v[50:51], v[180:181] op_sel_hi:[1,0]
	v_mul_f32_e32 v133, 0xbfb8aa3b, v138
	v_mul_f32_e32 v137, 0xbfb8aa3b, v139
	v_pk_mul_f32 v[138:139], v[48:49], v[180:181] op_sel_hi:[1,0]
	v_mul_f32_e32 v134, 0xbfb8aa3b, v134
	v_mul_f32_e32 v138, 0xbfb8aa3b, v138
	v_exp_f32_e32 v138, v138
	v_mul_f32_e32 v139, 0xbfb8aa3b, v139
	v_exp_f32_e32 v139, v139
	v_mul_f32_e32 v135, 0xbfb8aa3b, v135
	v_add_f32_e32 v138, 1.0, v138
	v_rcp_f32_e32 v142, v138
	v_add_f32_e32 v138, 1.0, v139
	v_mul_f32_e32 v139, 0xbfb8aa3b, v140
	v_exp_f32_e32 v139, v139
	v_mul_f32_e32 v140, 0xbfb8aa3b, v141
	v_exp_f32_e32 v133, v133
	v_exp_f32_e32 v137, v137
	v_exp_f32_e32 v134, v134
	v_exp_f32_e32 v135, v135
	v_exp_f32_e32 v140, v140
	v_rcp_f32_e32 v141, v138
	v_add_f32_e32 v138, 1.0, v139
	v_add_f32_e32 v133, 1.0, v133
	v_add_f32_e32 v137, 1.0, v137
	v_add_f32_e32 v134, 1.0, v134
	v_add_f32_e32 v135, 1.0, v135
	v_rcp_f32_e32 v143, v138
	v_add_f32_e32 v138, 1.0, v140
	v_rcp_f32_e32 v133, v133
	v_rcp_f32_e32 v137, v137
	v_rcp_f32_e32 v134, v134
	v_rcp_f32_e32 v135, v135
	v_rcp_f32_e32 v144, v138
	v_cvt_pk_bf16_f32 v138, v133, v137
	v_cvt_pk_bf16_f32 v140, v142, v141
	v_cvt_pk_bf16_f32 v139, v134, v135
	v_cvt_pk_bf16_f32 v141, v143, v144
	v_mov_b32_e32 v134, v181
	global_store_dwordx4 v[130:131], v[138:141], off offset:256
	v_pk_mul_f32 v[142:143], v[42:43], v[134:135] op_sel_hi:[1,0]
	v_lshl_add_u64 v[130:131], v[128:129], 0, s[8:9]
	v_pk_mul_f32 v[140:141], v[44:45], v[134:135] op_sel_hi:[1,0]
	v_pk_mul_f32 v[138:139], v[46:47], v[134:135] op_sel_hi:[1,0]
	v_mul_f32_e32 v135, 0xbfb8aa3b, v141
	v_exp_f32_e32 v135, v135
	v_mul_f32_e32 v133, 0xbfb8aa3b, v140
	v_mul_f32_e32 v137, 0xbfb8aa3b, v138
	v_mul_f32_e32 v138, 0xbfb8aa3b, v139
	v_pk_mul_f32 v[140:141], v[40:41], v[134:135] op_sel_hi:[1,0]
	v_exp_f32_e32 v138, v138
	v_mul_f32_e32 v139, 0xbfb8aa3b, v140
	v_exp_f32_e32 v139, v139
	v_mul_f32_e32 v140, 0xbfb8aa3b, v141
	v_exp_f32_e32 v140, v140
	v_add_f32_e32 v138, 1.0, v138
	v_rcp_f32_e32 v141, v138
	v_add_f32_e32 v138, 1.0, v139
	v_mul_f32_e32 v139, 0xbfb8aa3b, v142
	v_rcp_f32_e32 v144, v138
	v_add_f32_e32 v138, 1.0, v140
	v_exp_f32_e32 v139, v139
	v_mul_f32_e32 v140, 0xbfb8aa3b, v143
	v_exp_f32_e32 v133, v133
	v_exp_f32_e32 v137, v137
	v_exp_f32_e32 v140, v140
	v_rcp_f32_e32 v142, v138
	v_add_f32_e32 v138, 1.0, v139
	v_add_f32_e32 v133, 1.0, v133
; __device__ __forceinline__ unsigned cvt_pk_bf16(float lo, float hi) { f32x2_t v = {lo, hi}; bf16x2_t r = __builtin_convertvector(v, bf16x2_t); return __builtin_bit_cast(unsigned, r); }
; __device__ __forceinline__ float sigmoid_f(float x) { return __builtin_amdgcn_rcpf(1.f + __expf(-x)); }
; __device__ __forceinline__ f32x4 sigmoid4(f32x4 v) { return (f32x4){sigmoid_f(v[0]), sigmoid_f(v[1]), sigmoid_f(v[2]), sigmoid_f(v[3])}; }
; __device__ __forceinline__ f32x4 silu4(f32x4 v) { return v * sigmoid4(v); }
; __device__ __forceinline__ u32x4 pack8bf(f32x4 a, f32x4 b) {
;     u32x4 w; w.x = pg8::cvt_pk_bf16(a[0], a[1]); w.y = pg8::cvt_pk_bf16(a[2], a[3]); w.z = pg8::cvt_pk_bf16(b[0], b[1]); w.w = pg8::cvt_pk_bf16(b[2], b[3]); return w;
; }
;     template <int MODE, bool HEADMAJOR>
;     __device__ __forceinline__ void plain(const f32x4 (&acc)[2][2][4][2], const float (&rs)[2][4], bf16_t* base, int row0, int pl, int wc, int fq) const {
; #pragma unroll
;         for (int ai = 0; ai < 2; ++ai)
; #pragma unroll
;             for (int m = 0; m < 4; ++m) { const int row = row0 + ai * 128 + m * 16;
; #pragma unroll
;                 for (int bj = 0; bj < 2; ++bj) { f32x4 v0 = acc[ai][bj][m][0] * rs[ai][m], v1 = acc[ai][bj][m][1] * rs[ai][m];
;                     if (MODE == 1) { v0 = v0 * 0.08838834764831845f; v1 = v1 * 0.08838834764831845f; }
;                     if (MODE == 2) { v0 = silu4(v0); v1 = silu4(v1); }
;                     if (MODE == 3) { v0 = sigmoid4(v0); v1 = sigmoid4(v1); }
;                     bf16_t* ptr = HEADMAJOR ? base + ((size_t)(pl * 2 + bj) * S + row) * 128 + 32 * wc + 8 * fq
;                                             : base + (size_t)row * DM + pl * 256 + bj * 128 + 32 * wc + 8 * fq;
;                     *(u32x4*)ptr = pack8bf(v0, v1); }
;                 asm volatile("" ::: "memory"); }
	v_add_f32_e32 v135, 1.0, v135
	v_add_f32_e32 v137, 1.0, v137
	v_rcp_f32_e32 v143, v138
	v_add_f32_e32 v138, 1.0, v140
	v_rcp_f32_e32 v133, v133
	v_rcp_f32_e32 v135, v135
	v_rcp_f32_e32 v137, v137
	v_rcp_f32_e32 v145, v138
	s_mov_b32 s8, 0x2e590000
	v_cvt_pk_bf16_f32 v140, v144, v142
	v_add_co_u32_e32 v142, vcc, s8, v128
	v_cvt_pk_bf16_f32 v138, v133, v135
	v_cvt_pk_bf16_f32 v139, v137, v141
	v_cvt_pk_bf16_f32 v141, v143, v145
	v_addc_co_u32_e32 v143, vcc, 0, v129, vcc
	global_store_dwordx4 v[142:143], v[138:141], off
	v_pk_mul_f32 v[142:143], v[34:35], v[134:135] op_sel_hi:[1,0]
	s_mov_b64 s[8:9], 0x2e5a0000
	v_pk_mul_f32 v[138:139], v[38:39], v[134:135] op_sel_hi:[1,0]
	v_pk_mul_f32 v[140:141], v[36:37], v[134:135] op_sel_hi:[1,0]
	v_mul_f32_e32 v138, 0xbfb8aa3b, v138
	v_exp_f32_e32 v138, v138
	v_mul_f32_e32 v139, 0xbfb8aa3b, v139
	v_exp_f32_e32 v139, v139
	v_mul_f32_e32 v133, 0xbfb8aa3b, v140
	v_add_f32_e32 v138, 1.0, v138
	v_mul_f32_e32 v135, 0xbfb8aa3b, v141
	v_rcp_f32_e32 v140, v138
	v_add_f32_e32 v138, 1.0, v139
	v_exp_f32_e32 v137, v135
	v_pk_mul_f32 v[134:135], v[32:33], v[134:135] op_sel_hi:[1,0]
	v_rcp_f32_e32 v139, v138
	v_mul_f32_e32 v138, 0xbfb8aa3b, v142
	v_mul_f32_e32 v134, 0xbfb8aa3b, v134
	v_mul_f32_e32 v135, 0xbfb8aa3b, v135
	v_exp_f32_e32 v138, v138
	v_mul_f32_e32 v141, 0xbfb8aa3b, v143
	v_exp_f32_e32 v133, v133
	v_exp_f32_e32 v134, v134
	v_exp_f32_e32 v135, v135
	v_exp_f32_e32 v141, v141
	v_add_f32_e32 v138, 1.0, v138
	v_add_f32_e32 v133, 1.0, v133
	v_add_f32_e32 v137, 1.0, v137
	v_add_f32_e32 v134, 1.0, v134
	v_add_f32_e32 v135, 1.0, v135
	v_rcp_f32_e32 v142, v138
	v_add_f32_e32 v138, 1.0, v141
	v_rcp_f32_e32 v133, v133
	v_rcp_f32_e32 v137, v137
	v_rcp_f32_e32 v134, v134
	v_rcp_f32_e32 v135, v135
	v_rcp_f32_e32 v141, v138
	v_cvt_pk_bf16_f32 v138, v133, v137
	v_cvt_pk_bf16_f32 v139, v140, v139
	v_cvt_pk_bf16_f32 v140, v134, v135
	v_cvt_pk_bf16_f32 v141, v142, v141
	global_store_dwordx4 v[130:131], v[138:141], off offset:256
	v_pk_mul_f32 v[134:135], v[30:31], v[178:179] op_sel_hi:[1,0]
	v_lshl_add_u64 v[130:131], v[128:129], 0, s[8:9]
	v_pk_mul_f32 v[138:139], v[28:29], v[178:179] op_sel_hi:[1,0]
	v_pk_mul_f32 v[140:141], v[26:27], v[178:179] op_sel_hi:[1,0]
	v_mul_f32_e32 v133, 0xbfb8aa3b, v138
	v_mul_f32_e32 v137, 0xbfb8aa3b, v139
	v_pk_mul_f32 v[138:139], v[24:25], v[178:179] op_sel_hi:[1,0]
	v_mul_f32_e32 v134, 0xbfb8aa3b, v134
	v_mul_f32_e32 v138, 0xbfb8aa3b, v138
	v_exp_f32_e32 v138, v138
	v_mul_f32_e32 v139, 0xbfb8aa3b, v139
	v_exp_f32_e32 v139, v139
	v_mul_f32_e32 v135, 0xbfb8aa3b, v135
	v_add_f32_e32 v138, 1.0, v138
	v_rcp_f32_e32 v142, v138
	v_add_f32_e32 v138, 1.0, v139
	v_mul_f32_e32 v139, 0xbfb8aa3b, v140
	v_exp_f32_e32 v134, v134
	v_exp_f32_e32 v135, v135
	v_exp_f32_e32 v139, v139
	v_mul_f32_e32 v140, 0xbfb8aa3b, v141
	v_exp_f32_e32 v133, v133
	v_exp_f32_e32 v137, v137
	v_exp_f32_e32 v140, v140
	v_add_f32_e32 v134, 1.0, v134
	v_add_f32_e32 v135, 1.0, v135
	v_rcp_f32_e32 v141, v138
	v_add_f32_e32 v138, 1.0, v139
	v_add_f32_e32 v133, 1.0, v133
	v_add_f32_e32 v137, 1.0, v137
	v_rcp_f32_e32 v134, v134
	v_rcp_f32_e32 v135, v135
	v_rcp_f32_e32 v143, v138
	v_add_f32_e32 v138, 1.0, v140
	v_rcp_f32_e32 v133, v133
	v_rcp_f32_e32 v137, v137
	v_rcp_f32_e32 v144, v138
	s_mov_b32 s8, 0x2e5a0000
	v_cvt_pk_bf16_f32 v139, v134, v135
	v_add_co_u32_e32 v134, vcc, s8, v128
	v_cvt_pk_bf16_f32 v138, v133, v137
	v_cvt_pk_bf16_f32 v140, v142, v141
	v_cvt_pk_bf16_f32 v141, v143, v144
	v_addc_co_u32_e32 v135, vcc, 0, v129, vcc
	global_store_dwordx4 v[134:135], v[138:141], off
	v_pk_mul_f32 v[134:135], v[22:23], v[178:179] op_sel_hi:[1,0]
	s_mov_b64 s[8:9], 0x2e5b0000
	v_pk_mul_f32 v[138:139], v[20:21], v[178:179] op_sel_hi:[1,0]
	v_pk_mul_f32 v[140:141], v[18:19], v[178:179] op_sel_hi:[1,0]
	v_mul_f32_e32 v133, 0xbfb8aa3b, v138
	v_mul_f32_e32 v137, 0xbfb8aa3b, v139
	v_pk_mul_f32 v[138:139], v[16:17], v[178:179] op_sel_hi:[1,0]
	v_mul_f32_e32 v134, 0xbfb8aa3b, v134
	v_mul_f32_e32 v138, 0xbfb8aa3b, v138
	v_exp_f32_e32 v138, v138
	v_mul_f32_e32 v139, 0xbfb8aa3b, v139
	v_exp_f32_e32 v139, v139
	v_mul_f32_e32 v135, 0xbfb8aa3b, v135
	v_add_f32_e32 v138, 1.0, v138
	v_rcp_f32_e32 v142, v138
	v_add_f32_e32 v138, 1.0, v139
	v_mul_f32_e32 v139, 0xbfb8aa3b, v140
	v_exp_f32_e32 v139, v139
	v_mul_f32_e32 v140, 0xbfb8aa3b, v141
	v_exp_f32_e32 v133, v133
	v_exp_f32_e32 v137, v137
	v_exp_f32_e32 v134, v134
	v_exp_f32_e32 v135, v135
	v_exp_f32_e32 v140, v140
	v_rcp_f32_e32 v141, v138
	v_add_f32_e32 v138, 1.0, v139
	v_add_f32_e32 v133, 1.0, v133
	v_add_f32_e32 v137, 1.0, v137
	v_add_f32_e32 v134, 1.0, v134
	v_add_f32_e32 v135, 1.0, v135
	v_rcp_f32_e32 v143, v138
	v_add_f32_e32 v138, 1.0, v140
	v_rcp_f32_e32 v133, v133
	v_rcp_f32_e32 v137, v137
	v_rcp_f32_e32 v134, v134
	v_rcp_f32_e32 v135, v135
	v_rcp_f32_e32 v144, v138
	v_cvt_pk_bf16_f32 v138, v133, v137
	v_cvt_pk_bf16_f32 v140, v142, v141
	v_cvt_pk_bf16_f32 v139, v134, v135
	v_cvt_pk_bf16_f32 v141, v143, v144
	global_store_dwordx4 v[130:131], v[138:141], off offset:256
	v_mov_b32_e32 v130, v179
	v_pk_mul_f32 v[142:143], v[10:11], v[130:131] op_sel_hi:[1,0]
	v_pk_mul_f32 v[140:141], v[12:13], v[130:131] op_sel_hi:[1,0]
	v_pk_mul_f32 v[138:139], v[14:15], v[130:131] op_sel_hi:[1,0]
	v_mul_f32_e32 v131, 0xbfb8aa3b, v140
	v_exp_f32_e32 v131, v131
	v_mul_f32_e32 v133, 0xbfb8aa3b, v141
	v_mul_f32_e32 v137, 0xbfb8aa3b, v138
	v_mul_f32_e32 v138, 0xbfb8aa3b, v139
	v_pk_mul_f32 v[140:141], v[8:9], v[130:131] op_sel_hi:[1,0]
	v_exp_f32_e32 v138, v138
	v_mul_f32_e32 v139, 0xbfb8aa3b, v140
	v_exp_f32_e32 v139, v139
	v_mul_f32_e32 v140, 0xbfb8aa3b, v141
	v_exp_f32_e32 v140, v140
	v_add_f32_e32 v138, 1.0, v138
; __device__ __forceinline__ unsigned cvt_pk_bf16(float lo, float hi) { f32x2_t v = {lo, hi}; bf16x2_t r = __builtin_convertvector(v, bf16x2_t); return __builtin_bit_cast(unsigned, r); }
; __device__ __forceinline__ float sigmoid_f(float x) { return __builtin_amdgcn_rcpf(1.f + __expf(-x)); }
; __device__ __forceinline__ f32x4 sigmoid4(f32x4 v) { return (f32x4){sigmoid_f(v[0]), sigmoid_f(v[1]), sigmoid_f(v[2]), sigmoid_f(v[3])}; }
; __device__ __forceinline__ f32x4 silu4(f32x4 v) { return v * sigmoid4(v); }
; __device__ __forceinline__ u32x4 pack8bf(f32x4 a, f32x4 b) {
;     u32x4 w; w.x = pg8::cvt_pk_bf16(a[0], a[1]); w.y = pg8::cvt_pk_bf16(a[2], a[3]); w.z = pg8::cvt_pk_bf16(b[0], b[1]); w.w = pg8::cvt_pk_bf16(b[2], b[3]); return w;
; }
;     template <int MODE, bool HEADMAJOR>
;     __device__ __forceinline__ void plain(const f32x4 (&acc)[2][2][4][2], const float (&rs)[2][4], bf16_t* base, int row0, int pl, int wc, int fq) const {
; #pragma unroll
;         for (int ai = 0; ai < 2; ++ai)
; #pragma unroll
;             for (int m = 0; m < 4; ++m) { const int row = row0 + ai * 128 + m * 16;
; #pragma unroll
;                 for (int bj = 0; bj < 2; ++bj) { f32x4 v0 = acc[ai][bj][m][0] * rs[ai][m], v1 = acc[ai][bj][m][1] * rs[ai][m];
;                     if (MODE == 1) { v0 = v0 * 0.08838834764831845f; v1 = v1 * 0.08838834764831845f; }
;                     if (MODE == 2) { v0 = silu4(v0); v1 = silu4(v1); }
;                     if (MODE == 3) { v0 = sigmoid4(v0); v1 = sigmoid4(v1); }
;                     bf16_t* ptr = HEADMAJOR ? base + ((size_t)(pl * 2 + bj) * S + row) * 128 + 32 * wc + 8 * fq
;                                             : base + (size_t)row * DM + pl * 256 + bj * 128 + 32 * wc + 8 * fq;
;                     *(u32x4*)ptr = pack8bf(v0, v1); }
;                 asm volatile("" ::: "memory"); }
	v_rcp_f32_e32 v141, v138
	v_add_f32_e32 v138, 1.0, v139
	v_mul_f32_e32 v139, 0xbfb8aa3b, v142
	v_rcp_f32_e32 v144, v138
	v_add_f32_e32 v138, 1.0, v140
	v_exp_f32_e32 v139, v139
	v_mul_f32_e32 v140, 0xbfb8aa3b, v143
	v_exp_f32_e32 v133, v133
	v_exp_f32_e32 v137, v137
	v_exp_f32_e32 v140, v140
	v_rcp_f32_e32 v142, v138
	v_add_f32_e32 v138, 1.0, v139
	v_add_f32_e32 v131, 1.0, v131
	v_add_f32_e32 v133, 1.0, v133
	v_add_f32_e32 v137, 1.0, v137
	v_rcp_f32_e32 v143, v138
	v_add_f32_e32 v138, 1.0, v140
	v_rcp_f32_e32 v131, v131
	v_rcp_f32_e32 v133, v133
	v_rcp_f32_e32 v137, v137
	v_rcp_f32_e32 v145, v138
	v_lshl_add_u64 v[134:135], v[128:129], 0, s[8:9]
	s_mov_b32 s8, 0x2e5b0000
	v_add_co_u32_e32 v128, vcc, s8, v128
	v_cvt_pk_bf16_f32 v138, v131, v133
	v_cvt_pk_bf16_f32 v139, v137, v141
	v_cvt_pk_bf16_f32 v140, v144, v142
	v_cvt_pk_bf16_f32 v141, v143, v145
	v_addc_co_u32_e32 v129, vcc, 0, v129, vcc
	global_store_dwordx4 v[128:129], v[138:141], off
	v_pk_mul_f32 v[128:129], v[6:7], v[130:131] op_sel_hi:[1,0]
	s_mov_b64 s[8:9], 0
	v_mul_f32_e32 v128, 0xbfb8aa3b, v128
	v_exp_f32_e32 v128, v128
	v_mul_f32_e32 v129, 0xbfb8aa3b, v129
	v_pk_mul_f32 v[138:139], v[4:5], v[130:131] op_sel_hi:[1,0]
	v_exp_f32_e32 v129, v129
	v_pk_mul_f32 v[140:141], v[2:3], v[130:131] op_sel_hi:[1,0]
	v_mul_f32_e32 v131, 0xbfb8aa3b, v138
	v_exp_f32_e32 v133, v131
	v_mul_f32_e32 v131, 0xbfb8aa3b, v139
	v_exp_f32_e32 v137, v131
	v_pk_mul_f32 v[130:131], v[0:1], v[130:131] op_sel_hi:[1,0]
	v_add_f32_e32 v128, 1.0, v128
	v_rcp_f32_e32 v138, v128
	v_add_f32_e32 v128, 1.0, v129
	v_mul_f32_e32 v129, 0xbfb8aa3b, v130
	v_exp_f32_e32 v129, v129
	v_mul_f32_e32 v130, 0xbfb8aa3b, v131
	v_exp_f32_e32 v130, v130
	v_rcp_f32_e32 v131, v128
	v_add_f32_e32 v128, 1.0, v129
	v_mul_f32_e32 v129, 0xbfb8aa3b, v140
	v_rcp_f32_e32 v139, v128
	v_add_f32_e32 v128, 1.0, v130
	v_exp_f32_e32 v129, v129
	v_mul_f32_e32 v130, 0xbfb8aa3b, v141
	v_exp_f32_e32 v130, v130
	v_rcp_f32_e32 v140, v128
	v_add_f32_e32 v128, 1.0, v129
	v_add_f32_e32 v133, 1.0, v133
	v_add_f32_e32 v137, 1.0, v137
	v_rcp_f32_e32 v141, v128
	v_add_f32_e32 v128, 1.0, v130
	v_rcp_f32_e32 v133, v133
	v_rcp_f32_e32 v137, v137
	v_rcp_f32_e32 v142, v128
	v_cvt_pk_bf16_f32 v129, v138, v131
	v_cvt_pk_bf16_f32 v130, v139, v140
	v_cvt_pk_bf16_f32 v128, v133, v137
	v_cvt_pk_bf16_f32 v131, v141, v142
	global_store_dwordx4 v[134:135], v[128:131], off offset:256
.LBB0_82:
	s_andn2_b64 vcc, exec, s[8:9]
	s_cbranch_vccnz .LBB0_84
	s_waitcnt lgkmcnt(0)
	v_pk_mul_f32 v[138:139], v[124:125], v[186:187] op_sel_hi:[1,0]
	v_pk_mul_f32 v[134:135], v[126:127], v[186:187] op_sel_hi:[1,0]
	v_mul_f32_e32 v133, 0xbfb8aa3b, v138
	v_mul_f32_e32 v137, 0xbfb8aa3b, v139
	v_pk_mul_f32 v[138:139], v[120:121], v[186:187] op_sel_hi:[1,0]
	v_pk_mul_f32 v[140:141], v[122:123], v[186:187] op_sel_hi:[1,0]
	v_mul_f32_e32 v138, 0xbfb8aa3b, v138
	v_exp_f32_e32 v138, v138
	v_mul_f32_e32 v139, 0xbfb8aa3b, v139
	v_exp_f32_e32 v139, v139
	v_mul_f32_e32 v134, 0xbfb8aa3b, v134
	v_add_f32_e32 v138, 1.0, v138
	v_mul_f32_e32 v135, 0xbfb8aa3b, v135
	v_rcp_f32_e32 v142, v138
	v_add_f32_e32 v138, 1.0, v139
	v_mul_f32_e32 v139, 0xbfb8aa3b, v140
	v_exp_f32_e32 v134, v134
	v_exp_f32_e32 v135, v135
	v_exp_f32_e32 v139, v139
	v_mul_f32_e32 v140, 0xbfb8aa3b, v141
	s_lshl_b32 s8, s25, 9
	v_exp_f32_e32 v133, v133
	v_exp_f32_e32 v137, v137
	v_exp_f32_e32 v140, v140
	s_add_u32 s8, s6, s8
	s_addc_u32 s9, s7, 0
	s_lshl_b32 s22, s4, 1
	s_add_u32 s8, s8, s22
	v_lshlrev_b32_e32 v128, 3, v136
	v_add_f32_e32 v134, 1.0, v134
	v_add_f32_e32 v135, 1.0, v135
	v_rcp_f32_e32 v141, v138
	v_add_f32_e32 v138, 1.0, v139
	s_addc_u32 s9, s9, 0
	v_ashrrev_i32_e32 v129, 31, v128
	v_ashrrev_i32_e32 v183, 31, v182
	v_add_f32_e32 v133, 1.0, v133
	v_add_f32_e32 v137, 1.0, v137
	v_rcp_f32_e32 v134, v134
	v_rcp_f32_e32 v135, v135
	v_rcp_f32_e32 v143, v138
	v_add_f32_e32 v138, 1.0, v140
	v_lshl_add_u64 v[128:129], v[128:129], 1, s[8:9]
	v_lshlrev_b64 v[130:131], 12, v[182:183]
	v_rcp_f32_e32 v133, v133
	v_rcp_f32_e32 v137, v137
	v_rcp_f32_e32 v144, v138
	v_lshl_add_u64 v[128:129], v[128:129], 0, v[130:131]
	s_mov_b64 s[8:9], 0x2c500000
	v_lshl_add_u64 v[130:131], v[128:129], 0, s[8:9]
	s_mov_b32 s8, 0x2c500000
	v_cvt_pk_bf16_f32 v139, v134, v135
	v_add_co_u32_e32 v134, vcc, s8, v128
	v_cvt_pk_bf16_f32 v138, v133, v137
	v_cvt_pk_bf16_f32 v140, v142, v141
	v_cvt_pk_bf16_f32 v141, v143, v144
	v_addc_co_u32_e32 v135, vcc, 0, v129, vcc
	global_store_dwordx4 v[134:135], v[138:141], off
	v_pk_mul_f32 v[134:135], v[118:119], v[186:187] op_sel_hi:[1,0]
	s_mov_b64 s[8:9], 0x2c510000
	v_pk_mul_f32 v[138:139], v[116:117], v[186:187] op_sel_hi:[1,0]
	v_pk_mul_f32 v[140:141], v[114:115], v[186:187] op_sel_hi:[1,0]
	v_mul_f32_e32 v133, 0xbfb8aa3b, v138
	v_mul_f32_e32 v137, 0xbfb8aa3b, v139
	v_pk_mul_f32 v[138:139], v[112:113], v[186:187] op_sel_hi:[1,0]
	v_mul_f32_e32 v134, 0xbfb8aa3b, v134
	v_mul_f32_e32 v138, 0xbfb8aa3b, v138
	v_exp_f32_e32 v138, v138
	v_mul_f32_e32 v139, 0xbfb8aa3b, v139
	v_exp_f32_e32 v139, v139
	v_mul_f32_e32 v135, 0xbfb8aa3b, v135
	v_add_f32_e32 v138, 1.0, v138
	v_rcp_f32_e32 v142, v138
	v_add_f32_e32 v138, 1.0, v139
	v_mul_f32_e32 v139, 0xbfb8aa3b, v140
	v_exp_f32_e32 v139, v139
	v_mul_f32_e32 v140, 0xbfb8aa3b, v141
	v_exp_f32_e32 v133, v133
	v_exp_f32_e32 v137, v137
	v_exp_f32_e32 v134, v134
	v_exp_f32_e32 v135, v135
	v_exp_f32_e32 v140, v140
	v_rcp_f32_e32 v141, v138
	v_add_f32_e32 v138, 1.0, v139
	v_add_f32_e32 v133, 1.0, v133
	v_add_f32_e32 v137, 1.0, v137
	v_add_f32_e32 v134, 1.0, v134
	v_add_f32_e32 v135, 1.0, v135
	v_rcp_f32_e32 v143, v138
	v_add_f32_e32 v138, 1.0, v140
	v_rcp_f32_e32 v133, v133
; __device__ __forceinline__ unsigned cvt_pk_bf16(float lo, float hi) { f32x2_t v = {lo, hi}; bf16x2_t r = __builtin_convertvector(v, bf16x2_t); return __builtin_bit_cast(unsigned, r); }
; __device__ __forceinline__ float sigmoid_f(float x) { return __builtin_amdgcn_rcpf(1.f + __expf(-x)); }
; __device__ __forceinline__ f32x4 sigmoid4(f32x4 v) { return (f32x4){sigmoid_f(v[0]), sigmoid_f(v[1]), sigmoid_f(v[2]), sigmoid_f(v[3])}; }
; __device__ __forceinline__ f32x4 silu4(f32x4 v) { return v * sigmoid4(v); }
; __device__ __forceinline__ u32x4 pack8bf(f32x4 a, f32x4 b) {
;     u32x4 w; w.x = pg8::cvt_pk_bf16(a[0], a[1]); w.y = pg8::cvt_pk_bf16(a[2], a[3]); w.z = pg8::cvt_pk_bf16(b[0], b[1]); w.w = pg8::cvt_pk_bf16(b[2], b[3]); return w;
; }
;     template <int MODE, bool HEADMAJOR>
;     __device__ __forceinline__ void plain(const f32x4 (&acc)[2][2][4][2], const float (&rs)[2][4], bf16_t* base, int row0, int pl, int wc, int fq) const {
; #pragma unroll
;         for (int ai = 0; ai < 2; ++ai)
; #pragma unroll
;             for (int m = 0; m < 4; ++m) { const int row = row0 + ai * 128 + m * 16;
; #pragma unroll
;                 for (int bj = 0; bj < 2; ++bj) { f32x4 v0 = acc[ai][bj][m][0] * rs[ai][m], v1 = acc[ai][bj][m][1] * rs[ai][m];
;                     if (MODE == 1) { v0 = v0 * 0.08838834764831845f; v1 = v1 * 0.08838834764831845f; }
;                     if (MODE == 2) { v0 = silu4(v0); v1 = silu4(v1); }
;                     if (MODE == 3) { v0 = sigmoid4(v0); v1 = sigmoid4(v1); }
;                     bf16_t* ptr = HEADMAJOR ? base + ((size_t)(pl * 2 + bj) * S + row) * 128 + 32 * wc + 8 * fq
;                                             : base + (size_t)row * DM + pl * 256 + bj * 128 + 32 * wc + 8 * fq;
;                     *(u32x4*)ptr = pack8bf(v0, v1); }
;                 asm volatile("" ::: "memory"); }
	v_rcp_f32_e32 v137, v137
	v_rcp_f32_e32 v134, v134
	v_rcp_f32_e32 v135, v135
	v_rcp_f32_e32 v144, v138
	v_cvt_pk_bf16_f32 v138, v133, v137
	v_cvt_pk_bf16_f32 v140, v142, v141
	v_cvt_pk_bf16_f32 v139, v134, v135
	v_cvt_pk_bf16_f32 v141, v143, v144
	v_mov_b32_e32 v134, v187
	global_store_dwordx4 v[130:131], v[138:141], off offset:256
	v_pk_mul_f32 v[142:143], v[106:107], v[134:135] op_sel_hi:[1,0]
	v_lshl_add_u64 v[130:131], v[128:129], 0, s[8:9]
	v_pk_mul_f32 v[140:141], v[108:109], v[134:135] op_sel_hi:[1,0]
	v_pk_mul_f32 v[138:139], v[110:111], v[134:135] op_sel_hi:[1,0]
	v_mul_f32_e32 v135, 0xbfb8aa3b, v141
	v_exp_f32_e32 v135, v135
	v_mul_f32_e32 v133, 0xbfb8aa3b, v140
	v_mul_f32_e32 v137, 0xbfb8aa3b, v138
	v_mul_f32_e32 v138, 0xbfb8aa3b, v139
	v_pk_mul_f32 v[140:141], v[104:105], v[134:135] op_sel_hi:[1,0]
	v_exp_f32_e32 v138, v138
	v_mul_f32_e32 v139, 0xbfb8aa3b, v140
	v_exp_f32_e32 v139, v139
	v_mul_f32_e32 v140, 0xbfb8aa3b, v141
	v_exp_f32_e32 v140, v140
	v_add_f32_e32 v138, 1.0, v138
	v_rcp_f32_e32 v141, v138
	v_add_f32_e32 v138, 1.0, v139
	v_mul_f32_e32 v139, 0xbfb8aa3b, v142
	v_rcp_f32_e32 v144, v138
	v_add_f32_e32 v138, 1.0, v140
	v_exp_f32_e32 v139, v139
	v_mul_f32_e32 v140, 0xbfb8aa3b, v143
	v_exp_f32_e32 v133, v133
	v_exp_f32_e32 v137, v137
	v_exp_f32_e32 v140, v140
	v_rcp_f32_e32 v142, v138
	v_add_f32_e32 v138, 1.0, v139
	v_add_f32_e32 v133, 1.0, v133
	v_add_f32_e32 v135, 1.0, v135
	v_add_f32_e32 v137, 1.0, v137
	v_rcp_f32_e32 v143, v138
	v_add_f32_e32 v138, 1.0, v140
	v_rcp_f32_e32 v133, v133
	v_rcp_f32_e32 v135, v135
	v_rcp_f32_e32 v137, v137
	v_rcp_f32_e32 v145, v138
	s_mov_b32 s8, 0x2c510000
	v_cvt_pk_bf16_f32 v140, v144, v142
	v_add_co_u32_e32 v142, vcc, s8, v128
	v_cvt_pk_bf16_f32 v138, v133, v135
	v_cvt_pk_bf16_f32 v139, v137, v141
	v_cvt_pk_bf16_f32 v141, v143, v145
	v_addc_co_u32_e32 v143, vcc, 0, v129, vcc
	global_store_dwordx4 v[142:143], v[138:141], off
	v_pk_mul_f32 v[142:143], v[98:99], v[134:135] op_sel_hi:[1,0]
	s_mov_b64 s[8:9], 0x2c520000
	v_pk_mul_f32 v[138:139], v[102:103], v[134:135] op_sel_hi:[1,0]
	v_pk_mul_f32 v[140:141], v[100:101], v[134:135] op_sel_hi:[1,0]
	v_mul_f32_e32 v138, 0xbfb8aa3b, v138
	v_exp_f32_e32 v138, v138
	v_mul_f32_e32 v139, 0xbfb8aa3b, v139
	v_exp_f32_e32 v139, v139
	v_mul_f32_e32 v133, 0xbfb8aa3b, v140
	v_add_f32_e32 v138, 1.0, v138
	v_mul_f32_e32 v135, 0xbfb8aa3b, v141
	v_rcp_f32_e32 v140, v138
	v_add_f32_e32 v138, 1.0, v139
	v_exp_f32_e32 v137, v135
	v_pk_mul_f32 v[134:135], v[96:97], v[134:135] op_sel_hi:[1,0]
	v_rcp_f32_e32 v139, v138
	v_mul_f32_e32 v138, 0xbfb8aa3b, v142
	v_mul_f32_e32 v134, 0xbfb8aa3b, v134
	v_mul_f32_e32 v135, 0xbfb8aa3b, v135
	v_exp_f32_e32 v138, v138
	v_mul_f32_e32 v141, 0xbfb8aa3b, v143
	v_exp_f32_e32 v133, v133
	v_exp_f32_e32 v134, v134
	v_exp_f32_e32 v135, v135
	v_exp_f32_e32 v141, v141
	v_add_f32_e32 v138, 1.0, v138
	v_add_f32_e32 v133, 1.0, v133
	v_add_f32_e32 v137, 1.0, v137
	v_add_f32_e32 v134, 1.0, v134
	v_add_f32_e32 v135, 1.0, v135
	v_rcp_f32_e32 v142, v138
	v_add_f32_e32 v138, 1.0, v141
	v_rcp_f32_e32 v133, v133
	v_rcp_f32_e32 v137, v137
	v_rcp_f32_e32 v134, v134
	v_rcp_f32_e32 v135, v135
	v_rcp_f32_e32 v141, v138
	v_cvt_pk_bf16_f32 v138, v133, v137
	v_cvt_pk_bf16_f32 v139, v140, v139
	v_cvt_pk_bf16_f32 v140, v134, v135
	v_cvt_pk_bf16_f32 v141, v142, v141
	global_store_dwordx4 v[130:131], v[138:141], off offset:256
	v_pk_mul_f32 v[134:135], v[94:95], v[184:185] op_sel_hi:[1,0]
	v_lshl_add_u64 v[130:131], v[128:129], 0, s[8:9]
	v_pk_mul_f32 v[138:139], v[92:93], v[184:185] op_sel_hi:[1,0]
	v_pk_mul_f32 v[140:141], v[90:91], v[184:185] op_sel_hi:[1,0]
	v_mul_f32_e32 v133, 0xbfb8aa3b, v138
	v_mul_f32_e32 v137, 0xbfb8aa3b, v139
	v_pk_mul_f32 v[138:139], v[88:89], v[184:185] op_sel_hi:[1,0]
	v_mul_f32_e32 v134, 0xbfb8aa3b, v134
	v_mul_f32_e32 v138, 0xbfb8aa3b, v138
	v_exp_f32_e32 v138, v138
	v_mul_f32_e32 v139, 0xbfb8aa3b, v139
	v_exp_f32_e32 v139, v139
	v_mul_f32_e32 v135, 0xbfb8aa3b, v135
	v_add_f32_e32 v138, 1.0, v138
	v_rcp_f32_e32 v142, v138
	v_add_f32_e32 v138, 1.0, v139
	v_mul_f32_e32 v139, 0xbfb8aa3b, v140
	v_exp_f32_e32 v134, v134
	v_exp_f32_e32 v135, v135
	v_exp_f32_e32 v139, v139
	v_mul_f32_e32 v140, 0xbfb8aa3b, v141
	v_exp_f32_e32 v133, v133
	v_exp_f32_e32 v137, v137
	v_exp_f32_e32 v140, v140
	v_add_f32_e32 v134, 1.0, v134
	v_add_f32_e32 v135, 1.0, v135
	v_rcp_f32_e32 v141, v138
	v_add_f32_e32 v138, 1.0, v139
	v_add_f32_e32 v133, 1.0, v133
	v_add_f32_e32 v137, 1.0, v137
	v_rcp_f32_e32 v134, v134
	v_rcp_f32_e32 v135, v135
	v_rcp_f32_e32 v143, v138
	v_add_f32_e32 v138, 1.0, v140
	v_rcp_f32_e32 v133, v133
	v_rcp_f32_e32 v137, v137
	v_rcp_f32_e32 v144, v138
	s_mov_b32 s8, 0x2c520000
	v_cvt_pk_bf16_f32 v139, v134, v135
	v_add_co_u32_e32 v134, vcc, s8, v128
	v_cvt_pk_bf16_f32 v138, v133, v137
	v_cvt_pk_bf16_f32 v140, v142, v141
	v_cvt_pk_bf16_f32 v141, v143, v144
	v_addc_co_u32_e32 v135, vcc, 0, v129, vcc
	global_store_dwordx4 v[134:135], v[138:141], off
	v_pk_mul_f32 v[134:135], v[86:87], v[184:185] op_sel_hi:[1,0]
	s_mov_b64 s[8:9], 0x2c530000
	v_pk_mul_f32 v[138:139], v[84:85], v[184:185] op_sel_hi:[1,0]
	v_pk_mul_f32 v[140:141], v[82:83], v[184:185] op_sel_hi:[1,0]
	v_mul_f32_e32 v133, 0xbfb8aa3b, v138
	v_mul_f32_e32 v137, 0xbfb8aa3b, v139
	v_pk_mul_f32 v[138:139], v[80:81], v[184:185] op_sel_hi:[1,0]
	v_mul_f32_e32 v134, 0xbfb8aa3b, v134
	v_mul_f32_e32 v138, 0xbfb8aa3b, v138
	v_exp_f32_e32 v138, v138
	v_mul_f32_e32 v139, 0xbfb8aa3b, v139
	v_exp_f32_e32 v139, v139
	v_mul_f32_e32 v135, 0xbfb8aa3b, v135
	v_add_f32_e32 v138, 1.0, v138
	v_rcp_f32_e32 v142, v138
	v_add_f32_e32 v138, 1.0, v139
	v_mul_f32_e32 v139, 0xbfb8aa3b, v140
; __device__ __forceinline__ unsigned cvt_pk_bf16(float lo, float hi) { f32x2_t v = {lo, hi}; bf16x2_t r = __builtin_convertvector(v, bf16x2_t); return __builtin_bit_cast(unsigned, r); }
; __device__ __forceinline__ float sigmoid_f(float x) { return __builtin_amdgcn_rcpf(1.f + __expf(-x)); }
; __device__ __forceinline__ f32x4 sigmoid4(f32x4 v) { return (f32x4){sigmoid_f(v[0]), sigmoid_f(v[1]), sigmoid_f(v[2]), sigmoid_f(v[3])}; }
; __device__ __forceinline__ f32x4 silu4(f32x4 v) { return v * sigmoid4(v); }
; __device__ __forceinline__ u32x4 pack8bf(f32x4 a, f32x4 b) {
;     u32x4 w; w.x = pg8::cvt_pk_bf16(a[0], a[1]); w.y = pg8::cvt_pk_bf16(a[2], a[3]); w.z = pg8::cvt_pk_bf16(b[0], b[1]); w.w = pg8::cvt_pk_bf16(b[2], b[3]); return w;
; }
;     template <int MODE, bool HEADMAJOR>
;     __device__ __forceinline__ void plain(const f32x4 (&acc)[2][2][4][2], const float (&rs)[2][4], bf16_t* base, int row0, int pl, int wc, int fq) const {
; #pragma unroll
;         for (int ai = 0; ai < 2; ++ai)
; #pragma unroll
;             for (int m = 0; m < 4; ++m) { const int row = row0 + ai * 128 + m * 16;
; #pragma unroll
;                 for (int bj = 0; bj < 2; ++bj) { f32x4 v0 = acc[ai][bj][m][0] * rs[ai][m], v1 = acc[ai][bj][m][1] * rs[ai][m];
;                     if (MODE == 1) { v0 = v0 * 0.08838834764831845f; v1 = v1 * 0.08838834764831845f; }
;                     if (MODE == 2) { v0 = silu4(v0); v1 = silu4(v1); }
;                     if (MODE == 3) { v0 = sigmoid4(v0); v1 = sigmoid4(v1); }
;                     bf16_t* ptr = HEADMAJOR ? base + ((size_t)(pl * 2 + bj) * S + row) * 128 + 32 * wc + 8 * fq
;                                             : base + (size_t)row * DM + pl * 256 + bj * 128 + 32 * wc + 8 * fq;
;                     *(u32x4*)ptr = pack8bf(v0, v1); }
;                 asm volatile("" ::: "memory"); }
	v_exp_f32_e32 v139, v139
	v_mul_f32_e32 v140, 0xbfb8aa3b, v141
	v_exp_f32_e32 v133, v133
	v_exp_f32_e32 v137, v137
	v_exp_f32_e32 v134, v134
	v_exp_f32_e32 v135, v135
	v_exp_f32_e32 v140, v140
	v_rcp_f32_e32 v141, v138
	v_add_f32_e32 v138, 1.0, v139
	v_add_f32_e32 v133, 1.0, v133
	v_add_f32_e32 v137, 1.0, v137
	v_add_f32_e32 v134, 1.0, v134
	v_add_f32_e32 v135, 1.0, v135
	v_rcp_f32_e32 v143, v138
	v_add_f32_e32 v138, 1.0, v140
	v_rcp_f32_e32 v133, v133
	v_rcp_f32_e32 v137, v137
	v_rcp_f32_e32 v134, v134
	v_rcp_f32_e32 v135, v135
	v_rcp_f32_e32 v144, v138
	v_cvt_pk_bf16_f32 v138, v133, v137
	v_cvt_pk_bf16_f32 v140, v142, v141
	v_cvt_pk_bf16_f32 v139, v134, v135
	v_cvt_pk_bf16_f32 v141, v143, v144
	v_mov_b32_e32 v134, v185
	global_store_dwordx4 v[130:131], v[138:141], off offset:256
	v_pk_mul_f32 v[142:143], v[74:75], v[134:135] op_sel_hi:[1,0]
	v_lshl_add_u64 v[130:131], v[128:129], 0, s[8:9]
	v_pk_mul_f32 v[140:141], v[76:77], v[134:135] op_sel_hi:[1,0]
	v_pk_mul_f32 v[138:139], v[78:79], v[134:135] op_sel_hi:[1,0]
	v_mul_f32_e32 v135, 0xbfb8aa3b, v141
	v_exp_f32_e32 v135, v135
	v_mul_f32_e32 v133, 0xbfb8aa3b, v140
	v_mul_f32_e32 v137, 0xbfb8aa3b, v138
	v_mul_f32_e32 v138, 0xbfb8aa3b, v139
	v_pk_mul_f32 v[140:141], v[72:73], v[134:135] op_sel_hi:[1,0]
	v_exp_f32_e32 v138, v138
	v_mul_f32_e32 v139, 0xbfb8aa3b, v140
	v_exp_f32_e32 v139, v139
	v_mul_f32_e32 v140, 0xbfb8aa3b, v141
	v_exp_f32_e32 v140, v140
	v_add_f32_e32 v138, 1.0, v138
	v_rcp_f32_e32 v141, v138
	v_add_f32_e32 v138, 1.0, v139
	v_mul_f32_e32 v139, 0xbfb8aa3b, v142
	v_rcp_f32_e32 v144, v138
	v_add_f32_e32 v138, 1.0, v140
	v_exp_f32_e32 v139, v139
	v_mul_f32_e32 v140, 0xbfb8aa3b, v143
	v_exp_f32_e32 v133, v133
	v_exp_f32_e32 v137, v137
	v_exp_f32_e32 v140, v140
	v_rcp_f32_e32 v142, v138
	v_add_f32_e32 v138, 1.0, v139
	v_add_f32_e32 v133, 1.0, v133
	v_add_f32_e32 v135, 1.0, v135
	v_add_f32_e32 v137, 1.0, v137
	v_rcp_f32_e32 v143, v138
	v_add_f32_e32 v138, 1.0, v140
	v_rcp_f32_e32 v133, v133
	v_rcp_f32_e32 v135, v135
	v_rcp_f32_e32 v137, v137
	v_rcp_f32_e32 v145, v138
	s_mov_b32 s8, 0x2c530000
	v_cvt_pk_bf16_f32 v140, v144, v142
	v_add_co_u32_e32 v142, vcc, s8, v128
	v_cvt_pk_bf16_f32 v138, v133, v135
	v_cvt_pk_bf16_f32 v139, v137, v141
	v_cvt_pk_bf16_f32 v141, v143, v145
	v_addc_co_u32_e32 v143, vcc, 0, v129, vcc
	global_store_dwordx4 v[142:143], v[138:141], off
	v_pk_mul_f32 v[142:143], v[66:67], v[134:135] op_sel_hi:[1,0]
	s_mov_b64 s[8:9], 0x2c580000
	v_pk_mul_f32 v[138:139], v[70:71], v[134:135] op_sel_hi:[1,0]
	v_pk_mul_f32 v[140:141], v[68:69], v[134:135] op_sel_hi:[1,0]
	v_mul_f32_e32 v138, 0xbfb8aa3b, v138
	v_exp_f32_e32 v138, v138
	v_mul_f32_e32 v139, 0xbfb8aa3b, v139
	v_exp_f32_e32 v139, v139
	v_mul_f32_e32 v133, 0xbfb8aa3b, v140
	v_add_f32_e32 v138, 1.0, v138
	v_mul_f32_e32 v135, 0xbfb8aa3b, v141
	v_rcp_f32_e32 v140, v138
	v_add_f32_e32 v138, 1.0, v139
	v_exp_f32_e32 v137, v135
	v_pk_mul_f32 v[134:135], v[64:65], v[134:135] op_sel_hi:[1,0]
	v_rcp_f32_e32 v139, v138
	v_mul_f32_e32 v138, 0xbfb8aa3b, v142
	v_mul_f32_e32 v134, 0xbfb8aa3b, v134
	v_mul_f32_e32 v135, 0xbfb8aa3b, v135
	v_exp_f32_e32 v138, v138
	v_mul_f32_e32 v141, 0xbfb8aa3b, v143
	v_exp_f32_e32 v133, v133
	v_exp_f32_e32 v134, v134
	v_exp_f32_e32 v135, v135
	v_exp_f32_e32 v141, v141
	v_add_f32_e32 v138, 1.0, v138
	v_add_f32_e32 v133, 1.0, v133
	v_add_f32_e32 v137, 1.0, v137
	v_add_f32_e32 v134, 1.0, v134
	v_add_f32_e32 v135, 1.0, v135
	v_rcp_f32_e32 v142, v138
	v_add_f32_e32 v138, 1.0, v141
	v_rcp_f32_e32 v133, v133
	v_rcp_f32_e32 v137, v137
	v_rcp_f32_e32 v134, v134
	v_rcp_f32_e32 v135, v135
	v_rcp_f32_e32 v141, v138
	v_cvt_pk_bf16_f32 v138, v133, v137
	v_cvt_pk_bf16_f32 v139, v140, v139
	v_cvt_pk_bf16_f32 v140, v134, v135
	v_cvt_pk_bf16_f32 v141, v142, v141
	global_store_dwordx4 v[130:131], v[138:141], off offset:256
	v_pk_mul_f32 v[134:135], v[62:63], v[180:181] op_sel_hi:[1,0]
	v_lshl_add_u64 v[130:131], v[128:129], 0, s[8:9]
	v_pk_mul_f32 v[138:139], v[60:61], v[180:181] op_sel_hi:[1,0]
	v_pk_mul_f32 v[140:141], v[58:59], v[180:181] op_sel_hi:[1,0]
	v_mul_f32_e32 v133, 0xbfb8aa3b, v138
	v_mul_f32_e32 v137, 0xbfb8aa3b, v139
	v_pk_mul_f32 v[138:139], v[56:57], v[180:181] op_sel_hi:[1,0]
	v_mul_f32_e32 v134, 0xbfb8aa3b, v134
	v_mul_f32_e32 v138, 0xbfb8aa3b, v138
	v_exp_f32_e32 v138, v138
	v_mul_f32_e32 v139, 0xbfb8aa3b, v139
	v_exp_f32_e32 v139, v139
	v_mul_f32_e32 v135, 0xbfb8aa3b, v135
	v_add_f32_e32 v138, 1.0, v138
	v_rcp_f32_e32 v142, v138
	v_add_f32_e32 v138, 1.0, v139
	v_mul_f32_e32 v139, 0xbfb8aa3b, v140
	v_exp_f32_e32 v134, v134
	v_exp_f32_e32 v135, v135
	v_exp_f32_e32 v139, v139
	v_mul_f32_e32 v140, 0xbfb8aa3b, v141
	v_exp_f32_e32 v133, v133
	v_exp_f32_e32 v137, v137
	v_exp_f32_e32 v140, v140
	v_add_f32_e32 v134, 1.0, v134
	v_add_f32_e32 v135, 1.0, v135
	v_rcp_f32_e32 v141, v138
	v_add_f32_e32 v138, 1.0, v139
	v_add_f32_e32 v133, 1.0, v133
	v_add_f32_e32 v137, 1.0, v137
	v_rcp_f32_e32 v134, v134
	v_rcp_f32_e32 v135, v135
	v_rcp_f32_e32 v143, v138
	v_add_f32_e32 v138, 1.0, v140
	v_rcp_f32_e32 v133, v133
	v_rcp_f32_e32 v137, v137
	v_rcp_f32_e32 v144, v138
	s_mov_b32 s8, 0x2c580000
	v_cvt_pk_bf16_f32 v139, v134, v135
	v_add_co_u32_e32 v134, vcc, s8, v128
	v_cvt_pk_bf16_f32 v138, v133, v137
	v_cvt_pk_bf16_f32 v140, v142, v141
	v_cvt_pk_bf16_f32 v141, v143, v144
	v_addc_co_u32_e32 v135, vcc, 0, v129, vcc
	global_store_dwordx4 v[134:135], v[138:141], off
	v_pk_mul_f32 v[134:135], v[54:55], v[180:181] op_sel_hi:[1,0]
	s_mov_b64 s[8:9], 0x2c590000
	v_pk_mul_f32 v[138:139], v[52:53], v[180:181] op_sel_hi:[1,0]
	v_pk_mul_f32 v[140:141], v[50:51], v[180:181] op_sel_hi:[1,0]
	v_mul_f32_e32 v133, 0xbfb8aa3b, v138
; __device__ __forceinline__ unsigned cvt_pk_bf16(float lo, float hi) { f32x2_t v = {lo, hi}; bf16x2_t r = __builtin_convertvector(v, bf16x2_t); return __builtin_bit_cast(unsigned, r); }
; __device__ __forceinline__ float sigmoid_f(float x) { return __builtin_amdgcn_rcpf(1.f + __expf(-x)); }
; __device__ __forceinline__ f32x4 sigmoid4(f32x4 v) { return (f32x4){sigmoid_f(v[0]), sigmoid_f(v[1]), sigmoid_f(v[2]), sigmoid_f(v[3])}; }
; __device__ __forceinline__ f32x4 silu4(f32x4 v) { return v * sigmoid4(v); }
; __device__ __forceinline__ u32x4 pack8bf(f32x4 a, f32x4 b) {
;     u32x4 w; w.x = pg8::cvt_pk_bf16(a[0], a[1]); w.y = pg8::cvt_pk_bf16(a[2], a[3]); w.z = pg8::cvt_pk_bf16(b[0], b[1]); w.w = pg8::cvt_pk_bf16(b[2], b[3]); return w;
; }
;     template <int MODE, bool HEADMAJOR>
;     __device__ __forceinline__ void plain(const f32x4 (&acc)[2][2][4][2], const float (&rs)[2][4], bf16_t* base, int row0, int pl, int wc, int fq) const {
; #pragma unroll
;         for (int ai = 0; ai < 2; ++ai)
; #pragma unroll
;             for (int m = 0; m < 4; ++m) { const int row = row0 + ai * 128 + m * 16;
; #pragma unroll
;                 for (int bj = 0; bj < 2; ++bj) { f32x4 v0 = acc[ai][bj][m][0] * rs[ai][m], v1 = acc[ai][bj][m][1] * rs[ai][m];
;                     if (MODE == 1) { v0 = v0 * 0.08838834764831845f; v1 = v1 * 0.08838834764831845f; }
;                     if (MODE == 2) { v0 = silu4(v0); v1 = silu4(v1); }
;                     if (MODE == 3) { v0 = sigmoid4(v0); v1 = sigmoid4(v1); }
;                     bf16_t* ptr = HEADMAJOR ? base + ((size_t)(pl * 2 + bj) * S + row) * 128 + 32 * wc + 8 * fq
;                                             : base + (size_t)row * DM + pl * 256 + bj * 128 + 32 * wc + 8 * fq;
;                     *(u32x4*)ptr = pack8bf(v0, v1); }
;                 asm volatile("" ::: "memory"); }
	v_mul_f32_e32 v137, 0xbfb8aa3b, v139
	v_pk_mul_f32 v[138:139], v[48:49], v[180:181] op_sel_hi:[1,0]
	v_mul_f32_e32 v134, 0xbfb8aa3b, v134
	v_mul_f32_e32 v138, 0xbfb8aa3b, v138
	v_exp_f32_e32 v138, v138
	v_mul_f32_e32 v139, 0xbfb8aa3b, v139
	v_exp_f32_e32 v139, v139
	v_mul_f32_e32 v135, 0xbfb8aa3b, v135
	v_add_f32_e32 v138, 1.0, v138
	v_rcp_f32_e32 v142, v138
	v_add_f32_e32 v138, 1.0, v139
	v_mul_f32_e32 v139, 0xbfb8aa3b, v140
	v_exp_f32_e32 v139, v139
	v_mul_f32_e32 v140, 0xbfb8aa3b, v141
	v_exp_f32_e32 v133, v133
	v_exp_f32_e32 v137, v137
	v_exp_f32_e32 v134, v134
	v_exp_f32_e32 v135, v135
	v_exp_f32_e32 v140, v140
	v_rcp_f32_e32 v141, v138
	v_add_f32_e32 v138, 1.0, v139
	v_add_f32_e32 v133, 1.0, v133
	v_add_f32_e32 v137, 1.0, v137
	v_add_f32_e32 v134, 1.0, v134
	v_add_f32_e32 v135, 1.0, v135
	v_rcp_f32_e32 v143, v138
	v_add_f32_e32 v138, 1.0, v140
	v_rcp_f32_e32 v133, v133
	v_rcp_f32_e32 v137, v137
	v_rcp_f32_e32 v134, v134
	v_rcp_f32_e32 v135, v135
	v_rcp_f32_e32 v144, v138
	v_cvt_pk_bf16_f32 v138, v133, v137
	v_cvt_pk_bf16_f32 v140, v142, v141
	v_cvt_pk_bf16_f32 v139, v134, v135
	v_cvt_pk_bf16_f32 v141, v143, v144
	v_mov_b32_e32 v134, v181
	global_store_dwordx4 v[130:131], v[138:141], off offset:256
	v_pk_mul_f32 v[142:143], v[42:43], v[134:135] op_sel_hi:[1,0]
	v_lshl_add_u64 v[130:131], v[128:129], 0, s[8:9]
	v_pk_mul_f32 v[140:141], v[44:45], v[134:135] op_sel_hi:[1,0]
	v_pk_mul_f32 v[138:139], v[46:47], v[134:135] op_sel_hi:[1,0]
	v_mul_f32_e32 v135, 0xbfb8aa3b, v141
	v_exp_f32_e32 v135, v135
	v_mul_f32_e32 v133, 0xbfb8aa3b, v140
	v_mul_f32_e32 v137, 0xbfb8aa3b, v138
	v_mul_f32_e32 v138, 0xbfb8aa3b, v139
	v_pk_mul_f32 v[140:141], v[40:41], v[134:135] op_sel_hi:[1,0]
	v_exp_f32_e32 v138, v138
	v_mul_f32_e32 v139, 0xbfb8aa3b, v140
	v_exp_f32_e32 v139, v139
	v_mul_f32_e32 v140, 0xbfb8aa3b, v141
	v_exp_f32_e32 v140, v140
	v_add_f32_e32 v138, 1.0, v138
	v_rcp_f32_e32 v141, v138
	v_add_f32_e32 v138, 1.0, v139
	v_mul_f32_e32 v139, 0xbfb8aa3b, v142
	v_rcp_f32_e32 v144, v138
	v_add_f32_e32 v138, 1.0, v140
	v_exp_f32_e32 v139, v139
	v_mul_f32_e32 v140, 0xbfb8aa3b, v143
	v_exp_f32_e32 v133, v133
	v_exp_f32_e32 v137, v137
	v_exp_f32_e32 v140, v140
	v_rcp_f32_e32 v142, v138
	v_add_f32_e32 v138, 1.0, v139
	v_add_f32_e32 v133, 1.0, v133
	v_add_f32_e32 v135, 1.0, v135
	v_add_f32_e32 v137, 1.0, v137
	v_rcp_f32_e32 v143, v138
	v_add_f32_e32 v138, 1.0, v140
	v_rcp_f32_e32 v133, v133
	v_rcp_f32_e32 v135, v135
	v_rcp_f32_e32 v137, v137
	v_rcp_f32_e32 v145, v138
	s_mov_b32 s8, 0x2c590000
	v_cvt_pk_bf16_f32 v140, v144, v142
	v_add_co_u32_e32 v142, vcc, s8, v128
	v_cvt_pk_bf16_f32 v138, v133, v135
	v_cvt_pk_bf16_f32 v139, v137, v141
	v_cvt_pk_bf16_f32 v141, v143, v145
	v_addc_co_u32_e32 v143, vcc, 0, v129, vcc
	global_store_dwordx4 v[142:143], v[138:141], off
	v_pk_mul_f32 v[142:143], v[34:35], v[134:135] op_sel_hi:[1,0]
	s_mov_b64 s[8:9], 0x2c5a0000
	v_pk_mul_f32 v[138:139], v[38:39], v[134:135] op_sel_hi:[1,0]
	v_pk_mul_f32 v[140:141], v[36:37], v[134:135] op_sel_hi:[1,0]
	v_mul_f32_e32 v138, 0xbfb8aa3b, v138
	v_exp_f32_e32 v138, v138
	v_mul_f32_e32 v139, 0xbfb8aa3b, v139
	v_exp_f32_e32 v139, v139
	v_mul_f32_e32 v133, 0xbfb8aa3b, v140
	v_add_f32_e32 v138, 1.0, v138
	v_mul_f32_e32 v135, 0xbfb8aa3b, v141
	v_rcp_f32_e32 v140, v138
	v_add_f32_e32 v138, 1.0, v139
	v_exp_f32_e32 v137, v135
	v_pk_mul_f32 v[134:135], v[32:33], v[134:135] op_sel_hi:[1,0]
	v_rcp_f32_e32 v139, v138
	v_mul_f32_e32 v138, 0xbfb8aa3b, v142
	v_mul_f32_e32 v134, 0xbfb8aa3b, v134
	v_mul_f32_e32 v135, 0xbfb8aa3b, v135
	v_exp_f32_e32 v138, v138
	v_mul_f32_e32 v141, 0xbfb8aa3b, v143
	v_exp_f32_e32 v133, v133
	v_exp_f32_e32 v134, v134
	v_exp_f32_e32 v135, v135
	v_exp_f32_e32 v141, v141
	v_add_f32_e32 v138, 1.0, v138
	v_add_f32_e32 v133, 1.0, v133
	v_add_f32_e32 v137, 1.0, v137
	v_add_f32_e32 v134, 1.0, v134
	v_add_f32_e32 v135, 1.0, v135
	v_rcp_f32_e32 v142, v138
	v_add_f32_e32 v138, 1.0, v141
	v_rcp_f32_e32 v133, v133
	v_rcp_f32_e32 v137, v137
	v_rcp_f32_e32 v134, v134
	v_rcp_f32_e32 v135, v135
	v_rcp_f32_e32 v141, v138
	v_cvt_pk_bf16_f32 v138, v133, v137
	v_cvt_pk_bf16_f32 v139, v140, v139
	v_cvt_pk_bf16_f32 v140, v134, v135
	v_cvt_pk_bf16_f32 v141, v142, v141
	global_store_dwordx4 v[130:131], v[138:141], off offset:256
	v_pk_mul_f32 v[134:135], v[30:31], v[178:179] op_sel_hi:[1,0]
	v_lshl_add_u64 v[130:131], v[128:129], 0, s[8:9]
	v_pk_mul_f32 v[138:139], v[28:29], v[178:179] op_sel_hi:[1,0]
	v_pk_mul_f32 v[140:141], v[26:27], v[178:179] op_sel_hi:[1,0]
	v_mul_f32_e32 v133, 0xbfb8aa3b, v138
	v_mul_f32_e32 v137, 0xbfb8aa3b, v139
	v_pk_mul_f32 v[138:139], v[24:25], v[178:179] op_sel_hi:[1,0]
	v_mul_f32_e32 v134, 0xbfb8aa3b, v134
	v_mul_f32_e32 v138, 0xbfb8aa3b, v138
	v_exp_f32_e32 v138, v138
	v_mul_f32_e32 v139, 0xbfb8aa3b, v139
	v_exp_f32_e32 v139, v139
	v_mul_f32_e32 v135, 0xbfb8aa3b, v135
	v_add_f32_e32 v138, 1.0, v138
	v_rcp_f32_e32 v142, v138
	v_add_f32_e32 v138, 1.0, v139
	v_mul_f32_e32 v139, 0xbfb8aa3b, v140
	v_exp_f32_e32 v134, v134
	v_exp_f32_e32 v135, v135
	v_exp_f32_e32 v139, v139
	v_mul_f32_e32 v140, 0xbfb8aa3b, v141
	v_exp_f32_e32 v133, v133
	v_exp_f32_e32 v137, v137
	v_exp_f32_e32 v140, v140
; __device__ __forceinline__ unsigned cvt_pk_bf16(float lo, float hi) { f32x2_t v = {lo, hi}; bf16x2_t r = __builtin_convertvector(v, bf16x2_t); return __builtin_bit_cast(unsigned, r); }
; __device__ __forceinline__ float sigmoid_f(float x) { return __builtin_amdgcn_rcpf(1.f + __expf(-x)); }
; __device__ __forceinline__ f32x4 sigmoid4(f32x4 v) { return (f32x4){sigmoid_f(v[0]), sigmoid_f(v[1]), sigmoid_f(v[2]), sigmoid_f(v[3])}; }
; __device__ __forceinline__ f32x4 silu4(f32x4 v) { return v * sigmoid4(v); }
; __device__ __forceinline__ u32x4 pack8bf(f32x4 a, f32x4 b) {
;     u32x4 w; w.x = pg8::cvt_pk_bf16(a[0], a[1]); w.y = pg8::cvt_pk_bf16(a[2], a[3]); w.z = pg8::cvt_pk_bf16(b[0], b[1]); w.w = pg8::cvt_pk_bf16(b[2], b[3]); return w;
; }
;     template <int MODE, bool HEADMAJOR>
;     __device__ __forceinline__ void plain(const f32x4 (&acc)[2][2][4][2], const float (&rs)[2][4], bf16_t* base, int row0, int pl, int wc, int fq) const {
; #pragma unroll
;         for (int ai = 0; ai < 2; ++ai)
; #pragma unroll
;             for (int m = 0; m < 4; ++m) { const int row = row0 + ai * 128 + m * 16;
; #pragma unroll
;                 for (int bj = 0; bj < 2; ++bj) { f32x4 v0 = acc[ai][bj][m][0] * rs[ai][m], v1 = acc[ai][bj][m][1] * rs[ai][m];
;                     if (MODE == 1) { v0 = v0 * 0.08838834764831845f; v1 = v1 * 0.08838834764831845f; }
;                     if (MODE == 2) { v0 = silu4(v0); v1 = silu4(v1); }
;                     if (MODE == 3) { v0 = sigmoid4(v0); v1 = sigmoid4(v1); }
;                     bf16_t* ptr = HEADMAJOR ? base + ((size_t)(pl * 2 + bj) * S + row) * 128 + 32 * wc + 8 * fq
;                                             : base + (size_t)row * DM + pl * 256 + bj * 128 + 32 * wc + 8 * fq;
;                     *(u32x4*)ptr = pack8bf(v0, v1); }
;                 asm volatile("" ::: "memory"); }
	v_add_f32_e32 v134, 1.0, v134
	v_add_f32_e32 v135, 1.0, v135
	v_rcp_f32_e32 v141, v138
	v_add_f32_e32 v138, 1.0, v139
	v_add_f32_e32 v133, 1.0, v133
	v_add_f32_e32 v137, 1.0, v137
	v_rcp_f32_e32 v134, v134
	v_rcp_f32_e32 v135, v135
	v_rcp_f32_e32 v143, v138
	v_add_f32_e32 v138, 1.0, v140
	v_rcp_f32_e32 v133, v133
	v_rcp_f32_e32 v137, v137
	v_rcp_f32_e32 v144, v138
	s_mov_b32 s8, 0x2c5a0000
	v_cvt_pk_bf16_f32 v139, v134, v135
	v_add_co_u32_e32 v134, vcc, s8, v128
	v_cvt_pk_bf16_f32 v138, v133, v137
	v_cvt_pk_bf16_f32 v140, v142, v141
	v_cvt_pk_bf16_f32 v141, v143, v144
	v_addc_co_u32_e32 v135, vcc, 0, v129, vcc
	global_store_dwordx4 v[134:135], v[138:141], off
	v_pk_mul_f32 v[134:135], v[22:23], v[178:179] op_sel_hi:[1,0]
	s_mov_b64 s[8:9], 0x2c5b0000
	v_pk_mul_f32 v[138:139], v[20:21], v[178:179] op_sel_hi:[1,0]
	v_pk_mul_f32 v[140:141], v[18:19], v[178:179] op_sel_hi:[1,0]
	v_mul_f32_e32 v133, 0xbfb8aa3b, v138
	v_mul_f32_e32 v137, 0xbfb8aa3b, v139
	v_pk_mul_f32 v[138:139], v[16:17], v[178:179] op_sel_hi:[1,0]
	v_mul_f32_e32 v134, 0xbfb8aa3b, v134
	v_mul_f32_e32 v138, 0xbfb8aa3b, v138
	v_exp_f32_e32 v138, v138
	v_mul_f32_e32 v139, 0xbfb8aa3b, v139
	v_exp_f32_e32 v139, v139
	v_mul_f32_e32 v135, 0xbfb8aa3b, v135
	v_add_f32_e32 v138, 1.0, v138
	v_rcp_f32_e32 v142, v138
	v_add_f32_e32 v138, 1.0, v139
	v_mul_f32_e32 v139, 0xbfb8aa3b, v140
	v_exp_f32_e32 v139, v139
	v_mul_f32_e32 v140, 0xbfb8aa3b, v141
	v_exp_f32_e32 v133, v133
	v_exp_f32_e32 v137, v137
	v_exp_f32_e32 v134, v134
	v_exp_f32_e32 v135, v135
	v_exp_f32_e32 v140, v140
	v_rcp_f32_e32 v141, v138
	v_add_f32_e32 v138, 1.0, v139
	v_add_f32_e32 v133, 1.0, v133
	v_add_f32_e32 v137, 1.0, v137
	v_add_f32_e32 v134, 1.0, v134
	v_add_f32_e32 v135, 1.0, v135
	v_rcp_f32_e32 v143, v138
	v_add_f32_e32 v138, 1.0, v140
	v_rcp_f32_e32 v133, v133
	v_rcp_f32_e32 v137, v137
	v_rcp_f32_e32 v134, v134
	v_rcp_f32_e32 v135, v135
	v_rcp_f32_e32 v144, v138
	v_cvt_pk_bf16_f32 v138, v133, v137
	v_cvt_pk_bf16_f32 v140, v142, v141
	v_cvt_pk_bf16_f32 v139, v134, v135
	v_cvt_pk_bf16_f32 v141, v143, v144
	global_store_dwordx4 v[130:131], v[138:141], off offset:256
	v_mov_b32_e32 v130, v179
	v_pk_mul_f32 v[142:143], v[10:11], v[130:131] op_sel_hi:[1,0]
	v_pk_mul_f32 v[140:141], v[12:13], v[130:131] op_sel_hi:[1,0]
	v_pk_mul_f32 v[138:139], v[14:15], v[130:131] op_sel_hi:[1,0]
	v_mul_f32_e32 v131, 0xbfb8aa3b, v140
	v_exp_f32_e32 v131, v131
	v_mul_f32_e32 v133, 0xbfb8aa3b, v141
	v_mul_f32_e32 v137, 0xbfb8aa3b, v138
	v_mul_f32_e32 v138, 0xbfb8aa3b, v139
	v_pk_mul_f32 v[140:141], v[8:9], v[130:131] op_sel_hi:[1,0]
	v_exp_f32_e32 v138, v138
	v_mul_f32_e32 v139, 0xbfb8aa3b, v140
	v_exp_f32_e32 v139, v139
	v_mul_f32_e32 v140, 0xbfb8aa3b, v141
	v_exp_f32_e32 v140, v140
	v_add_f32_e32 v138, 1.0, v138
	v_rcp_f32_e32 v141, v138
	v_add_f32_e32 v138, 1.0, v139
	v_mul_f32_e32 v139, 0xbfb8aa3b, v142
	v_rcp_f32_e32 v144, v138
	v_add_f32_e32 v138, 1.0, v140
	v_exp_f32_e32 v139, v139
	v_mul_f32_e32 v140, 0xbfb8aa3b, v143
	v_exp_f32_e32 v133, v133
	v_exp_f32_e32 v137, v137
	v_exp_f32_e32 v140, v140
	v_rcp_f32_e32 v142, v138
	v_add_f32_e32 v138, 1.0, v139
	v_add_f32_e32 v131, 1.0, v131
	v_add_f32_e32 v133, 1.0, v133
	v_add_f32_e32 v137, 1.0, v137
	v_rcp_f32_e32 v143, v138
	v_add_f32_e32 v138, 1.0, v140
	v_rcp_f32_e32 v131, v131
	v_rcp_f32_e32 v133, v133
	v_rcp_f32_e32 v137, v137
	v_rcp_f32_e32 v145, v138
	v_lshl_add_u64 v[134:135], v[128:129], 0, s[8:9]
	s_mov_b32 s8, 0x2c5b0000
	v_add_co_u32_e32 v128, vcc, s8, v128
	v_cvt_pk_bf16_f32 v138, v131, v133
	v_cvt_pk_bf16_f32 v139, v137, v141
	v_cvt_pk_bf16_f32 v140, v144, v142
	v_cvt_pk_bf16_f32 v141, v143, v145
	v_addc_co_u32_e32 v129, vcc, 0, v129, vcc
	global_store_dwordx4 v[128:129], v[138:141], off
	v_pk_mul_f32 v[128:129], v[6:7], v[130:131] op_sel_hi:[1,0]
	s_nop 0
	v_mul_f32_e32 v128, 0xbfb8aa3b, v128
	v_exp_f32_e32 v128, v128
	v_mul_f32_e32 v129, 0xbfb8aa3b, v129
	v_pk_mul_f32 v[138:139], v[4:5], v[130:131] op_sel_hi:[1,0]
	v_exp_f32_e32 v129, v129
	v_pk_mul_f32 v[140:141], v[2:3], v[130:131] op_sel_hi:[1,0]
	v_mul_f32_e32 v131, 0xbfb8aa3b, v138
	v_exp_f32_e32 v133, v131
	v_mul_f32_e32 v131, 0xbfb8aa3b, v139
	v_exp_f32_e32 v137, v131
	v_pk_mul_f32 v[130:131], v[0:1], v[130:131] op_sel_hi:[1,0]
	v_add_f32_e32 v128, 1.0, v128
	v_rcp_f32_e32 v138, v128
	v_add_f32_e32 v128, 1.0, v129
	v_mul_f32_e32 v129, 0xbfb8aa3b, v130
	v_exp_f32_e32 v129, v129
	v_mul_f32_e32 v130, 0xbfb8aa3b, v131
	v_exp_f32_e32 v130, v130
	v_rcp_f32_e32 v131, v128
	v_add_f32_e32 v128, 1.0, v129
	v_mul_f32_e32 v129, 0xbfb8aa3b, v140
	v_rcp_f32_e32 v139, v128
	v_add_f32_e32 v128, 1.0, v130
	v_exp_f32_e32 v129, v129
	v_mul_f32_e32 v130, 0xbfb8aa3b, v141
	v_exp_f32_e32 v130, v130
	v_rcp_f32_e32 v140, v128
	v_add_f32_e32 v128, 1.0, v129
	v_add_f32_e32 v133, 1.0, v133
	v_add_f32_e32 v137, 1.0, v137
	v_rcp_f32_e32 v141, v128
	v_add_f32_e32 v128, 1.0, v130
	v_rcp_f32_e32 v133, v133
	v_rcp_f32_e32 v137, v137
	v_rcp_f32_e32 v142, v128
	v_cvt_pk_bf16_f32 v129, v138, v131
	v_cvt_pk_bf16_f32 v130, v139, v140
	v_cvt_pk_bf16_f32 v128, v133, v137
	v_cvt_pk_bf16_f32 v131, v141, v142
	global_store_dwordx4 v[134:135], v[128:131], off offset:256

; __device__ __forceinline__ unsigned cvt_pk_bf16(float lo, float hi) { f32x2_t v = {lo, hi}; bf16x2_t r = __builtin_convertvector(v, bf16x2_t); return __builtin_bit_cast(unsigned, r); }
; __device__ __forceinline__ float sigmoid_f(float x) { return __builtin_amdgcn_rcpf(1.f + __expf(-x)); }
; __device__ __forceinline__ f32x4 sigmoid4(f32x4 v) { return (f32x4){sigmoid_f(v[0]), sigmoid_f(v[1]), sigmoid_f(v[2]), sigmoid_f(v[3])}; }
; __device__ __forceinline__ f32x4 silu4(f32x4 v) { return v * sigmoid4(v); }
; __device__ __forceinline__ u32x4 pack8bf(f32x4 a, f32x4 b) {
;     u32x4 w; w.x = pg8::cvt_pk_bf16(a[0], a[1]); w.y = pg8::cvt_pk_bf16(a[2], a[3]); w.z = pg8::cvt_pk_bf16(b[0], b[1]); w.w = pg8::cvt_pk_bf16(b[2], b[3]); return w;
; }
;     template <int MODE, bool HEADMAJOR>
;     __device__ __forceinline__ void plain(const f32x4 (&acc)[2][2][4][2], const float (&rs)[2][4], bf16_t* base, int row0, int pl, int wc, int fq) const {
; #pragma unroll
;         for (int ai = 0; ai < 2; ++ai)
; #pragma unroll
;             for (int m = 0; m < 4; ++m) { const int row = row0 + ai * 128 + m * 16;
; #pragma unroll
;                 for (int bj = 0; bj < 2; ++bj) { f32x4 v0 = acc[ai][bj][m][0] * rs[ai][m], v1 = acc[ai][bj][m][1] * rs[ai][m];
;                     if (MODE == 1) { v0 = v0 * 0.08838834764831845f; v1 = v1 * 0.08838834764831845f; }
;                     if (MODE == 2) { v0 = silu4(v0); v1 = silu4(v1); }
;                     if (MODE == 3) { v0 = sigmoid4(v0); v1 = sigmoid4(v1); }
;                     bf16_t* ptr = HEADMAJOR ? base + ((size_t)(pl * 2 + bj) * S + row) * 128 + 32 * wc + 8 * fq
;                                             : base + (size_t)row * DM + pl * 256 + bj * 128 + 32 * wc + 8 * fq;
;                     *(u32x4*)ptr = pack8bf(v0, v1); }
;                 asm volatile("" ::: "memory"); }
.LBB0_85:
	s_andn2_b64 vcc, exec, s[8:9]
	s_cbranch_vccnz .LBB0_87
	s_waitcnt lgkmcnt(0)
	v_pk_mul_f32 v[138:139], v[124:125], v[186:187] op_sel_hi:[1,0]
	v_pk_mul_f32 v[134:135], v[126:127], v[186:187] op_sel_hi:[1,0]
	v_mul_f32_e32 v133, 0xbfb8aa3b, v138
	v_exp_f32_e32 v133, v133
	v_pk_mul_f32 v[142:143], v[120:121], v[186:187] op_sel_hi:[1,0]
	v_pk_mul_f32 v[140:141], v[122:123], v[186:187] op_sel_hi:[1,0]
	s_lshl_b32 s8, s25, 9
	v_add_f32_e32 v133, 1.0, v133
	v_rcp_f32_e32 v144, v133
	v_mul_f32_e32 v133, 0xbfb8aa3b, v139
	v_exp_f32_e32 v133, v133
	s_add_u32 s8, s6, s8
	s_addc_u32 s9, s7, 0
	s_lshl_b32 s22, s4, 1
	v_add_f32_e32 v133, 1.0, v133
	v_rcp_f32_e32 v145, v133
	v_mul_f32_e32 v133, 0xbfb8aa3b, v134
	v_exp_f32_e32 v133, v133
	s_add_u32 s8, s8, s22
	v_pk_mul_f32 v[138:139], v[138:139], v[144:145]
	v_lshlrev_b32_e32 v128, 3, v136
	v_add_f32_e32 v133, 1.0, v133
	v_rcp_f32_e32 v146, v133
	v_mul_f32_e32 v133, 0xbfb8aa3b, v135
	v_exp_f32_e32 v133, v133
	s_addc_u32 s9, s9, 0
	v_ashrrev_i32_e32 v129, 31, v128
	v_ashrrev_i32_e32 v183, 31, v182
	v_add_f32_e32 v133, 1.0, v133
	v_rcp_f32_e32 v147, v133
	v_mul_f32_e32 v133, 0xbfb8aa3b, v142
	v_exp_f32_e32 v133, v133
	v_lshl_add_u64 v[128:129], v[128:129], 1, s[8:9]
	v_pk_mul_f32 v[134:135], v[134:135], v[146:147]
	v_lshlrev_b64 v[130:131], 12, v[182:183]
	v_add_f32_e32 v133, 1.0, v133
	v_rcp_f32_e32 v144, v133
	v_mul_f32_e32 v133, 0xbfb8aa3b, v143
	v_exp_f32_e32 v133, v133
	v_lshl_add_u64 v[128:129], v[128:129], 0, v[130:131]
	s_mov_b64 s[8:9], 0x2a500000
	v_lshl_add_u64 v[130:131], v[128:129], 0, s[8:9]
	v_add_f32_e32 v133, 1.0, v133
	v_rcp_f32_e32 v145, v133
	v_mul_f32_e32 v133, 0xbfb8aa3b, v140
	v_exp_f32_e32 v133, v133
	s_mov_b32 s8, 0x2a500000
	v_cvt_pk_bf16_f32 v138, v138, v139
	v_cvt_pk_bf16_f32 v139, v134, v135
	v_add_f32_e32 v133, 1.0, v133
	v_rcp_f32_e32 v146, v133
	v_mul_f32_e32 v133, 0xbfb8aa3b, v141
	v_exp_f32_e32 v133, v133
	v_add_co_u32_e32 v134, vcc, s8, v128
	s_mov_b64 s[8:9], 0x2a510000
	v_add_f32_e32 v133, 1.0, v133
	v_rcp_f32_e32 v147, v133
	v_addc_co_u32_e32 v135, vcc, 0, v129, vcc
	v_pk_mul_f32 v[146:147], v[140:141], v[146:147]
	v_pk_mul_f32 v[140:141], v[142:143], v[144:145]
	v_pk_mul_f32 v[142:143], v[112:113], v[186:187] op_sel_hi:[1,0]
	v_cvt_pk_bf16_f32 v140, v140, v141
	v_cvt_pk_bf16_f32 v141, v146, v147
	global_store_dwordx4 v[134:135], v[138:141], off
	v_pk_mul_f32 v[134:135], v[118:119], v[186:187] op_sel_hi:[1,0]
	s_nop 0
	v_pk_mul_f32 v[138:139], v[116:117], v[186:187] op_sel_hi:[1,0]
	v_pk_mul_f32 v[140:141], v[114:115], v[186:187] op_sel_hi:[1,0]
	v_mul_f32_e32 v133, 0xbfb8aa3b, v138
	v_exp_f32_e32 v133, v133
	s_nop 0
	v_add_f32_e32 v133, 1.0, v133
	v_rcp_f32_e32 v144, v133
	v_mul_f32_e32 v133, 0xbfb8aa3b, v139
	v_exp_f32_e32 v133, v133
	s_nop 0
	v_add_f32_e32 v133, 1.0, v133
	v_rcp_f32_e32 v145, v133
	v_mul_f32_e32 v133, 0xbfb8aa3b, v134
	v_exp_f32_e32 v133, v133
	v_pk_mul_f32 v[138:139], v[138:139], v[144:145]
	s_nop 0
	v_cvt_pk_bf16_f32 v138, v138, v139
	v_add_f32_e32 v133, 1.0, v133
	v_rcp_f32_e32 v146, v133
	v_mul_f32_e32 v133, 0xbfb8aa3b, v135
	v_exp_f32_e32 v133, v133
	s_nop 0
	v_add_f32_e32 v133, 1.0, v133
	v_rcp_f32_e32 v147, v133
	v_mul_f32_e32 v133, 0xbfb8aa3b, v142
	v_exp_f32_e32 v133, v133
	v_pk_mul_f32 v[134:135], v[134:135], v[146:147]
	s_nop 0
	v_cvt_pk_bf16_f32 v139, v134, v135
	v_add_f32_e32 v133, 1.0, v133
	v_rcp_f32_e32 v144, v133
	v_mul_f32_e32 v133, 0xbfb8aa3b, v143
	v_exp_f32_e32 v133, v133
	v_mov_b32_e32 v134, v187
	v_add_f32_e32 v133, 1.0, v133
	v_rcp_f32_e32 v145, v133
	v_mul_f32_e32 v133, 0xbfb8aa3b, v140
	v_exp_f32_e32 v133, v133
	s_nop 0
	v_add_f32_e32 v133, 1.0, v133
	v_rcp_f32_e32 v146, v133
	v_mul_f32_e32 v133, 0xbfb8aa3b, v141
	v_exp_f32_e32 v133, v133
	s_nop 0
	v_add_f32_e32 v133, 1.0, v133
	v_rcp_f32_e32 v147, v133
	s_nop 0
	v_pk_mul_f32 v[146:147], v[140:141], v[146:147]
	v_pk_mul_f32 v[140:141], v[142:143], v[144:145]
	v_pk_mul_f32 v[144:145], v[104:105], v[134:135] op_sel_hi:[1,0]
	v_cvt_pk_bf16_f32 v140, v140, v141
	v_cvt_pk_bf16_f32 v141, v146, v147
	global_store_dwordx4 v[130:131], v[138:141], off offset:256
	v_pk_mul_f32 v[142:143], v[106:107], v[134:135] op_sel_hi:[1,0]
	v_lshl_add_u64 v[130:131], v[128:129], 0, s[8:9]
	v_pk_mul_f32 v[140:141], v[108:109], v[134:135] op_sel_hi:[1,0]
	v_pk_mul_f32 v[138:139], v[110:111], v[134:135] op_sel_hi:[1,0]
	v_mul_f32_e32 v133, 0xbfb8aa3b, v140
	v_exp_f32_e32 v133, v133
	s_mov_b32 s8, 0x2a510000
	v_add_f32_e32 v133, 1.0, v133
	v_rcp_f32_e32 v146, v133
	v_mul_f32_e32 v133, 0xbfb8aa3b, v141
	v_exp_f32_e32 v133, v133
	s_nop 0
	v_add_f32_e32 v133, 1.0, v133
	v_rcp_f32_e32 v147, v133
	v_mul_f32_e32 v133, 0xbfb8aa3b, v138
	v_exp_f32_e32 v133, v133
	s_nop 0
	v_add_f32_e32 v133, 1.0, v133
	v_rcp_f32_e32 v148, v133
	v_mul_f32_e32 v133, 0xbfb8aa3b, v139
	v_exp_f32_e32 v133, v133
	s_nop 0
	v_add_f32_e32 v133, 1.0, v133
	v_rcp_f32_e32 v149, v133
	v_mul_f32_e32 v133, 0xbfb8aa3b, v144
	v_exp_f32_e32 v133, v133
	v_pk_mul_f32 v[148:149], v[138:139], v[148:149]
	v_pk_mul_f32 v[138:139], v[140:141], v[146:147]
	v_add_f32_e32 v133, 1.0, v133
	v_rcp_f32_e32 v140, v133
	v_mul_f32_e32 v133, 0xbfb8aa3b, v145
	v_exp_f32_e32 v133, v133
	v_cvt_pk_bf16_f32 v138, v138, v139
	v_cvt_pk_bf16_f32 v139, v148, v149
	v_add_f32_e32 v133, 1.0, v133
	v_rcp_f32_e32 v141, v133
	v_mul_f32_e32 v133, 0xbfb8aa3b, v142
	v_exp_f32_e32 v133, v133
	v_pk_mul_f32 v[140:141], v[144:145], v[140:141]
	s_nop 0
	v_cvt_pk_bf16_f32 v140, v140, v141
	v_add_f32_e32 v133, 1.0, v133
	v_rcp_f32_e32 v146, v133
	v_mul_f32_e32 v133, 0xbfb8aa3b, v143
	v_exp_f32_e32 v133, v133
	s_nop 0
	v_add_f32_e32 v133, 1.0, v133
	v_rcp_f32_e32 v147, v133
; __device__ __forceinline__ unsigned cvt_pk_bf16(float lo, float hi) { f32x2_t v = {lo, hi}; bf16x2_t r = __builtin_convertvector(v, bf16x2_t); return __builtin_bit_cast(unsigned, r); }
; __device__ __forceinline__ float sigmoid_f(float x) { return __builtin_amdgcn_rcpf(1.f + __expf(-x)); }
; __device__ __forceinline__ f32x4 sigmoid4(f32x4 v) { return (f32x4){sigmoid_f(v[0]), sigmoid_f(v[1]), sigmoid_f(v[2]), sigmoid_f(v[3])}; }
; __device__ __forceinline__ f32x4 silu4(f32x4 v) { return v * sigmoid4(v); }
; __device__ __forceinline__ u32x4 pack8bf(f32x4 a, f32x4 b) {
;     u32x4 w; w.x = pg8::cvt_pk_bf16(a[0], a[1]); w.y = pg8::cvt_pk_bf16(a[2], a[3]); w.z = pg8::cvt_pk_bf16(b[0], b[1]); w.w = pg8::cvt_pk_bf16(b[2], b[3]); return w;
; }
;     template <int MODE, bool HEADMAJOR>
;     __device__ __forceinline__ void plain(const f32x4 (&acc)[2][2][4][2], const float (&rs)[2][4], bf16_t* base, int row0, int pl, int wc, int fq) const {
; #pragma unroll
;         for (int ai = 0; ai < 2; ++ai)
; #pragma unroll
;             for (int m = 0; m < 4; ++m) { const int row = row0 + ai * 128 + m * 16;
; #pragma unroll
;                 for (int bj = 0; bj < 2; ++bj) { f32x4 v0 = acc[ai][bj][m][0] * rs[ai][m], v1 = acc[ai][bj][m][1] * rs[ai][m];
;                     if (MODE == 1) { v0 = v0 * 0.08838834764831845f; v1 = v1 * 0.08838834764831845f; }
;                     if (MODE == 2) { v0 = silu4(v0); v1 = silu4(v1); }
;                     if (MODE == 3) { v0 = sigmoid4(v0); v1 = sigmoid4(v1); }
;                     bf16_t* ptr = HEADMAJOR ? base + ((size_t)(pl * 2 + bj) * S + row) * 128 + 32 * wc + 8 * fq
;                                             : base + (size_t)row * DM + pl * 256 + bj * 128 + 32 * wc + 8 * fq;
;                     *(u32x4*)ptr = pack8bf(v0, v1); }
;                 asm volatile("" ::: "memory"); }
	s_nop 0
	v_pk_mul_f32 v[142:143], v[142:143], v[146:147]
	s_nop 0
	v_cvt_pk_bf16_f32 v141, v142, v143
	v_add_co_u32_e32 v142, vcc, s8, v128
	s_mov_b64 s[8:9], 0x2a520000
	s_nop 0
	v_addc_co_u32_e32 v143, vcc, 0, v129, vcc
	global_store_dwordx4 v[142:143], v[138:141], off
	v_pk_mul_f32 v[142:143], v[98:99], v[134:135] op_sel_hi:[1,0]
	s_nop 0
	v_pk_mul_f32 v[140:141], v[100:101], v[134:135] op_sel_hi:[1,0]
	v_pk_mul_f32 v[138:139], v[102:103], v[134:135] op_sel_hi:[1,0]
	v_mul_f32_e32 v133, 0xbfb8aa3b, v140
	v_exp_f32_e32 v133, v133
	v_pk_mul_f32 v[134:135], v[96:97], v[134:135] op_sel_hi:[1,0]
	v_add_f32_e32 v133, 1.0, v133
	v_rcp_f32_e32 v144, v133
	v_mul_f32_e32 v133, 0xbfb8aa3b, v141
	v_exp_f32_e32 v133, v133
	s_nop 0
	v_add_f32_e32 v133, 1.0, v133
	v_rcp_f32_e32 v145, v133
	v_mul_f32_e32 v133, 0xbfb8aa3b, v138
	v_exp_f32_e32 v133, v133
	s_nop 0
	v_add_f32_e32 v133, 1.0, v133
	v_rcp_f32_e32 v146, v133
	v_mul_f32_e32 v133, 0xbfb8aa3b, v139
	v_exp_f32_e32 v133, v133
	s_nop 0
	v_add_f32_e32 v133, 1.0, v133
	v_rcp_f32_e32 v147, v133
	v_mul_f32_e32 v133, 0xbfb8aa3b, v134
	v_exp_f32_e32 v133, v133
	v_pk_mul_f32 v[146:147], v[138:139], v[146:147]
	v_pk_mul_f32 v[138:139], v[140:141], v[144:145]
	v_add_f32_e32 v133, 1.0, v133
	v_rcp_f32_e32 v140, v133
	v_mul_f32_e32 v133, 0xbfb8aa3b, v135
	v_exp_f32_e32 v133, v133
	v_cvt_pk_bf16_f32 v138, v138, v139
	v_cvt_pk_bf16_f32 v139, v146, v147
	v_add_f32_e32 v133, 1.0, v133
	v_rcp_f32_e32 v141, v133
	v_mul_f32_e32 v133, 0xbfb8aa3b, v142
	v_exp_f32_e32 v133, v133
	v_pk_mul_f32 v[134:135], v[134:135], v[140:141]
	s_nop 0
	v_cvt_pk_bf16_f32 v140, v134, v135
	v_add_f32_e32 v133, 1.0, v133
	v_rcp_f32_e32 v144, v133
	v_mul_f32_e32 v133, 0xbfb8aa3b, v143
	v_exp_f32_e32 v133, v133
	v_pk_mul_f32 v[134:135], v[94:95], v[184:185] op_sel_hi:[1,0]
	v_add_f32_e32 v133, 1.0, v133
	v_rcp_f32_e32 v145, v133
	s_nop 0
	v_pk_mul_f32 v[142:143], v[142:143], v[144:145]
	s_nop 0
	v_cvt_pk_bf16_f32 v141, v142, v143
	global_store_dwordx4 v[130:131], v[138:141], off offset:256
	v_pk_mul_f32 v[142:143], v[88:89], v[184:185] op_sel_hi:[1,0]
	v_lshl_add_u64 v[130:131], v[128:129], 0, s[8:9]
	v_pk_mul_f32 v[138:139], v[92:93], v[184:185] op_sel_hi:[1,0]
	v_pk_mul_f32 v[140:141], v[90:91], v[184:185] op_sel_hi:[1,0]
	v_mul_f32_e32 v133, 0xbfb8aa3b, v138
	v_exp_f32_e32 v133, v133
	s_mov_b32 s8, 0x2a520000
	v_add_f32_e32 v133, 1.0, v133
	v_rcp_f32_e32 v144, v133
	v_mul_f32_e32 v133, 0xbfb8aa3b, v139
	v_exp_f32_e32 v133, v133
	s_nop 0
	v_add_f32_e32 v133, 1.0, v133
	v_rcp_f32_e32 v145, v133
	v_mul_f32_e32 v133, 0xbfb8aa3b, v134
	v_exp_f32_e32 v133, v133
	v_pk_mul_f32 v[138:139], v[138:139], v[144:145]
	s_nop 0
	v_cvt_pk_bf16_f32 v138, v138, v139
	v_add_f32_e32 v133, 1.0, v133
	v_rcp_f32_e32 v146, v133
	v_mul_f32_e32 v133, 0xbfb8aa3b, v135
	v_exp_f32_e32 v133, v133
	s_nop 0
	v_add_f32_e32 v133, 1.0, v133
	v_rcp_f32_e32 v147, v133
	v_mul_f32_e32 v133, 0xbfb8aa3b, v142
	v_exp_f32_e32 v133, v133
	v_pk_mul_f32 v[134:135], v[134:135], v[146:147]
	s_nop 0
	v_cvt_pk_bf16_f32 v139, v134, v135
	v_add_f32_e32 v133, 1.0, v133
	v_rcp_f32_e32 v144, v133
	v_mul_f32_e32 v133, 0xbfb8aa3b, v143
	v_exp_f32_e32 v133, v133
	v_add_co_u32_e32 v134, vcc, s8, v128
	s_mov_b64 s[8:9], 0x2a530000
	v_add_f32_e32 v133, 1.0, v133
	v_rcp_f32_e32 v145, v133
	v_mul_f32_e32 v133, 0xbfb8aa3b, v140
	v_exp_f32_e32 v133, v133
	v_addc_co_u32_e32 v135, vcc, 0, v129, vcc
	v_add_f32_e32 v133, 1.0, v133
	v_rcp_f32_e32 v146, v133
	v_mul_f32_e32 v133, 0xbfb8aa3b, v141
	v_exp_f32_e32 v133, v133
	s_nop 0
	v_add_f32_e32 v133, 1.0, v133
	v_rcp_f32_e32 v147, v133
	s_nop 0
	v_pk_mul_f32 v[146:147], v[140:141], v[146:147]
	v_pk_mul_f32 v[140:141], v[142:143], v[144:145]
	v_pk_mul_f32 v[142:143], v[80:81], v[184:185] op_sel_hi:[1,0]
	v_cvt_pk_bf16_f32 v140, v140, v141
	v_cvt_pk_bf16_f32 v141, v146, v147
	global_store_dwordx4 v[134:135], v[138:141], off
	v_pk_mul_f32 v[134:135], v[86:87], v[184:185] op_sel_hi:[1,0]
	s_nop 0
	v_pk_mul_f32 v[138:139], v[84:85], v[184:185] op_sel_hi:[1,0]
	v_pk_mul_f32 v[140:141], v[82:83], v[184:185] op_sel_hi:[1,0]
	v_mul_f32_e32 v133, 0xbfb8aa3b, v138
	v_exp_f32_e32 v133, v133
	s_nop 0
	v_add_f32_e32 v133, 1.0, v133
	v_rcp_f32_e32 v144, v133
	v_mul_f32_e32 v133, 0xbfb8aa3b, v139
	v_exp_f32_e32 v133, v133
	s_nop 0
	v_add_f32_e32 v133, 1.0, v133
	v_rcp_f32_e32 v145, v133
	v_mul_f32_e32 v133, 0xbfb8aa3b, v134
	v_exp_f32_e32 v133, v133
	v_pk_mul_f32 v[138:139], v[138:139], v[144:145]
	s_nop 0
	v_cvt_pk_bf16_f32 v138, v138, v139
	v_add_f32_e32 v133, 1.0, v133
	v_rcp_f32_e32 v146, v133
	v_mul_f32_e32 v133, 0xbfb8aa3b, v135
	v_exp_f32_e32 v133, v133
	s_nop 0
	v_add_f32_e32 v133, 1.0, v133
	v_rcp_f32_e32 v147, v133
	v_mul_f32_e32 v133, 0xbfb8aa3b, v142
	v_exp_f32_e32 v133, v133
	v_pk_mul_f32 v[134:135], v[134:135], v[146:147]
	s_nop 0
	v_cvt_pk_bf16_f32 v139, v134, v135
	v_add_f32_e32 v133, 1.0, v133
	v_rcp_f32_e32 v144, v133
	v_mul_f32_e32 v133, 0xbfb8aa3b, v143
	v_exp_f32_e32 v133, v133
	v_mov_b32_e32 v134, v185
	v_add_f32_e32 v133, 1.0, v133
	v_rcp_f32_e32 v145, v133
	v_mul_f32_e32 v133, 0xbfb8aa3b, v140
	v_exp_f32_e32 v133, v133
	s_nop 0
	v_add_f32_e32 v133, 1.0, v133
	v_rcp_f32_e32 v146, v133
	v_mul_f32_e32 v133, 0xbfb8aa3b, v141
	v_exp_f32_e32 v133, v133
	s_nop 0
	v_add_f32_e32 v133, 1.0, v133
	v_rcp_f32_e32 v147, v133
	s_nop 0
	v_pk_mul_f32 v[146:147], v[140:141], v[146:147]
	v_pk_mul_f32 v[140:141], v[142:143], v[144:145]
	v_pk_mul_f32 v[144:145], v[72:73], v[134:135] op_sel_hi:[1,0]
	v_cvt_pk_bf16_f32 v140, v140, v141
	v_cvt_pk_bf16_f32 v141, v146, v147
	global_store_dwordx4 v[130:131], v[138:141], off offset:256
	v_pk_mul_f32 v[142:143], v[74:75], v[134:135] op_sel_hi:[1,0]
; __device__ __forceinline__ float sigmoid_f(float x) { return __builtin_amdgcn_rcpf(1.f + __expf(-x)); }
; __device__ __forceinline__ f32x4 sigmoid4(f32x4 v) { return (f32x4){sigmoid_f(v[0]), sigmoid_f(v[1]), sigmoid_f(v[2]), sigmoid_f(v[3])}; }
; __device__ __forceinline__ f32x4 silu4(f32x4 v) { return v * sigmoid4(v); }
;     template <int MODE, bool HEADMAJOR>
;     __device__ __forceinline__ void plain(const f32x4 (&acc)[2][2][4][2], const float (&rs)[2][4], bf16_t* base, int row0, int pl, int wc, int fq) const {
; #pragma unroll
;         for (int ai = 0; ai < 2; ++ai)
; #pragma unroll
;             for (int m = 0; m < 4; ++m) { const int row = row0 + ai * 128 + m * 16;
; #pragma unroll
;                 for (int bj = 0; bj < 2; ++bj) { f32x4 v0 = acc[ai][bj][m][0] * rs[ai][m], v1 = acc[ai][bj][m][1] * rs[ai][m];
;                     if (MODE == 1) { v0 = v0 * 0.08838834764831845f; v1 = v1 * 0.08838834764831845f; }
;                     if (MODE == 2) { v0 = silu4(v0); v1 = silu4(v1); }
;                     if (MODE == 3) { v0 = sigmoid4(v0); v1 = sigmoid4(v1); }
;                     bf16_t* ptr = HEADMAJOR ? base + ((size_t)(pl * 2 + bj) * S + row) * 128 + 32 * wc + 8 * fq
;                                             : base + (size_t)row * DM + pl * 256 + bj * 128 + 32 * wc + 8 * fq;
;                     *(u32x4*)ptr = pack8bf(v0, v1); }
;                 asm volatile("" ::: "memory"); }
	v_lshl_add_u64 v[130:131], v[128:129], 0, s[8:9]
	v_pk_mul_f32 v[140:141], v[76:77], v[134:135] op_sel_hi:[1,0]
	v_pk_mul_f32 v[138:139], v[78:79], v[134:135] op_sel_hi:[1,0]
	v_mul_f32_e32 v133, 0xbfb8aa3b, v140
	v_exp_f32_e32 v133, v133
	s_mov_b32 s8, 0x2a530000
	v_add_f32_e32 v133, 1.0, v133
	v_rcp_f32_e32 v146, v133
	v_mul_f32_e32 v133, 0xbfb8aa3b, v141
	v_exp_f32_e32 v133, v133
	s_nop 0
	v_add_f32_e32 v133, 1.0, v133
	v_rcp_f32_e32 v147, v133
	v_mul_f32_e32 v133, 0xbfb8aa3b, v138
	v_exp_f32_e32 v133, v133
	s_nop 0
	v_add_f32_e32 v133, 1.0, v133
	v_rcp_f32_e32 v148, v133
	v_mul_f32_e32 v133, 0xbfb8aa3b, v139
	v_exp_f32_e32 v133, v133
	s_nop 0
	v_add_f32_e32 v133, 1.0, v133
	v_rcp_f32_e32 v149, v133
	v_mul_f32_e32 v133, 0xbfb8aa3b, v144
	v_exp_f32_e32 v133, v133
	v_pk_mul_f32 v[148:149], v[138:139], v[148:149]
	v_pk_mul_f32 v[138:139], v[140:141], v[146:147]
	v_add_f32_e32 v133, 1.0, v133
	v_rcp_f32_e32 v140, v133
	v_mul_f32_e32 v133, 0xbfb8aa3b, v145
	v_exp_f32_e32 v133, v133
	v_cvt_pk_bf16_f32 v138, v138, v139
	v_cvt_pk_bf16_f32 v139, v148, v149
	v_add_f32_e32 v133, 1.0, v133
	v_rcp_f32_e32 v141, v133
	v_mul_f32_e32 v133, 0xbfb8aa3b, v142
	v_exp_f32_e32 v133, v133
	v_pk_mul_f32 v[140:141], v[144:145], v[140:141]
	s_nop 0
	v_cvt_pk_bf16_f32 v140, v140, v141
	v_add_f32_e32 v133, 1.0, v133
	v_rcp_f32_e32 v146, v133
	v_mul_f32_e32 v133, 0xbfb8aa3b, v143
	v_exp_f32_e32 v133, v133
	s_nop 0
	v_add_f32_e32 v133, 1.0, v133
	v_rcp_f32_e32 v147, v133
	s_nop 0
	v_pk_mul_f32 v[142:143], v[142:143], v[146:147]
	s_nop 0
	v_cvt_pk_bf16_f32 v141, v142, v143
	v_add_co_u32_e32 v142, vcc, s8, v128
	s_mov_b64 s[8:9], 0x2a580000
	s_nop 0
	v_addc_co_u32_e32 v143, vcc, 0, v129, vcc
	global_store_dwordx4 v[142:143], v[138:141], off
	v_pk_mul_f32 v[142:143], v[66:67], v[134:135] op_sel_hi:[1,0]
	s_nop 0
	v_pk_mul_f32 v[140:141], v[68:69], v[134:135] op_sel_hi:[1,0]
	v_pk_mul_f32 v[138:139], v[70:71], v[134:135] op_sel_hi:[1,0]
	v_mul_f32_e32 v133, 0xbfb8aa3b, v140
	v_exp_f32_e32 v133, v133
	v_pk_mul_f32 v[134:135], v[64:65], v[134:135] op_sel_hi:[1,0]
	v_add_f32_e32 v133, 1.0, v133
	v_rcp_f32_e32 v144, v133
	v_mul_f32_e32 v133, 0xbfb8aa3b, v141
	v_exp_f32_e32 v133, v133
	s_nop 0
	v_add_f32_e32 v133, 1.0, v133
	v_rcp_f32_e32 v145, v133
	v_mul_f32_e32 v133, 0xbfb8aa3b, v138
	v_exp_f32_e32 v133, v133
	s_nop 0
	v_add_f32_e32 v133, 1.0, v133
	v_rcp_f32_e32 v146, v133
	v_mul_f32_e32 v133, 0xbfb8aa3b, v139
	v_exp_f32_e32 v133, v133
	s_nop 0
	v_add_f32_e32 v133, 1.0, v133
	v_rcp_f32_e32 v147, v133
	v_mul_f32_e32 v133, 0xbfb8aa3b, v134
	v_exp_f32_e32 v133, v133
	v_pk_mul_f32 v[146:147], v[138:139], v[146:147]
	v_pk_mul_f32 v[138:139], v[140:141], v[144:145]
	v_add_f32_e32 v133, 1.0, v133
	v_rcp_f32_e32 v140, v133
	v_mul_f32_e32 v133, 0xbfb8aa3b, v135
	v_exp_f32_e32 v133, v133
	v_cvt_pk_bf16_f32 v138, v138, v139
	v_cvt_pk_bf16_f32 v139, v146, v147
	v_add_f32_e32 v133, 1.0, v133
	v_rcp_f32_e32 v141, v133
	v_mul_f32_e32 v133, 0xbfb8aa3b, v142
	v_exp_f32_e32 v133, v133
	v_pk_mul_f32 v[134:135], v[134:135], v[140:141]
	s_nop 0
	v_cvt_pk_bf16_f32 v140, v134, v135
	v_add_f32_e32 v133, 1.0, v133
	v_rcp_f32_e32 v144, v133
	v_mul_f32_e32 v133, 0xbfb8aa3b, v143
	v_exp_f32_e32 v133, v133
	v_pk_mul_f32 v[134:135], v[62:63], v[180:181] op_sel_hi:[1,0]
	v_add_f32_e32 v133, 1.0, v133
	v_rcp_f32_e32 v145, v133
	s_nop 0
	v_pk_mul_f32 v[142:143], v[142:143], v[144:145]
	s_nop 0
	v_cvt_pk_bf16_f32 v141, v142, v143
	global_store_dwordx4 v[130:131], v[138:141], off offset:256
	v_pk_mul_f32 v[142:143], v[56:57], v[180:181] op_sel_hi:[1,0]
	v_lshl_add_u64 v[130:131], v[128:129], 0, s[8:9]
	v_pk_mul_f32 v[138:139], v[60:61], v[180:181] op_sel_hi:[1,0]
	v_pk_mul_f32 v[140:141], v[58:59], v[180:181] op_sel_hi:[1,0]
	v_mul_f32_e32 v133, 0xbfb8aa3b, v138
	v_exp_f32_e32 v133, v133
	s_mov_b32 s8, 0x2a580000
	v_add_f32_e32 v133, 1.0, v133
	v_rcp_f32_e32 v144, v133
	v_mul_f32_e32 v133, 0xbfb8aa3b, v139
	v_exp_f32_e32 v133, v133
	s_nop 0
	v_add_f32_e32 v133, 1.0, v133
	v_rcp_f32_e32 v145, v133
	v_mul_f32_e32 v133, 0xbfb8aa3b, v134
	v_exp_f32_e32 v133, v133
	v_pk_mul_f32 v[138:139], v[138:139], v[144:145]
	s_nop 0
	v_cvt_pk_bf16_f32 v138, v138, v139
	v_add_f32_e32 v133, 1.0, v133
	v_rcp_f32_e32 v146, v133
	v_mul_f32_e32 v133, 0xbfb8aa3b, v135
	v_exp_f32_e32 v133, v133
	s_nop 0
	v_add_f32_e32 v133, 1.0, v133
	v_rcp_f32_e32 v147, v133
	v_mul_f32_e32 v133, 0xbfb8aa3b, v142
	v_exp_f32_e32 v133, v133
	v_pk_mul_f32 v[134:135], v[134:135], v[146:147]
	s_nop 0
	v_cvt_pk_bf16_f32 v139, v134, v135
	v_add_f32_e32 v133, 1.0, v133
	v_rcp_f32_e32 v144, v133
	v_mul_f32_e32 v133, 0xbfb8aa3b, v143
	v_exp_f32_e32 v133, v133
	v_add_co_u32_e32 v134, vcc, s8, v128
	s_mov_b64 s[8:9], 0x2a590000
	v_add_f32_e32 v133, 1.0, v133
	v_rcp_f32_e32 v145, v133
	v_mul_f32_e32 v133, 0xbfb8aa3b, v140
	v_exp_f32_e32 v133, v133
	v_addc_co_u32_e32 v135, vcc, 0, v129, vcc
	v_add_f32_e32 v133, 1.0, v133
	v_rcp_f32_e32 v146, v133
	v_mul_f32_e32 v133, 0xbfb8aa3b, v141
	v_exp_f32_e32 v133, v133
	s_nop 0
	v_add_f32_e32 v133, 1.0, v133
	v_rcp_f32_e32 v147, v133
	s_nop 0
	v_pk_mul_f32 v[146:147], v[140:141], v[146:147]
	v_pk_mul_f32 v[140:141], v[142:143], v[144:145]
	v_pk_mul_f32 v[142:143], v[48:49], v[180:181] op_sel_hi:[1,0]
	v_cvt_pk_bf16_f32 v140, v140, v141
	v_cvt_pk_bf16_f32 v141, v146, v147
	global_store_dwordx4 v[134:135], v[138:141], off
	v_pk_mul_f32 v[134:135], v[54:55], v[180:181] op_sel_hi:[1,0]
	s_nop 0
	v_pk_mul_f32 v[138:139], v[52:53], v[180:181] op_sel_hi:[1,0]
	v_pk_mul_f32 v[140:141], v[50:51], v[180:181] op_sel_hi:[1,0]
	v_mul_f32_e32 v133, 0xbfb8aa3b, v138
	v_exp_f32_e32 v133, v133
	s_nop 0
	v_add_f32_e32 v133, 1.0, v133
; __device__ __forceinline__ float sigmoid_f(float x) { return __builtin_amdgcn_rcpf(1.f + __expf(-x)); }
; __device__ __forceinline__ f32x4 sigmoid4(f32x4 v) { return (f32x4){sigmoid_f(v[0]), sigmoid_f(v[1]), sigmoid_f(v[2]), sigmoid_f(v[3])}; }
; __device__ __forceinline__ f32x4 silu4(f32x4 v) { return v * sigmoid4(v); }
;     template <int MODE, bool HEADMAJOR>
;     __device__ __forceinline__ void plain(const f32x4 (&acc)[2][2][4][2], const float (&rs)[2][4], bf16_t* base, int row0, int pl, int wc, int fq) const {
; #pragma unroll
;         for (int ai = 0; ai < 2; ++ai)
; #pragma unroll
;             for (int m = 0; m < 4; ++m) { const int row = row0 + ai * 128 + m * 16;
; #pragma unroll
;                 for (int bj = 0; bj < 2; ++bj) { f32x4 v0 = acc[ai][bj][m][0] * rs[ai][m], v1 = acc[ai][bj][m][1] * rs[ai][m];
;                     if (MODE == 1) { v0 = v0 * 0.08838834764831845f; v1 = v1 * 0.08838834764831845f; }
;                     if (MODE == 2) { v0 = silu4(v0); v1 = silu4(v1); }
;                     if (MODE == 3) { v0 = sigmoid4(v0); v1 = sigmoid4(v1); }
;                     bf16_t* ptr = HEADMAJOR ? base + ((size_t)(pl * 2 + bj) * S + row) * 128 + 32 * wc + 8 * fq
;                                             : base + (size_t)row * DM + pl * 256 + bj * 128 + 32 * wc + 8 * fq;
;                     *(u32x4*)ptr = pack8bf(v0, v1); }
;                 asm volatile("" ::: "memory"); }
	v_rcp_f32_e32 v144, v133
	v_mul_f32_e32 v133, 0xbfb8aa3b, v139
	v_exp_f32_e32 v133, v133
	s_nop 0
	v_add_f32_e32 v133, 1.0, v133
	v_rcp_f32_e32 v145, v133
	v_mul_f32_e32 v133, 0xbfb8aa3b, v134
	v_exp_f32_e32 v133, v133
	v_pk_mul_f32 v[138:139], v[138:139], v[144:145]
	s_nop 0
	v_cvt_pk_bf16_f32 v138, v138, v139
	v_add_f32_e32 v133, 1.0, v133
	v_rcp_f32_e32 v146, v133
	v_mul_f32_e32 v133, 0xbfb8aa3b, v135
	v_exp_f32_e32 v133, v133
	s_nop 0
	v_add_f32_e32 v133, 1.0, v133
	v_rcp_f32_e32 v147, v133
	v_mul_f32_e32 v133, 0xbfb8aa3b, v142
	v_exp_f32_e32 v133, v133
	v_pk_mul_f32 v[134:135], v[134:135], v[146:147]
	s_nop 0
	v_cvt_pk_bf16_f32 v139, v134, v135
	v_add_f32_e32 v133, 1.0, v133
	v_rcp_f32_e32 v144, v133
	v_mul_f32_e32 v133, 0xbfb8aa3b, v143
	v_exp_f32_e32 v133, v133
	v_mov_b32_e32 v134, v181
	v_add_f32_e32 v133, 1.0, v133
	v_rcp_f32_e32 v145, v133
	v_mul_f32_e32 v133, 0xbfb8aa3b, v140
	v_exp_f32_e32 v133, v133
	s_nop 0
	v_add_f32_e32 v133, 1.0, v133
	v_rcp_f32_e32 v146, v133
	v_mul_f32_e32 v133, 0xbfb8aa3b, v141
	v_exp_f32_e32 v133, v133
	s_nop 0
	v_add_f32_e32 v133, 1.0, v133
	v_rcp_f32_e32 v147, v133
	s_nop 0
	v_pk_mul_f32 v[146:147], v[140:141], v[146:147]
	v_pk_mul_f32 v[140:141], v[142:143], v[144:145]
	v_pk_mul_f32 v[144:145], v[40:41], v[134:135] op_sel_hi:[1,0]
	v_cvt_pk_bf16_f32 v140, v140, v141
	v_cvt_pk_bf16_f32 v141, v146, v147
	global_store_dwordx4 v[130:131], v[138:141], off offset:256
	v_pk_mul_f32 v[142:143], v[42:43], v[134:135] op_sel_hi:[1,0]
	v_lshl_add_u64 v[130:131], v[128:129], 0, s[8:9]
	v_pk_mul_f32 v[140:141], v[44:45], v[134:135] op_sel_hi:[1,0]
	v_pk_mul_f32 v[138:139], v[46:47], v[134:135] op_sel_hi:[1,0]
	v_mul_f32_e32 v133, 0xbfb8aa3b, v140
	v_exp_f32_e32 v133, v133
	s_mov_b32 s8, 0x2a590000
	v_add_f32_e32 v133, 1.0, v133
	v_rcp_f32_e32 v146, v133
	v_mul_f32_e32 v133, 0xbfb8aa3b, v141
	v_exp_f32_e32 v133, v133
	s_nop 0
	v_add_f32_e32 v133, 1.0, v133
	v_rcp_f32_e32 v147, v133
	v_mul_f32_e32 v133, 0xbfb8aa3b, v138
	v_exp_f32_e32 v133, v133
	s_nop 0
	v_add_f32_e32 v133, 1.0, v133
	v_rcp_f32_e32 v148, v133
	v_mul_f32_e32 v133, 0xbfb8aa3b, v139
	v_exp_f32_e32 v133, v133
	s_nop 0
	v_add_f32_e32 v133, 1.0, v133
	v_rcp_f32_e32 v149, v133
	v_mul_f32_e32 v133, 0xbfb8aa3b, v144
	v_exp_f32_e32 v133, v133
	v_pk_mul_f32 v[148:149], v[138:139], v[148:149]
	v_pk_mul_f32 v[138:139], v[140:141], v[146:147]
	v_add_f32_e32 v133, 1.0, v133
	v_rcp_f32_e32 v140, v133
	v_mul_f32_e32 v133, 0xbfb8aa3b, v145
	v_exp_f32_e32 v133, v133
	v_cvt_pk_bf16_f32 v138, v138, v139
	v_cvt_pk_bf16_f32 v139, v148, v149
	v_add_f32_e32 v133, 1.0, v133
	v_rcp_f32_e32 v141, v133
	v_mul_f32_e32 v133, 0xbfb8aa3b, v142
	v_exp_f32_e32 v133, v133
	v_pk_mul_f32 v[140:141], v[144:145], v[140:141]
	s_nop 0
	v_cvt_pk_bf16_f32 v140, v140, v141
	v_add_f32_e32 v133, 1.0, v133
	v_rcp_f32_e32 v146, v133
	v_mul_f32_e32 v133, 0xbfb8aa3b, v143
	v_exp_f32_e32 v133, v133
	s_nop 0
	v_add_f32_e32 v133, 1.0, v133
	v_rcp_f32_e32 v147, v133
	s_nop 0
	v_pk_mul_f32 v[142:143], v[142:143], v[146:147]
	s_nop 0
	v_cvt_pk_bf16_f32 v141, v142, v143
	v_add_co_u32_e32 v142, vcc, s8, v128
	s_mov_b64 s[8:9], 0x2a5a0000
	s_nop 0
	v_addc_co_u32_e32 v143, vcc, 0, v129, vcc
	global_store_dwordx4 v[142:143], v[138:141], off
	v_pk_mul_f32 v[142:143], v[34:35], v[134:135] op_sel_hi:[1,0]
	s_nop 0
	v_pk_mul_f32 v[140:141], v[36:37], v[134:135] op_sel_hi:[1,0]
	v_pk_mul_f32 v[138:139], v[38:39], v[134:135] op_sel_hi:[1,0]
	v_mul_f32_e32 v133, 0xbfb8aa3b, v140
	v_exp_f32_e32 v133, v133
	v_pk_mul_f32 v[134:135], v[32:33], v[134:135] op_sel_hi:[1,0]
	v_add_f32_e32 v133, 1.0, v133
	v_rcp_f32_e32 v144, v133
	v_mul_f32_e32 v133, 0xbfb8aa3b, v141
	v_exp_f32_e32 v133, v133
	s_nop 0
	v_add_f32_e32 v133, 1.0, v133
	v_rcp_f32_e32 v145, v133
	v_mul_f32_e32 v133, 0xbfb8aa3b, v138
	v_exp_f32_e32 v133, v133
	s_nop 0
	v_add_f32_e32 v133, 1.0, v133
	v_rcp_f32_e32 v146, v133
	v_mul_f32_e32 v133, 0xbfb8aa3b, v139
	v_exp_f32_e32 v133, v133
	s_nop 0
	v_add_f32_e32 v133, 1.0, v133
	v_rcp_f32_e32 v147, v133
	v_mul_f32_e32 v133, 0xbfb8aa3b, v134
	v_exp_f32_e32 v133, v133
	v_pk_mul_f32 v[146:147], v[138:139], v[146:147]
	v_pk_mul_f32 v[138:139], v[140:141], v[144:145]
	v_add_f32_e32 v133, 1.0, v133
	v_rcp_f32_e32 v140, v133
	v_mul_f32_e32 v133, 0xbfb8aa3b, v135
	v_exp_f32_e32 v133, v133
	v_cvt_pk_bf16_f32 v138, v138, v139
	v_cvt_pk_bf16_f32 v139, v146, v147
	v_add_f32_e32 v133, 1.0, v133
	v_rcp_f32_e32 v141, v133
	v_mul_f32_e32 v133, 0xbfb8aa3b, v142
	v_exp_f32_e32 v133, v133
	v_pk_mul_f32 v[134:135], v[134:135], v[140:141]
	s_nop 0
	v_cvt_pk_bf16_f32 v140, v134, v135
	v_add_f32_e32 v133, 1.0, v133
	v_rcp_f32_e32 v144, v133
	v_mul_f32_e32 v133, 0xbfb8aa3b, v143
	v_exp_f32_e32 v133, v133
	v_pk_mul_f32 v[134:135], v[30:31], v[178:179] op_sel_hi:[1,0]
	v_add_f32_e32 v133, 1.0, v133
	v_rcp_f32_e32 v145, v133
	s_nop 0
	v_pk_mul_f32 v[142:143], v[142:143], v[144:145]
	s_nop 0
	v_cvt_pk_bf16_f32 v141, v142, v143
	global_store_dwordx4 v[130:131], v[138:141], off offset:256
	v_pk_mul_f32 v[142:143], v[24:25], v[178:179] op_sel_hi:[1,0]
	v_lshl_add_u64 v[130:131], v[128:129], 0, s[8:9]
	v_pk_mul_f32 v[138:139], v[28:29], v[178:179] op_sel_hi:[1,0]
	v_pk_mul_f32 v[140:141], v[26:27], v[178:179] op_sel_hi:[1,0]
	v_mul_f32_e32 v133, 0xbfb8aa3b, v138
	v_exp_f32_e32 v133, v133
	s_mov_b32 s8, 0x2a5a0000
	v_add_f32_e32 v133, 1.0, v133
	v_rcp_f32_e32 v144, v133
	v_mul_f32_e32 v133, 0xbfb8aa3b, v139
	v_exp_f32_e32 v133, v133
	s_nop 0
	v_add_f32_e32 v133, 1.0, v133
	v_rcp_f32_e32 v145, v133
	v_mul_f32_e32 v133, 0xbfb8aa3b, v134
	v_exp_f32_e32 v133, v133
	v_pk_mul_f32 v[138:139], v[138:139], v[144:145]
	s_nop 0
	v_cvt_pk_bf16_f32 v138, v138, v139
; __device__ __forceinline__ float sigmoid_f(float x) { return __builtin_amdgcn_rcpf(1.f + __expf(-x)); }
; __device__ __forceinline__ f32x4 sigmoid4(f32x4 v) { return (f32x4){sigmoid_f(v[0]), sigmoid_f(v[1]), sigmoid_f(v[2]), sigmoid_f(v[3])}; }
; __device__ __forceinline__ f32x4 silu4(f32x4 v) { return v * sigmoid4(v); }
;     template <int MODE, bool HEADMAJOR>
;     __device__ __forceinline__ void plain(const f32x4 (&acc)[2][2][4][2], const float (&rs)[2][4], bf16_t* base, int row0, int pl, int wc, int fq) const {
; #pragma unroll
;         for (int ai = 0; ai < 2; ++ai)
; #pragma unroll
;             for (int m = 0; m < 4; ++m) { const int row = row0 + ai * 128 + m * 16;
; #pragma unroll
;                 for (int bj = 0; bj < 2; ++bj) { f32x4 v0 = acc[ai][bj][m][0] * rs[ai][m], v1 = acc[ai][bj][m][1] * rs[ai][m];
;                     if (MODE == 1) { v0 = v0 * 0.08838834764831845f; v1 = v1 * 0.08838834764831845f; }
;                     if (MODE == 2) { v0 = silu4(v0); v1 = silu4(v1); }
;                     if (MODE == 3) { v0 = sigmoid4(v0); v1 = sigmoid4(v1); }
;                     bf16_t* ptr = HEADMAJOR ? base + ((size_t)(pl * 2 + bj) * S + row) * 128 + 32 * wc + 8 * fq
;                                             : base + (size_t)row * DM + pl * 256 + bj * 128 + 32 * wc + 8 * fq;
;                     *(u32x4*)ptr = pack8bf(v0, v1); }
;                 asm volatile("" ::: "memory"); }
	v_add_f32_e32 v133, 1.0, v133
	v_rcp_f32_e32 v146, v133
	v_mul_f32_e32 v133, 0xbfb8aa3b, v135
	v_exp_f32_e32 v133, v133
	s_nop 0
	v_add_f32_e32 v133, 1.0, v133
	v_rcp_f32_e32 v147, v133
	v_mul_f32_e32 v133, 0xbfb8aa3b, v142
	v_exp_f32_e32 v133, v133
	v_pk_mul_f32 v[134:135], v[134:135], v[146:147]
	s_nop 0
	v_cvt_pk_bf16_f32 v139, v134, v135
	v_add_f32_e32 v133, 1.0, v133
	v_rcp_f32_e32 v144, v133
	v_mul_f32_e32 v133, 0xbfb8aa3b, v143
	v_exp_f32_e32 v133, v133
	v_add_co_u32_e32 v134, vcc, s8, v128
	s_mov_b64 s[8:9], 0x2a5b0000
	v_add_f32_e32 v133, 1.0, v133
	v_rcp_f32_e32 v145, v133
	v_mul_f32_e32 v133, 0xbfb8aa3b, v140
	v_exp_f32_e32 v133, v133
	v_addc_co_u32_e32 v135, vcc, 0, v129, vcc
	v_add_f32_e32 v133, 1.0, v133
	v_rcp_f32_e32 v146, v133
	v_mul_f32_e32 v133, 0xbfb8aa3b, v141
	v_exp_f32_e32 v133, v133
	s_nop 0
	v_add_f32_e32 v133, 1.0, v133
	v_rcp_f32_e32 v147, v133
	s_nop 0
	v_pk_mul_f32 v[146:147], v[140:141], v[146:147]
	v_pk_mul_f32 v[140:141], v[142:143], v[144:145]
	v_pk_mul_f32 v[142:143], v[16:17], v[178:179] op_sel_hi:[1,0]
	v_cvt_pk_bf16_f32 v140, v140, v141
	v_cvt_pk_bf16_f32 v141, v146, v147
	global_store_dwordx4 v[134:135], v[138:141], off
	v_pk_mul_f32 v[134:135], v[22:23], v[178:179] op_sel_hi:[1,0]
	s_nop 0
	v_pk_mul_f32 v[138:139], v[20:21], v[178:179] op_sel_hi:[1,0]
	v_pk_mul_f32 v[140:141], v[18:19], v[178:179] op_sel_hi:[1,0]
	v_mul_f32_e32 v133, 0xbfb8aa3b, v138
	v_exp_f32_e32 v133, v133
	s_nop 0
	v_add_f32_e32 v133, 1.0, v133
	v_rcp_f32_e32 v144, v133
	v_mul_f32_e32 v133, 0xbfb8aa3b, v139
	v_exp_f32_e32 v133, v133
	s_nop 0
	v_add_f32_e32 v133, 1.0, v133
	v_rcp_f32_e32 v145, v133
	v_mul_f32_e32 v133, 0xbfb8aa3b, v134
	v_exp_f32_e32 v133, v133
	v_pk_mul_f32 v[138:139], v[138:139], v[144:145]
	s_nop 0
	v_cvt_pk_bf16_f32 v138, v138, v139
	v_add_f32_e32 v133, 1.0, v133
	v_rcp_f32_e32 v146, v133
	v_mul_f32_e32 v133, 0xbfb8aa3b, v135
	v_exp_f32_e32 v133, v133
	s_nop 0
	v_add_f32_e32 v133, 1.0, v133
	v_rcp_f32_e32 v147, v133
	v_mul_f32_e32 v133, 0xbfb8aa3b, v142
	v_exp_f32_e32 v133, v133
	v_pk_mul_f32 v[134:135], v[134:135], v[146:147]
	s_nop 0
	v_cvt_pk_bf16_f32 v139, v134, v135
	v_add_f32_e32 v133, 1.0, v133
	v_rcp_f32_e32 v144, v133
	v_mul_f32_e32 v133, 0xbfb8aa3b, v143
	v_exp_f32_e32 v133, v133
	v_mov_b32_e32 v134, v179
	v_add_f32_e32 v133, 1.0, v133
	v_rcp_f32_e32 v145, v133
	v_mul_f32_e32 v133, 0xbfb8aa3b, v140
	v_exp_f32_e32 v133, v133
	s_nop 0
	v_add_f32_e32 v133, 1.0, v133
	v_rcp_f32_e32 v146, v133
	v_mul_f32_e32 v133, 0xbfb8aa3b, v141
	v_exp_f32_e32 v133, v133
	s_nop 0
	v_add_f32_e32 v133, 1.0, v133
	v_rcp_f32_e32 v147, v133
	s_nop 0
	v_pk_mul_f32 v[146:147], v[140:141], v[146:147]
	v_pk_mul_f32 v[140:141], v[142:143], v[144:145]
	v_pk_mul_f32 v[144:145], v[8:9], v[134:135] op_sel_hi:[1,0]
	v_cvt_pk_bf16_f32 v140, v140, v141
	v_cvt_pk_bf16_f32 v141, v146, v147
	global_store_dwordx4 v[130:131], v[138:141], off offset:256
	v_pk_mul_f32 v[142:143], v[10:11], v[134:135] op_sel_hi:[1,0]
	v_lshl_add_u64 v[130:131], v[128:129], 0, s[8:9]
	v_pk_mul_f32 v[140:141], v[12:13], v[134:135] op_sel_hi:[1,0]
	v_pk_mul_f32 v[138:139], v[14:15], v[134:135] op_sel_hi:[1,0]
	v_mul_f32_e32 v133, 0xbfb8aa3b, v140
	v_exp_f32_e32 v133, v133
	s_mov_b32 s8, 0x2a5b0000
	v_add_co_u32_e32 v128, vcc, s8, v128
	v_add_f32_e32 v133, 1.0, v133
	v_rcp_f32_e32 v146, v133
	v_mul_f32_e32 v133, 0xbfb8aa3b, v141
	v_exp_f32_e32 v133, v133
	v_addc_co_u32_e32 v129, vcc, 0, v129, vcc
	v_add_f32_e32 v133, 1.0, v133
	v_rcp_f32_e32 v147, v133
	v_mul_f32_e32 v133, 0xbfb8aa3b, v138
	v_exp_f32_e32 v133, v133
	s_nop 0
	v_add_f32_e32 v133, 1.0, v133
	v_rcp_f32_e32 v148, v133
	v_mul_f32_e32 v133, 0xbfb8aa3b, v139
	v_exp_f32_e32 v133, v133
	s_nop 0
	v_add_f32_e32 v133, 1.0, v133
	v_rcp_f32_e32 v149, v133
	v_mul_f32_e32 v133, 0xbfb8aa3b, v144
	v_exp_f32_e32 v133, v133
	v_pk_mul_f32 v[148:149], v[138:139], v[148:149]
	v_pk_mul_f32 v[138:139], v[140:141], v[146:147]
	v_add_f32_e32 v133, 1.0, v133
	v_rcp_f32_e32 v140, v133
	v_mul_f32_e32 v133, 0xbfb8aa3b, v145
	v_exp_f32_e32 v133, v133
	v_cvt_pk_bf16_f32 v138, v138, v139
	v_cvt_pk_bf16_f32 v139, v148, v149
	v_add_f32_e32 v133, 1.0, v133
	v_rcp_f32_e32 v141, v133
	v_mul_f32_e32 v133, 0xbfb8aa3b, v142
	v_exp_f32_e32 v133, v133
	v_pk_mul_f32 v[140:141], v[144:145], v[140:141]
	s_nop 0
	v_cvt_pk_bf16_f32 v140, v140, v141
	v_add_f32_e32 v133, 1.0, v133
	v_rcp_f32_e32 v146, v133
	v_mul_f32_e32 v133, 0xbfb8aa3b, v143
	v_exp_f32_e32 v133, v133
	s_nop 0
	v_add_f32_e32 v133, 1.0, v133
	v_rcp_f32_e32 v147, v133
	s_nop 0
	v_pk_mul_f32 v[142:143], v[142:143], v[146:147]
	s_nop 0
	v_cvt_pk_bf16_f32 v141, v142, v143
	global_store_dwordx4 v[128:129], v[138:141], off
	v_pk_mul_f32 v[128:129], v[6:7], v[134:135] op_sel_hi:[1,0]
	s_nop 0
	v_pk_mul_f32 v[138:139], v[4:5], v[134:135] op_sel_hi:[1,0]
	v_pk_mul_f32 v[140:141], v[2:3], v[134:135] op_sel_hi:[1,0]
	v_mul_f32_e32 v133, 0xbfb8aa3b, v138
	v_exp_f32_e32 v133, v133
	v_pk_mul_f32 v[134:135], v[0:1], v[134:135] op_sel_hi:[1,0]
	v_add_f32_e32 v133, 1.0, v133
	v_rcp_f32_e32 v142, v133
	v_mul_f32_e32 v133, 0xbfb8aa3b, v139
	v_exp_f32_e32 v133, v133
	s_nop 0
	v_add_f32_e32 v133, 1.0, v133
	v_rcp_f32_e32 v143, v133
	v_mul_f32_e32 v133, 0xbfb8aa3b, v128
	v_exp_f32_e32 v133, v133
	v_pk_mul_f32 v[138:139], v[138:139], v[142:143]
	s_nop 0
	v_cvt_pk_bf16_f32 v138, v138, v139
	v_add_f32_e32 v133, 1.0, v133
	v_rcp_f32_e32 v144, v133
	v_mul_f32_e32 v133, 0xbfb8aa3b, v129
	v_exp_f32_e32 v133, v133
	s_nop 0
	v_add_f32_e32 v133, 1.0, v133
	v_rcp_f32_e32 v145, v133
	v_mul_f32_e32 v133, 0xbfb8aa3b, v134
	v_exp_f32_e32 v133, v133
	v_pk_mul_f32 v[128:129], v[128:129], v[144:145]
	s_nop 0
	v_cvt_pk_bf16_f32 v139, v128, v129
	v_add_f32_e32 v133, 1.0, v133
	v_rcp_f32_e32 v142, v133
	v_mul_f32_e32 v133, 0xbfb8aa3b, v135
	v_exp_f32_e32 v133, v133
	s_nop 0
	v_add_f32_e32 v133, 1.0, v133
	v_rcp_f32_e32 v143, v133
	v_mul_f32_e32 v133, 0xbfb8aa3b, v140
	v_exp_f32_e32 v133, v133
	v_pk_mul_f32 v[134:135], v[134:135], v[142:143]
	v_add_f32_e32 v133, 1.0, v133
	v_rcp_f32_e32 v144, v133
	v_mul_f32_e32 v133, 0xbfb8aa3b, v141
	v_exp_f32_e32 v133, v133
	s_nop 0
	v_add_f32_e32 v133, 1.0, v133
	v_rcp_f32_e32 v145, v133
	s_nop 0
	v_pk_mul_f32 v[144:145], v[140:141], v[144:145]
	v_cvt_pk_bf16_f32 v140, v134, v135
	v_cvt_pk_bf16_f32 v141, v144, v145
	global_store_dwordx4 v[130:131], v[138:141], off offset:256

; __device__ __forceinline__ f32x4 sigmoid4(f32x4 v) { return (f32x4){sigmoid_f(v[0]), sigmoid_f(v[1]), sigmoid_f(v[2]), sigmoid_f(v[3])}; }
; __device__ __forceinline__ f32x4 silu4(f32x4 v) { return v * sigmoid4(v); }
;     template <int MODE, bool HEADMAJOR>
;     __device__ __forceinline__ void plain(const f32x4 (&acc)[2][2][4][2], const float (&rs)[2][4], bf16_t* base, int row0, int pl, int wc, int fq) const {
; #pragma unroll
;         for (int ai = 0; ai < 2; ++ai)
; #pragma unroll
;             for (int m = 0; m < 4; ++m) { const int row = row0 + ai * 128 + m * 16;
; #pragma unroll
;                 for (int bj = 0; bj < 2; ++bj) { f32x4 v0 = acc[ai][bj][m][0] * rs[ai][m], v1 = acc[ai][bj][m][1] * rs[ai][m];
;                     if (MODE == 1) { v0 = v0 * 0.08838834764831845f; v1 = v1 * 0.08838834764831845f; }
;                     if (MODE == 2) { v0 = silu4(v0); v1 = silu4(v1); }
;                     if (MODE == 3) { v0 = sigmoid4(v0); v1 = sigmoid4(v1); }
;                     bf16_t* ptr = HEADMAJOR ? base + ((size_t)(pl * 2 + bj) * S + row) * 128 + 32 * wc + 8 * fq
;                                             : base + (size_t)row * DM + pl * 256 + bj * 128 + 32 * wc + 8 * fq;
;                     *(u32x4*)ptr = pack8bf(v0, v1); }
;                 asm volatile("" ::: "memory"); }
;     __device__ __forceinline__ void operator()(const f32x4 (&acc)[2][2][4][2], const pg8::Unit& u, int wr, int wc, int fr_, int fq_) const {
;     ...
;             case 6: plain<0, true>(acc, rs, (bf16_t*)(ws + WS_VSB), row0, pl, wc, fq); break;
.LBB0_88:
	s_andn2_b64 vcc, exec, s[8:9]
	s_cbranch_vccnz .LBB0_93
	s_cmp_gt_i32 s40, 5
	s_mov_b64 s[8:9], -1
	s_cbranch_scc0 .LBB0_91
	s_lshl_b32 s22, s25, 14
	s_lshl_b32 s8, s4, 1
	s_add_u32 s8, s6, s8
	v_lshlrev_b32_e32 v128, 3, v136
	s_addc_u32 s9, s7, 0
	v_ashrrev_i32_e32 v129, 31, v128
	v_ashrrev_i32_e32 v183, 31, v182
	v_lshl_add_u64 v[128:129], v[128:129], 1, s[8:9]
	s_mov_b64 s[8:9], 0x26500000
	v_lshl_add_u64 v[138:139], v[182:183], 0, s[22:23]
	v_lshl_add_u64 v[128:129], v[128:129], 0, s[8:9]
	s_waitcnt lgkmcnt(0)
	v_pk_mul_f32 v[130:131], v[126:127], v[186:187] op_sel_hi:[1,0]
	v_pk_mul_f32 v[134:135], v[124:125], v[186:187] op_sel_hi:[1,0]
	v_pk_mul_f32 v[142:143], v[122:123], v[186:187] op_sel_hi:[1,0]
	v_pk_mul_f32 v[140:141], v[120:121], v[186:187] op_sel_hi:[1,0]
	v_lshlrev_b64 v[138:139], 8, v[138:139]
	v_lshl_add_u64 v[144:145], v[128:129], 0, v[138:139]
	v_cvt_pk_bf16_f32 v138, v134, v135
	v_cvt_pk_bf16_f32 v139, v130, v131
	v_cvt_pk_bf16_f32 v140, v140, v141
	v_cvt_pk_bf16_f32 v141, v142, v143
	s_or_b32 s8, s22, 0x2000
	s_mov_b32 s9, s23
	global_store_dwordx4 v[144:145], v[138:141], off
	v_pk_mul_f32 v[130:131], v[118:119], v[186:187] op_sel_hi:[1,0]
	v_pk_mul_f32 v[134:135], v[116:117], v[186:187] op_sel_hi:[1,0]
	v_lshl_add_u64 v[138:139], v[182:183], 0, s[8:9]
	v_lshlrev_b64 v[138:139], 8, v[138:139]
	v_lshl_add_u64 v[144:145], v[128:129], 0, v[138:139]
	v_cvt_pk_bf16_f32 v139, v130, v131
	v_add_u32_e32 v130, 16, v182
	v_pk_mul_f32 v[142:143], v[114:115], v[186:187] op_sel_hi:[1,0]
	v_pk_mul_f32 v[140:141], v[112:113], v[186:187] op_sel_hi:[1,0]
	v_ashrrev_i32_e32 v131, 31, v130
	v_cvt_pk_bf16_f32 v138, v134, v135
	v_cvt_pk_bf16_f32 v140, v140, v141
	v_cvt_pk_bf16_f32 v141, v142, v143
	v_mov_b32_e32 v134, v187
	v_lshl_add_u64 v[146:147], v[130:131], 0, s[22:23]
	global_store_dwordx4 v[144:145], v[138:141], off
	v_pk_mul_f32 v[142:143], v[106:107], v[134:135] op_sel_hi:[1,0]
	v_pk_mul_f32 v[144:145], v[104:105], v[134:135] op_sel_hi:[1,0]
	v_pk_mul_f32 v[140:141], v[110:111], v[134:135] op_sel_hi:[1,0]
	v_pk_mul_f32 v[138:139], v[108:109], v[134:135] op_sel_hi:[1,0]
	v_lshlrev_b64 v[146:147], 8, v[146:147]
	v_lshl_add_u64 v[146:147], v[128:129], 0, v[146:147]
	v_cvt_pk_bf16_f32 v138, v138, v139
	v_cvt_pk_bf16_f32 v139, v140, v141
	v_cvt_pk_bf16_f32 v140, v144, v145
	v_cvt_pk_bf16_f32 v141, v142, v143
	v_lshl_add_u64 v[130:131], v[130:131], 0, s[8:9]
	global_store_dwordx4 v[146:147], v[138:141], off
	v_pk_mul_f32 v[142:143], v[98:99], v[134:135] op_sel_hi:[1,0]
	v_lshlrev_b64 v[130:131], 8, v[130:131]
	v_pk_mul_f32 v[140:141], v[102:103], v[134:135] op_sel_hi:[1,0]
	v_pk_mul_f32 v[138:139], v[100:101], v[134:135] op_sel_hi:[1,0]
	v_pk_mul_f32 v[134:135], v[96:97], v[134:135] op_sel_hi:[1,0]
	v_lshl_add_u64 v[130:131], v[128:129], 0, v[130:131]
	v_cvt_pk_bf16_f32 v138, v138, v139
	v_cvt_pk_bf16_f32 v139, v140, v141
	v_cvt_pk_bf16_f32 v140, v134, v135
	v_cvt_pk_bf16_f32 v141, v142, v143
	global_store_dwordx4 v[130:131], v[138:141], off
	v_add_u32_e32 v130, 32, v182
	v_ashrrev_i32_e32 v131, 31, v130
	v_lshl_add_u64 v[144:145], v[130:131], 0, s[22:23]
	v_pk_mul_f32 v[134:135], v[94:95], v[184:185] op_sel_hi:[1,0]
	v_pk_mul_f32 v[138:139], v[92:93], v[184:185] op_sel_hi:[1,0]
	v_pk_mul_f32 v[142:143], v[90:91], v[184:185] op_sel_hi:[1,0]
	v_pk_mul_f32 v[140:141], v[88:89], v[184:185] op_sel_hi:[1,0]
	v_lshlrev_b64 v[144:145], 8, v[144:145]
	v_lshl_add_u64 v[144:145], v[128:129], 0, v[144:145]
	v_cvt_pk_bf16_f32 v138, v138, v139
	v_cvt_pk_bf16_f32 v139, v134, v135
	v_cvt_pk_bf16_f32 v140, v140, v141
	v_cvt_pk_bf16_f32 v141, v142, v143
	v_lshl_add_u64 v[130:131], v[130:131], 0, s[8:9]
	global_store_dwordx4 v[144:145], v[138:141], off
	v_pk_mul_f32 v[134:135], v[86:87], v[184:185] op_sel_hi:[1,0]
	v_pk_mul_f32 v[142:143], v[82:83], v[184:185] op_sel_hi:[1,0]
	v_pk_mul_f32 v[138:139], v[84:85], v[184:185] op_sel_hi:[1,0]
	v_pk_mul_f32 v[140:141], v[80:81], v[184:185] op_sel_hi:[1,0]
	v_lshlrev_b64 v[130:131], 8, v[130:131]
	v_lshl_add_u64 v[130:131], v[128:129], 0, v[130:131]
	v_cvt_pk_bf16_f32 v138, v138, v139
	v_cvt_pk_bf16_f32 v139, v134, v135
	v_cvt_pk_bf16_f32 v140, v140, v141
	v_cvt_pk_bf16_f32 v141, v142, v143
	global_store_dwordx4 v[130:131], v[138:141], off
	v_add_u32_e32 v130, 48, v182
	v_ashrrev_i32_e32 v131, 31, v130
	v_mov_b32_e32 v134, v185
	v_lshl_add_u64 v[146:147], v[130:131], 0, s[22:23]
	v_pk_mul_f32 v[140:141], v[78:79], v[134:135] op_sel_hi:[1,0]
	v_pk_mul_f32 v[138:139], v[76:77], v[134:135] op_sel_hi:[1,0]
	v_pk_mul_f32 v[142:143], v[74:75], v[134:135] op_sel_hi:[1,0]
	v_pk_mul_f32 v[144:145], v[72:73], v[134:135] op_sel_hi:[1,0]
	v_lshlrev_b64 v[146:147], 8, v[146:147]
	v_lshl_add_u64 v[146:147], v[128:129], 0, v[146:147]
	v_cvt_pk_bf16_f32 v138, v138, v139
	v_cvt_pk_bf16_f32 v139, v140, v141
	v_cvt_pk_bf16_f32 v140, v144, v145
	v_cvt_pk_bf16_f32 v141, v142, v143
	v_lshl_add_u64 v[130:131], v[130:131], 0, s[8:9]
	global_store_dwordx4 v[146:147], v[138:141], off
	v_pk_mul_f32 v[142:143], v[66:67], v[134:135] op_sel_hi:[1,0]
	v_lshlrev_b64 v[130:131], 8, v[130:131]
	v_pk_mul_f32 v[140:141], v[70:71], v[134:135] op_sel_hi:[1,0]
	v_pk_mul_f32 v[138:139], v[68:69], v[134:135] op_sel_hi:[1,0]
	v_pk_mul_f32 v[134:135], v[64:65], v[134:135] op_sel_hi:[1,0]
	v_lshl_add_u64 v[130:131], v[128:129], 0, v[130:131]
	v_cvt_pk_bf16_f32 v138, v138, v139
	v_cvt_pk_bf16_f32 v139, v140, v141
	v_cvt_pk_bf16_f32 v140, v134, v135
	v_cvt_pk_bf16_f32 v141, v142, v143
	global_store_dwordx4 v[130:131], v[138:141], off
	v_add_u32_e32 v130, 0x80, v182
	v_ashrrev_i32_e32 v131, 31, v130
	v_lshl_add_u64 v[144:145], v[130:131], 0, s[22:23]
; __device__ __forceinline__ f32x4 sigmoid4(f32x4 v) { return (f32x4){sigmoid_f(v[0]), sigmoid_f(v[1]), sigmoid_f(v[2]), sigmoid_f(v[3])}; }
; __device__ __forceinline__ f32x4 silu4(f32x4 v) { return v * sigmoid4(v); }
;     template <int MODE, bool HEADMAJOR>
;     __device__ __forceinline__ void plain(const f32x4 (&acc)[2][2][4][2], const float (&rs)[2][4], bf16_t* base, int row0, int pl, int wc, int fq) const {
; #pragma unroll
;         for (int ai = 0; ai < 2; ++ai)
; #pragma unroll
;             for (int m = 0; m < 4; ++m) { const int row = row0 + ai * 128 + m * 16;
; #pragma unroll
;                 for (int bj = 0; bj < 2; ++bj) { f32x4 v0 = acc[ai][bj][m][0] * rs[ai][m], v1 = acc[ai][bj][m][1] * rs[ai][m];
;                     if (MODE == 1) { v0 = v0 * 0.08838834764831845f; v1 = v1 * 0.08838834764831845f; }
;                     if (MODE == 2) { v0 = silu4(v0); v1 = silu4(v1); }
;                     if (MODE == 3) { v0 = sigmoid4(v0); v1 = sigmoid4(v1); }
;                     bf16_t* ptr = HEADMAJOR ? base + ((size_t)(pl * 2 + bj) * S + row) * 128 + 32 * wc + 8 * fq
;                                             : base + (size_t)row * DM + pl * 256 + bj * 128 + 32 * wc + 8 * fq;
;                     *(u32x4*)ptr = pack8bf(v0, v1); }
;                 asm volatile("" ::: "memory"); }
;     __device__ __forceinline__ void operator()(const f32x4 (&acc)[2][2][4][2], const pg8::Unit& u, int wr, int wc, int fr_, int fq_) const {
;     ...
;             case 6: plain<0, true>(acc, rs, (bf16_t*)(ws + WS_VSB), row0, pl, wc, fq); break;
	v_pk_mul_f32 v[134:135], v[62:63], v[180:181] op_sel_hi:[1,0]
	v_pk_mul_f32 v[138:139], v[60:61], v[180:181] op_sel_hi:[1,0]
	v_pk_mul_f32 v[142:143], v[58:59], v[180:181] op_sel_hi:[1,0]
	v_pk_mul_f32 v[140:141], v[56:57], v[180:181] op_sel_hi:[1,0]
	v_lshlrev_b64 v[144:145], 8, v[144:145]
	v_lshl_add_u64 v[144:145], v[128:129], 0, v[144:145]
	v_cvt_pk_bf16_f32 v138, v138, v139
	v_cvt_pk_bf16_f32 v139, v134, v135
	v_cvt_pk_bf16_f32 v140, v140, v141
	v_cvt_pk_bf16_f32 v141, v142, v143
	v_lshl_add_u64 v[130:131], v[130:131], 0, s[8:9]
	global_store_dwordx4 v[144:145], v[138:141], off
	v_pk_mul_f32 v[134:135], v[54:55], v[180:181] op_sel_hi:[1,0]
	v_pk_mul_f32 v[142:143], v[50:51], v[180:181] op_sel_hi:[1,0]
	v_pk_mul_f32 v[138:139], v[52:53], v[180:181] op_sel_hi:[1,0]
	v_pk_mul_f32 v[140:141], v[48:49], v[180:181] op_sel_hi:[1,0]
	v_lshlrev_b64 v[130:131], 8, v[130:131]
	v_lshl_add_u64 v[130:131], v[128:129], 0, v[130:131]
	v_cvt_pk_bf16_f32 v138, v138, v139
	v_cvt_pk_bf16_f32 v139, v134, v135
	v_cvt_pk_bf16_f32 v140, v140, v141
	v_cvt_pk_bf16_f32 v141, v142, v143
	global_store_dwordx4 v[130:131], v[138:141], off
	v_add_u32_e32 v130, 0x90, v182
	v_ashrrev_i32_e32 v131, 31, v130
	v_mov_b32_e32 v134, v181
	v_lshl_add_u64 v[146:147], v[130:131], 0, s[22:23]
	v_pk_mul_f32 v[140:141], v[46:47], v[134:135] op_sel_hi:[1,0]
	v_pk_mul_f32 v[138:139], v[44:45], v[134:135] op_sel_hi:[1,0]
	v_pk_mul_f32 v[142:143], v[42:43], v[134:135] op_sel_hi:[1,0]
	v_pk_mul_f32 v[144:145], v[40:41], v[134:135] op_sel_hi:[1,0]
	v_lshlrev_b64 v[146:147], 8, v[146:147]
	v_lshl_add_u64 v[146:147], v[128:129], 0, v[146:147]
	v_cvt_pk_bf16_f32 v138, v138, v139
	v_cvt_pk_bf16_f32 v139, v140, v141
	v_cvt_pk_bf16_f32 v140, v144, v145
	v_cvt_pk_bf16_f32 v141, v142, v143
	v_lshl_add_u64 v[130:131], v[130:131], 0, s[8:9]
	global_store_dwordx4 v[146:147], v[138:141], off
	v_pk_mul_f32 v[142:143], v[34:35], v[134:135] op_sel_hi:[1,0]
	v_lshlrev_b64 v[130:131], 8, v[130:131]
	v_pk_mul_f32 v[140:141], v[38:39], v[134:135] op_sel_hi:[1,0]
	v_pk_mul_f32 v[138:139], v[36:37], v[134:135] op_sel_hi:[1,0]
	v_pk_mul_f32 v[134:135], v[32:33], v[134:135] op_sel_hi:[1,0]
	v_lshl_add_u64 v[130:131], v[128:129], 0, v[130:131]
	v_cvt_pk_bf16_f32 v138, v138, v139
	v_cvt_pk_bf16_f32 v139, v140, v141
	v_cvt_pk_bf16_f32 v140, v134, v135
	v_cvt_pk_bf16_f32 v141, v142, v143
	global_store_dwordx4 v[130:131], v[138:141], off
	v_add_u32_e32 v130, 0xa0, v182
	v_ashrrev_i32_e32 v131, 31, v130
	v_lshl_add_u64 v[144:145], v[130:131], 0, s[22:23]
	v_pk_mul_f32 v[134:135], v[30:31], v[178:179] op_sel_hi:[1,0]
	v_pk_mul_f32 v[138:139], v[28:29], v[178:179] op_sel_hi:[1,0]
	v_pk_mul_f32 v[142:143], v[26:27], v[178:179] op_sel_hi:[1,0]
	v_pk_mul_f32 v[140:141], v[24:25], v[178:179] op_sel_hi:[1,0]
	v_lshlrev_b64 v[144:145], 8, v[144:145]
	v_lshl_add_u64 v[144:145], v[128:129], 0, v[144:145]
	v_cvt_pk_bf16_f32 v138, v138, v139
	v_cvt_pk_bf16_f32 v139, v134, v135
	v_cvt_pk_bf16_f32 v140, v140, v141
	v_cvt_pk_bf16_f32 v141, v142, v143
	v_lshl_add_u64 v[130:131], v[130:131], 0, s[8:9]
	global_store_dwordx4 v[144:145], v[138:141], off
	v_pk_mul_f32 v[134:135], v[22:23], v[178:179] op_sel_hi:[1,0]
	v_pk_mul_f32 v[142:143], v[18:19], v[178:179] op_sel_hi:[1,0]
	v_pk_mul_f32 v[138:139], v[20:21], v[178:179] op_sel_hi:[1,0]
	v_pk_mul_f32 v[140:141], v[16:17], v[178:179] op_sel_hi:[1,0]
	v_lshlrev_b64 v[130:131], 8, v[130:131]
	v_lshl_add_u64 v[130:131], v[128:129], 0, v[130:131]
	v_cvt_pk_bf16_f32 v138, v138, v139
	v_cvt_pk_bf16_f32 v139, v134, v135
	v_cvt_pk_bf16_f32 v140, v140, v141
	v_cvt_pk_bf16_f32 v141, v142, v143
	global_store_dwordx4 v[130:131], v[138:141], off
	v_add_u32_e32 v130, 0xb0, v182
	v_ashrrev_i32_e32 v131, 31, v130
	v_mov_b32_e32 v134, v179
	v_lshl_add_u64 v[146:147], v[130:131], 0, s[22:23]
	v_pk_mul_f32 v[140:141], v[14:15], v[134:135] op_sel_hi:[1,0]
	v_pk_mul_f32 v[138:139], v[12:13], v[134:135] op_sel_hi:[1,0]
	v_pk_mul_f32 v[142:143], v[10:11], v[134:135] op_sel_hi:[1,0]
	v_pk_mul_f32 v[144:145], v[8:9], v[134:135] op_sel_hi:[1,0]
	v_lshlrev_b64 v[146:147], 8, v[146:147]
	v_lshl_add_u64 v[146:147], v[128:129], 0, v[146:147]
	v_cvt_pk_bf16_f32 v138, v138, v139
	v_cvt_pk_bf16_f32 v139, v140, v141
	v_cvt_pk_bf16_f32 v140, v144, v145
	v_cvt_pk_bf16_f32 v141, v142, v143
	v_lshl_add_u64 v[130:131], v[130:131], 0, s[8:9]
	global_store_dwordx4 v[146:147], v[138:141], off
	v_pk_mul_f32 v[142:143], v[2:3], v[134:135] op_sel_hi:[1,0]
	v_lshlrev_b64 v[130:131], 8, v[130:131]
	v_pk_mul_f32 v[138:139], v[6:7], v[134:135] op_sel_hi:[1,0]
	v_pk_mul_f32 v[140:141], v[4:5], v[134:135] op_sel_hi:[1,0]
	v_pk_mul_f32 v[134:135], v[0:1], v[134:135] op_sel_hi:[1,0]
	v_lshl_add_u64 v[144:145], v[128:129], 0, v[130:131]
	v_cvt_pk_bf16_f32 v128, v140, v141
	v_cvt_pk_bf16_f32 v129, v138, v139
	v_cvt_pk_bf16_f32 v130, v134, v135
	v_cvt_pk_bf16_f32 v131, v142, v143
	global_store_dwordx4 v[144:145], v[128:131], off
	s_mov_b64 s[8:9], 0
; __device__ __forceinline__ f32x4 sigmoid4(f32x4 v) { return (f32x4){sigmoid_f(v[0]), sigmoid_f(v[1]), sigmoid_f(v[2]), sigmoid_f(v[3])}; }
; __device__ __forceinline__ f32x4 silu4(f32x4 v) { return v * sigmoid4(v); }
;     template <int MODE, bool HEADMAJOR>
;     __device__ __forceinline__ void plain(const f32x4 (&acc)[2][2][4][2], const float (&rs)[2][4], bf16_t* base, int row0, int pl, int wc, int fq) const {
; #pragma unroll
;         for (int ai = 0; ai < 2; ++ai)
; #pragma unroll
;             for (int m = 0; m < 4; ++m) { const int row = row0 + ai * 128 + m * 16;
; #pragma unroll
;                 for (int bj = 0; bj < 2; ++bj) { f32x4 v0 = acc[ai][bj][m][0] * rs[ai][m], v1 = acc[ai][bj][m][1] * rs[ai][m];
;                     if (MODE == 1) { v0 = v0 * 0.08838834764831845f; v1 = v1 * 0.08838834764831845f; }
;                     if (MODE == 2) { v0 = silu4(v0); v1 = silu4(v1); }
;                     if (MODE == 3) { v0 = sigmoid4(v0); v1 = sigmoid4(v1); }
;                     bf16_t* ptr = HEADMAJOR ? base + ((size_t)(pl * 2 + bj) * S + row) * 128 + 32 * wc + 8 * fq
;                                             : base + (size_t)row * DM + pl * 256 + bj * 128 + 32 * wc + 8 * fq;
;                     *(u32x4*)ptr = pack8bf(v0, v1); }
;                 asm volatile("" ::: "memory"); }
;     __device__ __forceinline__ void operator()(const f32x4 (&acc)[2][2][4][2], const pg8::Unit& u, int wr, int wc, int fr_, int fq_) const {
;     ...
;             case 5: plain<0, true>(acc, rs, (bf16_t*)(ws + WS_KSB), row0, pl, wc, fq); break;
.LBB0_91:
	s_andn2_b64 vcc, exec, s[8:9]
	s_cbranch_vccnz .LBB0_93
	s_lshl_b32 s22, s25, 14
	s_lshl_b32 s8, s4, 1
	s_add_u32 s8, s6, s8
	v_lshlrev_b32_e32 v128, 3, v136
	s_addc_u32 s9, s7, 0
	v_ashrrev_i32_e32 v129, 31, v128
	v_ashrrev_i32_e32 v183, 31, v182
	v_lshl_add_u64 v[128:129], v[128:129], 1, s[8:9]
	s_mov_b64 s[8:9], 0x24500000
	v_lshl_add_u64 v[138:139], v[182:183], 0, s[22:23]
	v_lshl_add_u64 v[128:129], v[128:129], 0, s[8:9]
	s_waitcnt lgkmcnt(0)
	v_pk_mul_f32 v[130:131], v[126:127], v[186:187] op_sel_hi:[1,0]
	v_pk_mul_f32 v[134:135], v[124:125], v[186:187] op_sel_hi:[1,0]
	v_pk_mul_f32 v[142:143], v[122:123], v[186:187] op_sel_hi:[1,0]
	v_pk_mul_f32 v[140:141], v[120:121], v[186:187] op_sel_hi:[1,0]
	v_lshlrev_b64 v[138:139], 8, v[138:139]
	v_lshl_add_u64 v[144:145], v[128:129], 0, v[138:139]
	v_cvt_pk_bf16_f32 v138, v134, v135
	v_cvt_pk_bf16_f32 v139, v130, v131
	v_cvt_pk_bf16_f32 v140, v140, v141
	v_cvt_pk_bf16_f32 v141, v142, v143
	s_or_b32 s8, s22, 0x2000
	s_mov_b32 s9, s23
	global_store_dwordx4 v[144:145], v[138:141], off
	v_pk_mul_f32 v[130:131], v[118:119], v[186:187] op_sel_hi:[1,0]
	v_pk_mul_f32 v[134:135], v[116:117], v[186:187] op_sel_hi:[1,0]
	v_lshl_add_u64 v[138:139], v[182:183], 0, s[8:9]
	v_lshlrev_b64 v[138:139], 8, v[138:139]
	v_lshl_add_u64 v[144:145], v[128:129], 0, v[138:139]
	v_cvt_pk_bf16_f32 v139, v130, v131
	v_add_u32_e32 v130, 16, v182
	v_pk_mul_f32 v[142:143], v[114:115], v[186:187] op_sel_hi:[1,0]
	v_pk_mul_f32 v[140:141], v[112:113], v[186:187] op_sel_hi:[1,0]
	v_ashrrev_i32_e32 v131, 31, v130
	v_cvt_pk_bf16_f32 v138, v134, v135
	v_cvt_pk_bf16_f32 v140, v140, v141
	v_cvt_pk_bf16_f32 v141, v142, v143
	v_mov_b32_e32 v134, v187
	v_lshl_add_u64 v[146:147], v[130:131], 0, s[22:23]
	global_store_dwordx4 v[144:145], v[138:141], off
	v_pk_mul_f32 v[142:143], v[106:107], v[134:135] op_sel_hi:[1,0]
	v_pk_mul_f32 v[144:145], v[104:105], v[134:135] op_sel_hi:[1,0]
	v_pk_mul_f32 v[140:141], v[110:111], v[134:135] op_sel_hi:[1,0]
	v_pk_mul_f32 v[138:139], v[108:109], v[134:135] op_sel_hi:[1,0]
	v_lshlrev_b64 v[146:147], 8, v[146:147]
	v_lshl_add_u64 v[146:147], v[128:129], 0, v[146:147]
	v_cvt_pk_bf16_f32 v138, v138, v139
	v_cvt_pk_bf16_f32 v139, v140, v141
	v_cvt_pk_bf16_f32 v140, v144, v145
	v_cvt_pk_bf16_f32 v141, v142, v143
	v_lshl_add_u64 v[130:131], v[130:131], 0, s[8:9]
	global_store_dwordx4 v[146:147], v[138:141], off
	v_pk_mul_f32 v[142:143], v[98:99], v[134:135] op_sel_hi:[1,0]
	v_lshlrev_b64 v[130:131], 8, v[130:131]
	v_pk_mul_f32 v[140:141], v[102:103], v[134:135] op_sel_hi:[1,0]
	v_pk_mul_f32 v[138:139], v[100:101], v[134:135] op_sel_hi:[1,0]
	v_pk_mul_f32 v[134:135], v[96:97], v[134:135] op_sel_hi:[1,0]
	v_lshl_add_u64 v[130:131], v[128:129], 0, v[130:131]
	v_cvt_pk_bf16_f32 v138, v138, v139
	v_cvt_pk_bf16_f32 v139, v140, v141
	v_cvt_pk_bf16_f32 v140, v134, v135
	v_cvt_pk_bf16_f32 v141, v142, v143
	global_store_dwordx4 v[130:131], v[138:141], off
	v_add_u32_e32 v130, 32, v182
	v_ashrrev_i32_e32 v131, 31, v130
	v_lshl_add_u64 v[144:145], v[130:131], 0, s[22:23]
	v_pk_mul_f32 v[134:135], v[94:95], v[184:185] op_sel_hi:[1,0]
	v_pk_mul_f32 v[138:139], v[92:93], v[184:185] op_sel_hi:[1,0]
	v_pk_mul_f32 v[142:143], v[90:91], v[184:185] op_sel_hi:[1,0]
	v_pk_mul_f32 v[140:141], v[88:89], v[184:185] op_sel_hi:[1,0]
	v_lshlrev_b64 v[144:145], 8, v[144:145]
	v_lshl_add_u64 v[144:145], v[128:129], 0, v[144:145]
	v_cvt_pk_bf16_f32 v138, v138, v139
	v_cvt_pk_bf16_f32 v139, v134, v135
	v_cvt_pk_bf16_f32 v140, v140, v141
	v_cvt_pk_bf16_f32 v141, v142, v143
	v_lshl_add_u64 v[130:131], v[130:131], 0, s[8:9]
	global_store_dwordx4 v[144:145], v[138:141], off
	v_pk_mul_f32 v[134:135], v[86:87], v[184:185] op_sel_hi:[1,0]
	v_pk_mul_f32 v[142:143], v[82:83], v[184:185] op_sel_hi:[1,0]
	v_pk_mul_f32 v[138:139], v[84:85], v[184:185] op_sel_hi:[1,0]
	v_pk_mul_f32 v[140:141], v[80:81], v[184:185] op_sel_hi:[1,0]
	v_lshlrev_b64 v[130:131], 8, v[130:131]
	v_lshl_add_u64 v[130:131], v[128:129], 0, v[130:131]
	v_cvt_pk_bf16_f32 v138, v138, v139
	v_cvt_pk_bf16_f32 v139, v134, v135
	v_cvt_pk_bf16_f32 v140, v140, v141
	v_cvt_pk_bf16_f32 v141, v142, v143
	global_store_dwordx4 v[130:131], v[138:141], off
	v_add_u32_e32 v130, 48, v182
	v_ashrrev_i32_e32 v131, 31, v130
	v_mov_b32_e32 v134, v185
	v_lshl_add_u64 v[146:147], v[130:131], 0, s[22:23]
	v_pk_mul_f32 v[140:141], v[78:79], v[134:135] op_sel_hi:[1,0]
	v_pk_mul_f32 v[138:139], v[76:77], v[134:135] op_sel_hi:[1,0]
	v_pk_mul_f32 v[142:143], v[74:75], v[134:135] op_sel_hi:[1,0]
	v_pk_mul_f32 v[144:145], v[72:73], v[134:135] op_sel_hi:[1,0]
	v_lshlrev_b64 v[146:147], 8, v[146:147]
	v_lshl_add_u64 v[146:147], v[128:129], 0, v[146:147]
	v_cvt_pk_bf16_f32 v138, v138, v139
	v_cvt_pk_bf16_f32 v139, v140, v141
	v_cvt_pk_bf16_f32 v140, v144, v145
	v_cvt_pk_bf16_f32 v141, v142, v143
	v_lshl_add_u64 v[130:131], v[130:131], 0, s[8:9]
	global_store_dwordx4 v[146:147], v[138:141], off
	v_pk_mul_f32 v[142:143], v[66:67], v[134:135] op_sel_hi:[1,0]
	v_lshlrev_b64 v[130:131], 8, v[130:131]
	v_pk_mul_f32 v[140:141], v[70:71], v[134:135] op_sel_hi:[1,0]
	v_pk_mul_f32 v[138:139], v[68:69], v[134:135] op_sel_hi:[1,0]
	v_pk_mul_f32 v[134:135], v[64:65], v[134:135] op_sel_hi:[1,0]
	v_lshl_add_u64 v[130:131], v[128:129], 0, v[130:131]
; __device__ __forceinline__ f32x4 sigmoid4(f32x4 v) { return (f32x4){sigmoid_f(v[0]), sigmoid_f(v[1]), sigmoid_f(v[2]), sigmoid_f(v[3])}; }
; __device__ __forceinline__ f32x4 silu4(f32x4 v) { return v * sigmoid4(v); }
;     template <int MODE, bool HEADMAJOR>
;     __device__ __forceinline__ void plain(const f32x4 (&acc)[2][2][4][2], const float (&rs)[2][4], bf16_t* base, int row0, int pl, int wc, int fq) const {
; #pragma unroll
;         for (int ai = 0; ai < 2; ++ai)
; #pragma unroll
;             for (int m = 0; m < 4; ++m) { const int row = row0 + ai * 128 + m * 16;
; #pragma unroll
;                 for (int bj = 0; bj < 2; ++bj) { f32x4 v0 = acc[ai][bj][m][0] * rs[ai][m], v1 = acc[ai][bj][m][1] * rs[ai][m];
;                     if (MODE == 1) { v0 = v0 * 0.08838834764831845f; v1 = v1 * 0.08838834764831845f; }
;                     if (MODE == 2) { v0 = silu4(v0); v1 = silu4(v1); }
;                     if (MODE == 3) { v0 = sigmoid4(v0); v1 = sigmoid4(v1); }
;                     bf16_t* ptr = HEADMAJOR ? base + ((size_t)(pl * 2 + bj) * S + row) * 128 + 32 * wc + 8 * fq
;                                             : base + (size_t)row * DM + pl * 256 + bj * 128 + 32 * wc + 8 * fq;
;                     *(u32x4*)ptr = pack8bf(v0, v1); }
;                 asm volatile("" ::: "memory"); }
;     __device__ __forceinline__ void operator()(const f32x4 (&acc)[2][2][4][2], const pg8::Unit& u, int wr, int wc, int fr_, int fq_) const {
;     ...
;             case 5: plain<0, true>(acc, rs, (bf16_t*)(ws + WS_KSB), row0, pl, wc, fq); break;
	v_cvt_pk_bf16_f32 v138, v138, v139
	v_cvt_pk_bf16_f32 v139, v140, v141
	v_cvt_pk_bf16_f32 v140, v134, v135
	v_cvt_pk_bf16_f32 v141, v142, v143
	global_store_dwordx4 v[130:131], v[138:141], off
	v_add_u32_e32 v130, 0x80, v182
	v_ashrrev_i32_e32 v131, 31, v130
	v_lshl_add_u64 v[144:145], v[130:131], 0, s[22:23]
	v_pk_mul_f32 v[134:135], v[62:63], v[180:181] op_sel_hi:[1,0]
	v_pk_mul_f32 v[138:139], v[60:61], v[180:181] op_sel_hi:[1,0]
	v_pk_mul_f32 v[142:143], v[58:59], v[180:181] op_sel_hi:[1,0]
	v_pk_mul_f32 v[140:141], v[56:57], v[180:181] op_sel_hi:[1,0]
	v_lshlrev_b64 v[144:145], 8, v[144:145]
	v_lshl_add_u64 v[144:145], v[128:129], 0, v[144:145]
	v_cvt_pk_bf16_f32 v138, v138, v139
	v_cvt_pk_bf16_f32 v139, v134, v135
	v_cvt_pk_bf16_f32 v140, v140, v141
	v_cvt_pk_bf16_f32 v141, v142, v143
	v_lshl_add_u64 v[130:131], v[130:131], 0, s[8:9]
	global_store_dwordx4 v[144:145], v[138:141], off
	v_pk_mul_f32 v[134:135], v[54:55], v[180:181] op_sel_hi:[1,0]
	v_pk_mul_f32 v[142:143], v[50:51], v[180:181] op_sel_hi:[1,0]
	v_pk_mul_f32 v[138:139], v[52:53], v[180:181] op_sel_hi:[1,0]
	v_pk_mul_f32 v[140:141], v[48:49], v[180:181] op_sel_hi:[1,0]
	v_lshlrev_b64 v[130:131], 8, v[130:131]
	v_lshl_add_u64 v[130:131], v[128:129], 0, v[130:131]
	v_cvt_pk_bf16_f32 v138, v138, v139
	v_cvt_pk_bf16_f32 v139, v134, v135
	v_cvt_pk_bf16_f32 v140, v140, v141
	v_cvt_pk_bf16_f32 v141, v142, v143
	global_store_dwordx4 v[130:131], v[138:141], off
	v_add_u32_e32 v130, 0x90, v182
	v_ashrrev_i32_e32 v131, 31, v130
	v_mov_b32_e32 v134, v181
	v_lshl_add_u64 v[146:147], v[130:131], 0, s[22:23]
	v_pk_mul_f32 v[140:141], v[46:47], v[134:135] op_sel_hi:[1,0]
	v_pk_mul_f32 v[138:139], v[44:45], v[134:135] op_sel_hi:[1,0]
	v_pk_mul_f32 v[142:143], v[42:43], v[134:135] op_sel_hi:[1,0]
	v_pk_mul_f32 v[144:145], v[40:41], v[134:135] op_sel_hi:[1,0]
	v_lshlrev_b64 v[146:147], 8, v[146:147]
	v_lshl_add_u64 v[146:147], v[128:129], 0, v[146:147]
	v_cvt_pk_bf16_f32 v138, v138, v139
	v_cvt_pk_bf16_f32 v139, v140, v141
	v_cvt_pk_bf16_f32 v140, v144, v145
	v_cvt_pk_bf16_f32 v141, v142, v143
	v_lshl_add_u64 v[130:131], v[130:131], 0, s[8:9]
	global_store_dwordx4 v[146:147], v[138:141], off
	v_pk_mul_f32 v[142:143], v[34:35], v[134:135] op_sel_hi:[1,0]
	v_lshlrev_b64 v[130:131], 8, v[130:131]
	v_pk_mul_f32 v[140:141], v[38:39], v[134:135] op_sel_hi:[1,0]
	v_pk_mul_f32 v[138:139], v[36:37], v[134:135] op_sel_hi:[1,0]
	v_pk_mul_f32 v[134:135], v[32:33], v[134:135] op_sel_hi:[1,0]
	v_lshl_add_u64 v[130:131], v[128:129], 0, v[130:131]
	v_cvt_pk_bf16_f32 v138, v138, v139
	v_cvt_pk_bf16_f32 v139, v140, v141
	v_cvt_pk_bf16_f32 v140, v134, v135
	v_cvt_pk_bf16_f32 v141, v142, v143
	global_store_dwordx4 v[130:131], v[138:141], off
	v_add_u32_e32 v130, 0xa0, v182
	v_ashrrev_i32_e32 v131, 31, v130
	v_lshl_add_u64 v[144:145], v[130:131], 0, s[22:23]
	v_pk_mul_f32 v[134:135], v[30:31], v[178:179] op_sel_hi:[1,0]
	v_pk_mul_f32 v[138:139], v[28:29], v[178:179] op_sel_hi:[1,0]
	v_pk_mul_f32 v[142:143], v[26:27], v[178:179] op_sel_hi:[1,0]
	v_pk_mul_f32 v[140:141], v[24:25], v[178:179] op_sel_hi:[1,0]
	v_lshlrev_b64 v[144:145], 8, v[144:145]
	v_lshl_add_u64 v[144:145], v[128:129], 0, v[144:145]
	v_cvt_pk_bf16_f32 v138, v138, v139
	v_cvt_pk_bf16_f32 v139, v134, v135
	v_cvt_pk_bf16_f32 v140, v140, v141
	v_cvt_pk_bf16_f32 v141, v142, v143
	v_lshl_add_u64 v[130:131], v[130:131], 0, s[8:9]
	global_store_dwordx4 v[144:145], v[138:141], off
	v_pk_mul_f32 v[134:135], v[22:23], v[178:179] op_sel_hi:[1,0]
	v_pk_mul_f32 v[142:143], v[18:19], v[178:179] op_sel_hi:[1,0]
	v_pk_mul_f32 v[138:139], v[20:21], v[178:179] op_sel_hi:[1,0]
	v_pk_mul_f32 v[140:141], v[16:17], v[178:179] op_sel_hi:[1,0]
	v_lshlrev_b64 v[130:131], 8, v[130:131]
	v_lshl_add_u64 v[130:131], v[128:129], 0, v[130:131]
	v_cvt_pk_bf16_f32 v138, v138, v139
	v_cvt_pk_bf16_f32 v139, v134, v135
	v_cvt_pk_bf16_f32 v140, v140, v141
	v_cvt_pk_bf16_f32 v141, v142, v143
	global_store_dwordx4 v[130:131], v[138:141], off
	v_add_u32_e32 v130, 0xb0, v182
	v_ashrrev_i32_e32 v131, 31, v130
	v_mov_b32_e32 v134, v179
	v_lshl_add_u64 v[146:147], v[130:131], 0, s[22:23]
	v_pk_mul_f32 v[140:141], v[14:15], v[134:135] op_sel_hi:[1,0]
	v_pk_mul_f32 v[138:139], v[12:13], v[134:135] op_sel_hi:[1,0]
	v_pk_mul_f32 v[142:143], v[10:11], v[134:135] op_sel_hi:[1,0]
	v_pk_mul_f32 v[144:145], v[8:9], v[134:135] op_sel_hi:[1,0]
	v_lshlrev_b64 v[146:147], 8, v[146:147]
	v_lshl_add_u64 v[146:147], v[128:129], 0, v[146:147]
	v_cvt_pk_bf16_f32 v138, v138, v139
	v_cvt_pk_bf16_f32 v139, v140, v141
	v_cvt_pk_bf16_f32 v140, v144, v145
	v_cvt_pk_bf16_f32 v141, v142, v143
	v_lshl_add_u64 v[130:131], v[130:131], 0, s[8:9]
	global_store_dwordx4 v[146:147], v[138:141], off
	v_pk_mul_f32 v[142:143], v[2:3], v[134:135] op_sel_hi:[1,0]
	v_lshlrev_b64 v[130:131], 8, v[130:131]
	v_pk_mul_f32 v[138:139], v[6:7], v[134:135] op_sel_hi:[1,0]
	v_pk_mul_f32 v[140:141], v[4:5], v[134:135] op_sel_hi:[1,0]
	v_pk_mul_f32 v[134:135], v[0:1], v[134:135] op_sel_hi:[1,0]
	v_lshl_add_u64 v[144:145], v[128:129], 0, v[130:131]
	v_cvt_pk_bf16_f32 v128, v140, v141
	v_cvt_pk_bf16_f32 v129, v138, v139
	v_cvt_pk_bf16_f32 v130, v134, v135
	v_cvt_pk_bf16_f32 v131, v142, v143
	global_store_dwordx4 v[144:145], v[128:131], off

; __device__ __forceinline__ f32x4 sigmoid4(f32x4 v) { return (f32x4){sigmoid_f(v[0]), sigmoid_f(v[1]), sigmoid_f(v[2]), sigmoid_f(v[3])}; }
; __device__ __forceinline__ f32x4 silu4(f32x4 v) { return v * sigmoid4(v); }
;     template <int MODE, bool HEADMAJOR>
;     __device__ __forceinline__ void plain(const f32x4 (&acc)[2][2][4][2], const float (&rs)[2][4], bf16_t* base, int row0, int pl, int wc, int fq) const {
; #pragma unroll
;         for (int ai = 0; ai < 2; ++ai)
; #pragma unroll
;             for (int m = 0; m < 4; ++m) { const int row = row0 + ai * 128 + m * 16;
; #pragma unroll
;                 for (int bj = 0; bj < 2; ++bj) { f32x4 v0 = acc[ai][bj][m][0] * rs[ai][m], v1 = acc[ai][bj][m][1] * rs[ai][m];
;                     if (MODE == 1) { v0 = v0 * 0.08838834764831845f; v1 = v1 * 0.08838834764831845f; }
;                     if (MODE == 2) { v0 = silu4(v0); v1 = silu4(v1); }
;                     if (MODE == 3) { v0 = sigmoid4(v0); v1 = sigmoid4(v1); }
;                     bf16_t* ptr = HEADMAJOR ? base + ((size_t)(pl * 2 + bj) * S + row) * 128 + 32 * wc + 8 * fq
;                                             : base + (size_t)row * DM + pl * 256 + bj * 128 + 32 * wc + 8 * fq;
;                     *(u32x4*)ptr = pack8bf(v0, v1); }
;                 asm volatile("" ::: "memory"); }
;     __device__ __forceinline__ void operator()(const f32x4 (&acc)[2][2][4][2], const pg8::Unit& u, int wr, int wc, int fr_, int fq_) const {
;     ...
;             case 4: plain<1, true>(acc, rs, (bf16_t*)(ws + WS_QSB), row0, pl, wc, fq); break;
.LBB0_94:
	s_andn2_b64 vcc, exec, s[8:9]
	s_cbranch_vccnz .LBB0_103
	s_cmp_lt_i32 s40, 3
	s_mov_b64 s[8:9], -1
	s_cbranch_scc1 .LBB0_101
	s_cmp_gt_i32 s40, 3
	s_cbranch_scc0 .LBB0_98
	s_lshl_b32 s22, s25, 14
	s_lshl_b32 s8, s4, 1
	s_add_u32 s8, s6, s8
	v_lshlrev_b32_e32 v128, 3, v136
	s_addc_u32 s9, s7, 0
	v_ashrrev_i32_e32 v129, 31, v128
	v_ashrrev_i32_e32 v183, 31, v182
	s_waitcnt lgkmcnt(0)
	v_pk_mul_f32 v[138:139], v[122:123], v[186:187] op_sel_hi:[1,0]
	v_lshl_add_u64 v[128:129], v[128:129], 1, s[8:9]
	s_mov_b64 s[8:9], 0x22500000
	v_pk_mul_f32 v[130:131], v[126:127], v[186:187] op_sel_hi:[1,0]
	v_pk_mul_f32 v[134:135], v[124:125], v[186:187] op_sel_hi:[1,0]
	v_pk_mul_f32 v[140:141], v[120:121], v[186:187] op_sel_hi:[1,0]
	v_pk_mul_f32 v[142:143], v[138:139], s[30:31] op_sel_hi:[1,0]
	v_lshl_add_u64 v[138:139], v[182:183], 0, s[22:23]
	v_lshl_add_u64 v[128:129], v[128:129], 0, s[8:9]
	v_pk_mul_f32 v[130:131], v[130:131], s[30:31] op_sel_hi:[1,0]
	v_pk_mul_f32 v[134:135], v[134:135], s[30:31] op_sel_hi:[1,0]
	v_pk_mul_f32 v[140:141], v[140:141], s[30:31] op_sel_hi:[1,0]
	v_lshlrev_b64 v[138:139], 8, v[138:139]
	v_lshl_add_u64 v[144:145], v[128:129], 0, v[138:139]
	v_cvt_pk_bf16_f32 v138, v134, v135
	v_cvt_pk_bf16_f32 v139, v130, v131
	v_cvt_pk_bf16_f32 v140, v140, v141
	v_cvt_pk_bf16_f32 v141, v142, v143
	global_store_dwordx4 v[144:145], v[138:141], off
	s_or_b32 s8, s22, 0x2000
	s_mov_b32 s9, s23
	v_pk_mul_f32 v[138:139], v[114:115], v[186:187] op_sel_hi:[1,0]
	v_pk_mul_f32 v[130:131], v[118:119], v[186:187] op_sel_hi:[1,0]
	v_pk_mul_f32 v[134:135], v[116:117], v[186:187] op_sel_hi:[1,0]
	v_pk_mul_f32 v[140:141], v[112:113], v[186:187] op_sel_hi:[1,0]
	v_pk_mul_f32 v[142:143], v[138:139], s[30:31] op_sel_hi:[1,0]
	v_lshl_add_u64 v[138:139], v[182:183], 0, s[8:9]
	v_pk_mul_f32 v[130:131], v[130:131], s[30:31] op_sel_hi:[1,0]
	v_pk_mul_f32 v[134:135], v[134:135], s[30:31] op_sel_hi:[1,0]
	v_pk_mul_f32 v[140:141], v[140:141], s[30:31] op_sel_hi:[1,0]
	v_lshlrev_b64 v[138:139], 8, v[138:139]
	v_lshl_add_u64 v[144:145], v[128:129], 0, v[138:139]
	v_cvt_pk_bf16_f32 v138, v134, v135
	v_cvt_pk_bf16_f32 v139, v130, v131
	v_cvt_pk_bf16_f32 v140, v140, v141
	v_cvt_pk_bf16_f32 v141, v142, v143
	v_add_u32_e32 v130, 16, v182
	v_mov_b32_e32 v134, v187
	global_store_dwordx4 v[144:145], v[138:141], off
	v_ashrrev_i32_e32 v131, 31, v130
	v_pk_mul_f32 v[144:145], v[104:105], v[134:135] op_sel_hi:[1,0]
	v_pk_mul_f32 v[138:139], v[110:111], v[134:135] op_sel_hi:[1,0]
	v_pk_mul_f32 v[140:141], v[108:109], v[134:135] op_sel_hi:[1,0]
	v_pk_mul_f32 v[142:143], v[106:107], v[134:135] op_sel_hi:[1,0]
	v_pk_mul_f32 v[146:147], v[138:139], s[30:31] op_sel_hi:[1,0]
	v_pk_mul_f32 v[138:139], v[140:141], s[30:31] op_sel_hi:[1,0]
	v_pk_mul_f32 v[140:141], v[144:145], s[30:31] op_sel_hi:[1,0]
	v_lshl_add_u64 v[144:145], v[130:131], 0, s[22:23]
	v_pk_mul_f32 v[142:143], v[142:143], s[30:31] op_sel_hi:[1,0]
	v_lshlrev_b64 v[144:145], 8, v[144:145]
	v_lshl_add_u64 v[144:145], v[128:129], 0, v[144:145]
	v_cvt_pk_bf16_f32 v138, v138, v139
	v_cvt_pk_bf16_f32 v139, v146, v147
	v_cvt_pk_bf16_f32 v140, v140, v141
	v_cvt_pk_bf16_f32 v141, v142, v143
	global_store_dwordx4 v[144:145], v[138:141], off
	v_pk_mul_f32 v[142:143], v[98:99], v[134:135] op_sel_hi:[1,0]
	v_lshl_add_u64 v[130:131], v[130:131], 0, s[8:9]
	v_pk_mul_f32 v[138:139], v[102:103], v[134:135] op_sel_hi:[1,0]
	v_pk_mul_f32 v[140:141], v[100:101], v[134:135] op_sel_hi:[1,0]
	v_pk_mul_f32 v[134:135], v[96:97], v[134:135] op_sel_hi:[1,0]
	v_pk_mul_f32 v[144:145], v[138:139], s[30:31] op_sel_hi:[1,0]
	v_pk_mul_f32 v[138:139], v[140:141], s[30:31] op_sel_hi:[1,0]
	v_pk_mul_f32 v[142:143], v[142:143], s[30:31] op_sel_hi:[1,0]
	v_pk_mul_f32 v[134:135], v[134:135], s[30:31] op_sel_hi:[1,0]
	v_lshlrev_b64 v[130:131], 8, v[130:131]
	v_lshl_add_u64 v[130:131], v[128:129], 0, v[130:131]
	v_cvt_pk_bf16_f32 v138, v138, v139
	v_cvt_pk_bf16_f32 v139, v144, v145
	v_cvt_pk_bf16_f32 v140, v134, v135
	v_cvt_pk_bf16_f32 v141, v142, v143
	global_store_dwordx4 v[130:131], v[138:141], off
	v_add_u32_e32 v130, 32, v182
	v_ashrrev_i32_e32 v131, 31, v130
	v_pk_mul_f32 v[140:141], v[90:91], v[184:185] op_sel_hi:[1,0]
	v_pk_mul_f32 v[142:143], v[88:89], v[184:185] op_sel_hi:[1,0]
	v_pk_mul_f32 v[134:135], v[94:95], v[184:185] op_sel_hi:[1,0]
	v_pk_mul_f32 v[138:139], v[92:93], v[184:185] op_sel_hi:[1,0]
	v_pk_mul_f32 v[144:145], v[140:141], s[30:31] op_sel_hi:[1,0]
	v_pk_mul_f32 v[140:141], v[142:143], s[30:31] op_sel_hi:[1,0]
	v_lshl_add_u64 v[142:143], v[130:131], 0, s[22:23]
	v_pk_mul_f32 v[134:135], v[134:135], s[30:31] op_sel_hi:[1,0]
	v_pk_mul_f32 v[138:139], v[138:139], s[30:31] op_sel_hi:[1,0]
	v_lshlrev_b64 v[142:143], 8, v[142:143]
	v_lshl_add_u64 v[142:143], v[128:129], 0, v[142:143]
	v_cvt_pk_bf16_f32 v138, v138, v139
	v_cvt_pk_bf16_f32 v139, v134, v135
	v_cvt_pk_bf16_f32 v140, v140, v141
	v_cvt_pk_bf16_f32 v141, v144, v145
	global_store_dwordx4 v[142:143], v[138:141], off
	v_pk_mul_f32 v[134:135], v[86:87], v[184:185] op_sel_hi:[1,0]
	v_pk_mul_f32 v[142:143], v[80:81], v[184:185] op_sel_hi:[1,0]
	v_pk_mul_f32 v[138:139], v[84:85], v[184:185] op_sel_hi:[1,0]
	v_pk_mul_f32 v[140:141], v[82:83], v[184:185] op_sel_hi:[1,0]
	v_lshl_add_u64 v[130:131], v[130:131], 0, s[8:9]
	v_pk_mul_f32 v[134:135], v[134:135], s[30:31] op_sel_hi:[1,0]
	v_pk_mul_f32 v[138:139], v[138:139], s[30:31] op_sel_hi:[1,0]
	v_pk_mul_f32 v[144:145], v[140:141], s[30:31] op_sel_hi:[1,0]
	v_pk_mul_f32 v[140:141], v[142:143], s[30:31] op_sel_hi:[1,0]
	v_lshlrev_b64 v[130:131], 8, v[130:131]
	v_lshl_add_u64 v[130:131], v[128:129], 0, v[130:131]
; __device__ __forceinline__ f32x4 sigmoid4(f32x4 v) { return (f32x4){sigmoid_f(v[0]), sigmoid_f(v[1]), sigmoid_f(v[2]), sigmoid_f(v[3])}; }
; __device__ __forceinline__ f32x4 silu4(f32x4 v) { return v * sigmoid4(v); }
;     template <int MODE, bool HEADMAJOR>
;     __device__ __forceinline__ void plain(const f32x4 (&acc)[2][2][4][2], const float (&rs)[2][4], bf16_t* base, int row0, int pl, int wc, int fq) const {
; #pragma unroll
;         for (int ai = 0; ai < 2; ++ai)
; #pragma unroll
;             for (int m = 0; m < 4; ++m) { const int row = row0 + ai * 128 + m * 16;
; #pragma unroll
;                 for (int bj = 0; bj < 2; ++bj) { f32x4 v0 = acc[ai][bj][m][0] * rs[ai][m], v1 = acc[ai][bj][m][1] * rs[ai][m];
;                     if (MODE == 1) { v0 = v0 * 0.08838834764831845f; v1 = v1 * 0.08838834764831845f; }
;                     if (MODE == 2) { v0 = silu4(v0); v1 = silu4(v1); }
;                     if (MODE == 3) { v0 = sigmoid4(v0); v1 = sigmoid4(v1); }
;                     bf16_t* ptr = HEADMAJOR ? base + ((size_t)(pl * 2 + bj) * S + row) * 128 + 32 * wc + 8 * fq
;                                             : base + (size_t)row * DM + pl * 256 + bj * 128 + 32 * wc + 8 * fq;
;                     *(u32x4*)ptr = pack8bf(v0, v1); }
;                 asm volatile("" ::: "memory"); }
;     __device__ __forceinline__ void operator()(const f32x4 (&acc)[2][2][4][2], const pg8::Unit& u, int wr, int wc, int fr_, int fq_) const {
;     ...
;             case 4: plain<1, true>(acc, rs, (bf16_t*)(ws + WS_QSB), row0, pl, wc, fq); break;
	v_cvt_pk_bf16_f32 v138, v138, v139
	v_cvt_pk_bf16_f32 v139, v134, v135
	v_cvt_pk_bf16_f32 v140, v140, v141
	v_cvt_pk_bf16_f32 v141, v144, v145
	global_store_dwordx4 v[130:131], v[138:141], off
	v_add_u32_e32 v130, 48, v182
	v_mov_b32_e32 v134, v185
	v_ashrrev_i32_e32 v131, 31, v130
	v_pk_mul_f32 v[138:139], v[78:79], v[134:135] op_sel_hi:[1,0]
	v_pk_mul_f32 v[140:141], v[76:77], v[134:135] op_sel_hi:[1,0]
	v_pk_mul_f32 v[144:145], v[72:73], v[134:135] op_sel_hi:[1,0]
	v_pk_mul_f32 v[142:143], v[74:75], v[134:135] op_sel_hi:[1,0]
	v_pk_mul_f32 v[146:147], v[138:139], s[30:31] op_sel_hi:[1,0]
	v_pk_mul_f32 v[138:139], v[140:141], s[30:31] op_sel_hi:[1,0]
	v_pk_mul_f32 v[140:141], v[144:145], s[30:31] op_sel_hi:[1,0]
	v_lshl_add_u64 v[144:145], v[130:131], 0, s[22:23]
	v_pk_mul_f32 v[142:143], v[142:143], s[30:31] op_sel_hi:[1,0]
	v_lshlrev_b64 v[144:145], 8, v[144:145]
	v_lshl_add_u64 v[144:145], v[128:129], 0, v[144:145]
	v_cvt_pk_bf16_f32 v138, v138, v139
	v_cvt_pk_bf16_f32 v139, v146, v147
	v_cvt_pk_bf16_f32 v140, v140, v141
	v_cvt_pk_bf16_f32 v141, v142, v143
	global_store_dwordx4 v[144:145], v[138:141], off
	v_pk_mul_f32 v[142:143], v[66:67], v[134:135] op_sel_hi:[1,0]
	v_lshl_add_u64 v[130:131], v[130:131], 0, s[8:9]
	v_pk_mul_f32 v[138:139], v[70:71], v[134:135] op_sel_hi:[1,0]
	v_pk_mul_f32 v[140:141], v[68:69], v[134:135] op_sel_hi:[1,0]
	v_pk_mul_f32 v[134:135], v[64:65], v[134:135] op_sel_hi:[1,0]
	v_pk_mul_f32 v[144:145], v[138:139], s[30:31] op_sel_hi:[1,0]
	v_pk_mul_f32 v[138:139], v[140:141], s[30:31] op_sel_hi:[1,0]
	v_pk_mul_f32 v[142:143], v[142:143], s[30:31] op_sel_hi:[1,0]
	v_pk_mul_f32 v[134:135], v[134:135], s[30:31] op_sel_hi:[1,0]
	v_lshlrev_b64 v[130:131], 8, v[130:131]
	v_lshl_add_u64 v[130:131], v[128:129], 0, v[130:131]
	v_cvt_pk_bf16_f32 v138, v138, v139
	v_cvt_pk_bf16_f32 v139, v144, v145
	v_cvt_pk_bf16_f32 v140, v134, v135
	v_cvt_pk_bf16_f32 v141, v142, v143
	global_store_dwordx4 v[130:131], v[138:141], off
	v_add_u32_e32 v130, 0x80, v182
	v_ashrrev_i32_e32 v131, 31, v130
	v_pk_mul_f32 v[140:141], v[58:59], v[180:181] op_sel_hi:[1,0]
	v_pk_mul_f32 v[142:143], v[56:57], v[180:181] op_sel_hi:[1,0]
	v_pk_mul_f32 v[134:135], v[62:63], v[180:181] op_sel_hi:[1,0]
	v_pk_mul_f32 v[138:139], v[60:61], v[180:181] op_sel_hi:[1,0]
	v_pk_mul_f32 v[144:145], v[140:141], s[30:31] op_sel_hi:[1,0]
	v_pk_mul_f32 v[140:141], v[142:143], s[30:31] op_sel_hi:[1,0]
	v_lshl_add_u64 v[142:143], v[130:131], 0, s[22:23]
	v_pk_mul_f32 v[134:135], v[134:135], s[30:31] op_sel_hi:[1,0]
	v_pk_mul_f32 v[138:139], v[138:139], s[30:31] op_sel_hi:[1,0]
	v_lshlrev_b64 v[142:143], 8, v[142:143]
	v_lshl_add_u64 v[142:143], v[128:129], 0, v[142:143]
	v_cvt_pk_bf16_f32 v138, v138, v139
	v_cvt_pk_bf16_f32 v139, v134, v135
	v_cvt_pk_bf16_f32 v140, v140, v141
	v_cvt_pk_bf16_f32 v141, v144, v145
	global_store_dwordx4 v[142:143], v[138:141], off
	v_pk_mul_f32 v[134:135], v[54:55], v[180:181] op_sel_hi:[1,0]
	v_pk_mul_f32 v[142:143], v[48:49], v[180:181] op_sel_hi:[1,0]
	v_pk_mul_f32 v[138:139], v[52:53], v[180:181] op_sel_hi:[1,0]
	v_pk_mul_f32 v[140:141], v[50:51], v[180:181] op_sel_hi:[1,0]
	v_lshl_add_u64 v[130:131], v[130:131], 0, s[8:9]
	v_pk_mul_f32 v[134:135], v[134:135], s[30:31] op_sel_hi:[1,0]
	v_pk_mul_f32 v[138:139], v[138:139], s[30:31] op_sel_hi:[1,0]
	v_pk_mul_f32 v[144:145], v[140:141], s[30:31] op_sel_hi:[1,0]
	v_pk_mul_f32 v[140:141], v[142:143], s[30:31] op_sel_hi:[1,0]
	v_lshlrev_b64 v[130:131], 8, v[130:131]
	v_lshl_add_u64 v[130:131], v[128:129], 0, v[130:131]
	v_cvt_pk_bf16_f32 v138, v138, v139
	v_cvt_pk_bf16_f32 v139, v134, v135
	v_cvt_pk_bf16_f32 v140, v140, v141
	v_cvt_pk_bf16_f32 v141, v144, v145
	global_store_dwordx4 v[130:131], v[138:141], off
	v_add_u32_e32 v130, 0x90, v182
	v_mov_b32_e32 v134, v181
	v_ashrrev_i32_e32 v131, 31, v130
	v_pk_mul_f32 v[138:139], v[46:47], v[134:135] op_sel_hi:[1,0]
	v_pk_mul_f32 v[140:141], v[44:45], v[134:135] op_sel_hi:[1,0]
	v_pk_mul_f32 v[144:145], v[40:41], v[134:135] op_sel_hi:[1,0]
	v_pk_mul_f32 v[142:143], v[42:43], v[134:135] op_sel_hi:[1,0]
	v_pk_mul_f32 v[146:147], v[138:139], s[30:31] op_sel_hi:[1,0]
	v_pk_mul_f32 v[138:139], v[140:141], s[30:31] op_sel_hi:[1,0]
	v_pk_mul_f32 v[140:141], v[144:145], s[30:31] op_sel_hi:[1,0]
	v_lshl_add_u64 v[144:145], v[130:131], 0, s[22:23]
	v_pk_mul_f32 v[142:143], v[142:143], s[30:31] op_sel_hi:[1,0]
	v_lshlrev_b64 v[144:145], 8, v[144:145]
	v_lshl_add_u64 v[144:145], v[128:129], 0, v[144:145]
	v_cvt_pk_bf16_f32 v138, v138, v139
	v_cvt_pk_bf16_f32 v139, v146, v147
	v_cvt_pk_bf16_f32 v140, v140, v141
	v_cvt_pk_bf16_f32 v141, v142, v143
	global_store_dwordx4 v[144:145], v[138:141], off
	v_pk_mul_f32 v[142:143], v[34:35], v[134:135] op_sel_hi:[1,0]
	v_lshl_add_u64 v[130:131], v[130:131], 0, s[8:9]
	v_pk_mul_f32 v[138:139], v[38:39], v[134:135] op_sel_hi:[1,0]
	v_pk_mul_f32 v[140:141], v[36:37], v[134:135] op_sel_hi:[1,0]
	v_pk_mul_f32 v[134:135], v[32:33], v[134:135] op_sel_hi:[1,0]
	v_pk_mul_f32 v[144:145], v[138:139], s[30:31] op_sel_hi:[1,0]
	v_pk_mul_f32 v[138:139], v[140:141], s[30:31] op_sel_hi:[1,0]
	v_pk_mul_f32 v[142:143], v[142:143], s[30:31] op_sel_hi:[1,0]
	v_pk_mul_f32 v[134:135], v[134:135], s[30:31] op_sel_hi:[1,0]
	v_lshlrev_b64 v[130:131], 8, v[130:131]
	v_lshl_add_u64 v[130:131], v[128:129], 0, v[130:131]
	v_cvt_pk_bf16_f32 v138, v138, v139
	v_cvt_pk_bf16_f32 v139, v144, v145
	v_cvt_pk_bf16_f32 v140, v134, v135
	v_cvt_pk_bf16_f32 v141, v142, v143
	global_store_dwordx4 v[130:131], v[138:141], off
	v_add_u32_e32 v130, 0xa0, v182
	v_ashrrev_i32_e32 v131, 31, v130
	v_pk_mul_f32 v[140:141], v[26:27], v[178:179] op_sel_hi:[1,0]
; __device__ __forceinline__ float sigmoid_f(float x) { return __builtin_amdgcn_rcpf(1.f + __expf(-x)); }
; __device__ __forceinline__ f32x4 sigmoid4(f32x4 v) { return (f32x4){sigmoid_f(v[0]), sigmoid_f(v[1]), sigmoid_f(v[2]), sigmoid_f(v[3])}; }
; __device__ __forceinline__ f32x4 silu4(f32x4 v) { return v * sigmoid4(v); }
;     template <int MODE, bool HEADMAJOR>
;     __device__ __forceinline__ void plain(const f32x4 (&acc)[2][2][4][2], const float (&rs)[2][4], bf16_t* base, int row0, int pl, int wc, int fq) const {
; #pragma unroll
;         for (int ai = 0; ai < 2; ++ai)
; #pragma unroll
;             for (int m = 0; m < 4; ++m) { const int row = row0 + ai * 128 + m * 16;
; #pragma unroll
;                 for (int bj = 0; bj < 2; ++bj) { f32x4 v0 = acc[ai][bj][m][0] * rs[ai][m], v1 = acc[ai][bj][m][1] * rs[ai][m];
;                     if (MODE == 1) { v0 = v0 * 0.08838834764831845f; v1 = v1 * 0.08838834764831845f; }
;                     if (MODE == 2) { v0 = silu4(v0); v1 = silu4(v1); }
;                     if (MODE == 3) { v0 = sigmoid4(v0); v1 = sigmoid4(v1); }
;                     bf16_t* ptr = HEADMAJOR ? base + ((size_t)(pl * 2 + bj) * S + row) * 128 + 32 * wc + 8 * fq
;                                             : base + (size_t)row * DM + pl * 256 + bj * 128 + 32 * wc + 8 * fq;
;                     *(u32x4*)ptr = pack8bf(v0, v1); }
;                 asm volatile("" ::: "memory"); }
;     __device__ __forceinline__ void operator()(const f32x4 (&acc)[2][2][4][2], const pg8::Unit& u, int wr, int wc, int fr_, int fq_) const {
;     ...
;             case 3: plain<2, false>(acc, rs, (bf16_t*)(ws + WS_ZDA), row0, pl, wc, fq); break;
;             case 4: plain<1, true>(acc, rs, (bf16_t*)(ws + WS_QSB), row0, pl, wc, fq); break;
	v_pk_mul_f32 v[142:143], v[24:25], v[178:179] op_sel_hi:[1,0]
	v_pk_mul_f32 v[134:135], v[30:31], v[178:179] op_sel_hi:[1,0]
	v_pk_mul_f32 v[138:139], v[28:29], v[178:179] op_sel_hi:[1,0]
	v_pk_mul_f32 v[144:145], v[140:141], s[30:31] op_sel_hi:[1,0]
	v_pk_mul_f32 v[140:141], v[142:143], s[30:31] op_sel_hi:[1,0]
	v_lshl_add_u64 v[142:143], v[130:131], 0, s[22:23]
	v_pk_mul_f32 v[134:135], v[134:135], s[30:31] op_sel_hi:[1,0]
	v_pk_mul_f32 v[138:139], v[138:139], s[30:31] op_sel_hi:[1,0]
	v_lshlrev_b64 v[142:143], 8, v[142:143]
	v_lshl_add_u64 v[142:143], v[128:129], 0, v[142:143]
	v_cvt_pk_bf16_f32 v138, v138, v139
	v_cvt_pk_bf16_f32 v139, v134, v135
	v_cvt_pk_bf16_f32 v140, v140, v141
	v_cvt_pk_bf16_f32 v141, v144, v145
	global_store_dwordx4 v[142:143], v[138:141], off
	v_pk_mul_f32 v[134:135], v[22:23], v[178:179] op_sel_hi:[1,0]
	v_pk_mul_f32 v[142:143], v[16:17], v[178:179] op_sel_hi:[1,0]
	v_pk_mul_f32 v[138:139], v[20:21], v[178:179] op_sel_hi:[1,0]
	v_pk_mul_f32 v[140:141], v[18:19], v[178:179] op_sel_hi:[1,0]
	v_lshl_add_u64 v[130:131], v[130:131], 0, s[8:9]
	v_pk_mul_f32 v[134:135], v[134:135], s[30:31] op_sel_hi:[1,0]
	v_pk_mul_f32 v[138:139], v[138:139], s[30:31] op_sel_hi:[1,0]
	v_pk_mul_f32 v[144:145], v[140:141], s[30:31] op_sel_hi:[1,0]
	v_pk_mul_f32 v[140:141], v[142:143], s[30:31] op_sel_hi:[1,0]
	v_lshlrev_b64 v[130:131], 8, v[130:131]
	v_lshl_add_u64 v[130:131], v[128:129], 0, v[130:131]
	v_cvt_pk_bf16_f32 v138, v138, v139
	v_cvt_pk_bf16_f32 v139, v134, v135
	v_cvt_pk_bf16_f32 v140, v140, v141
	v_cvt_pk_bf16_f32 v141, v144, v145
	global_store_dwordx4 v[130:131], v[138:141], off
	v_add_u32_e32 v130, 0xb0, v182
	v_mov_b32_e32 v134, v179
	v_ashrrev_i32_e32 v131, 31, v130
	v_pk_mul_f32 v[138:139], v[14:15], v[134:135] op_sel_hi:[1,0]
	v_pk_mul_f32 v[140:141], v[12:13], v[134:135] op_sel_hi:[1,0]
	v_pk_mul_f32 v[144:145], v[8:9], v[134:135] op_sel_hi:[1,0]
	v_pk_mul_f32 v[142:143], v[10:11], v[134:135] op_sel_hi:[1,0]
	v_pk_mul_f32 v[146:147], v[138:139], s[30:31] op_sel_hi:[1,0]
	v_pk_mul_f32 v[138:139], v[140:141], s[30:31] op_sel_hi:[1,0]
	v_pk_mul_f32 v[140:141], v[144:145], s[30:31] op_sel_hi:[1,0]
	v_lshl_add_u64 v[144:145], v[130:131], 0, s[22:23]
	v_pk_mul_f32 v[142:143], v[142:143], s[30:31] op_sel_hi:[1,0]
	v_lshlrev_b64 v[144:145], 8, v[144:145]
	v_lshl_add_u64 v[144:145], v[128:129], 0, v[144:145]
	v_cvt_pk_bf16_f32 v138, v138, v139
	v_cvt_pk_bf16_f32 v139, v146, v147
	v_cvt_pk_bf16_f32 v140, v140, v141
	v_cvt_pk_bf16_f32 v141, v142, v143
	global_store_dwordx4 v[144:145], v[138:141], off
	v_pk_mul_f32 v[142:143], v[2:3], v[134:135] op_sel_hi:[1,0]
	v_lshl_add_u64 v[130:131], v[130:131], 0, s[8:9]
	v_pk_mul_f32 v[138:139], v[6:7], v[134:135] op_sel_hi:[1,0]
	v_pk_mul_f32 v[140:141], v[4:5], v[134:135] op_sel_hi:[1,0]
	v_pk_mul_f32 v[134:135], v[0:1], v[134:135] op_sel_hi:[1,0]
	v_pk_mul_f32 v[138:139], v[138:139], s[30:31] op_sel_hi:[1,0]
	v_pk_mul_f32 v[140:141], v[140:141], s[30:31] op_sel_hi:[1,0]
	v_pk_mul_f32 v[142:143], v[142:143], s[30:31] op_sel_hi:[1,0]
	v_pk_mul_f32 v[134:135], v[134:135], s[30:31] op_sel_hi:[1,0]
	v_lshlrev_b64 v[130:131], 8, v[130:131]
	v_lshl_add_u64 v[144:145], v[128:129], 0, v[130:131]
	v_cvt_pk_bf16_f32 v128, v140, v141
	v_cvt_pk_bf16_f32 v129, v138, v139
	v_cvt_pk_bf16_f32 v130, v134, v135
	v_cvt_pk_bf16_f32 v131, v142, v143
	global_store_dwordx4 v[144:145], v[128:131], off
	s_mov_b64 s[8:9], 0
.LBB0_98:
	s_andn2_b64 vcc, exec, s[8:9]
	s_cbranch_vccnz .LBB0_100
	s_waitcnt lgkmcnt(0)
	v_pk_mul_f32 v[138:139], v[124:125], v[186:187] op_sel_hi:[1,0]
	v_pk_mul_f32 v[134:135], v[126:127], v[186:187] op_sel_hi:[1,0]
	v_mul_f32_e32 v133, 0xbfb8aa3b, v138
	v_exp_f32_e32 v133, v133
	v_pk_mul_f32 v[142:143], v[120:121], v[186:187] op_sel_hi:[1,0]
	v_pk_mul_f32 v[140:141], v[122:123], v[186:187] op_sel_hi:[1,0]
	s_lshl_b32 s8, s25, 9
	v_add_f32_e32 v133, 1.0, v133
	v_rcp_f32_e32 v144, v133
	v_mul_f32_e32 v133, 0xbfb8aa3b, v139
	v_exp_f32_e32 v133, v133
	s_add_u32 s8, s6, s8
	s_addc_u32 s9, s7, 0
	s_lshl_b32 s22, s4, 1
	v_add_f32_e32 v133, 1.0, v133
	v_rcp_f32_e32 v145, v133
	v_mul_f32_e32 v133, 0xbfb8aa3b, v134
	v_exp_f32_e32 v133, v133
	s_add_u32 s8, s8, s22
	v_pk_mul_f32 v[138:139], v[138:139], v[144:145]
	v_lshlrev_b32_e32 v128, 3, v136
	v_add_f32_e32 v133, 1.0, v133
	v_rcp_f32_e32 v146, v133
	v_mul_f32_e32 v133, 0xbfb8aa3b, v135
	v_exp_f32_e32 v133, v133
	s_addc_u32 s9, s9, 0
	v_ashrrev_i32_e32 v129, 31, v128
	v_ashrrev_i32_e32 v183, 31, v182
	v_add_f32_e32 v133, 1.0, v133
	v_rcp_f32_e32 v147, v133
	v_mul_f32_e32 v133, 0xbfb8aa3b, v142
	v_exp_f32_e32 v133, v133
	v_lshl_add_u64 v[128:129], v[128:129], 1, s[8:9]
	v_pk_mul_f32 v[134:135], v[134:135], v[146:147]
	v_lshlrev_b64 v[130:131], 12, v[182:183]
	v_add_f32_e32 v133, 1.0, v133
	v_rcp_f32_e32 v144, v133
	v_mul_f32_e32 v133, 0xbfb8aa3b, v143
	v_exp_f32_e32 v133, v133
	v_lshl_add_u64 v[128:129], v[128:129], 0, v[130:131]
	s_mov_b64 s[8:9], 0x28500000
	v_lshl_add_u64 v[130:131], v[128:129], 0, s[8:9]
	v_add_f32_e32 v133, 1.0, v133
	v_rcp_f32_e32 v145, v133
	v_mul_f32_e32 v133, 0xbfb8aa3b, v140
	v_exp_f32_e32 v133, v133
	s_mov_b32 s8, 0x28500000
	v_cvt_pk_bf16_f32 v138, v138, v139
	v_cvt_pk_bf16_f32 v139, v134, v135
	v_add_f32_e32 v133, 1.0, v133
	v_rcp_f32_e32 v146, v133
	v_mul_f32_e32 v133, 0xbfb8aa3b, v141
	v_exp_f32_e32 v133, v133
	v_add_co_u32_e32 v134, vcc, s8, v128
	s_mov_b64 s[8:9], 0x28510000
	v_add_f32_e32 v133, 1.0, v133
	v_rcp_f32_e32 v147, v133
	v_addc_co_u32_e32 v135, vcc, 0, v129, vcc
	v_pk_mul_f32 v[146:147], v[140:141], v[146:147]
	v_pk_mul_f32 v[140:141], v[142:143], v[144:145]
	v_pk_mul_f32 v[142:143], v[112:113], v[186:187] op_sel_hi:[1,0]
; __device__ __forceinline__ float sigmoid_f(float x) { return __builtin_amdgcn_rcpf(1.f + __expf(-x)); }
; __device__ __forceinline__ f32x4 sigmoid4(f32x4 v) { return (f32x4){sigmoid_f(v[0]), sigmoid_f(v[1]), sigmoid_f(v[2]), sigmoid_f(v[3])}; }
; __device__ __forceinline__ f32x4 silu4(f32x4 v) { return v * sigmoid4(v); }
;     template <int MODE, bool HEADMAJOR>
;     __device__ __forceinline__ void plain(const f32x4 (&acc)[2][2][4][2], const float (&rs)[2][4], bf16_t* base, int row0, int pl, int wc, int fq) const {
; #pragma unroll
;         for (int ai = 0; ai < 2; ++ai)
; #pragma unroll
;             for (int m = 0; m < 4; ++m) { const int row = row0 + ai * 128 + m * 16;
; #pragma unroll
;                 for (int bj = 0; bj < 2; ++bj) { f32x4 v0 = acc[ai][bj][m][0] * rs[ai][m], v1 = acc[ai][bj][m][1] * rs[ai][m];
;                     if (MODE == 1) { v0 = v0 * 0.08838834764831845f; v1 = v1 * 0.08838834764831845f; }
;                     if (MODE == 2) { v0 = silu4(v0); v1 = silu4(v1); }
;                     if (MODE == 3) { v0 = sigmoid4(v0); v1 = sigmoid4(v1); }
;                     bf16_t* ptr = HEADMAJOR ? base + ((size_t)(pl * 2 + bj) * S + row) * 128 + 32 * wc + 8 * fq
;                                             : base + (size_t)row * DM + pl * 256 + bj * 128 + 32 * wc + 8 * fq;
;                     *(u32x4*)ptr = pack8bf(v0, v1); }
;                 asm volatile("" ::: "memory"); }
	v_cvt_pk_bf16_f32 v140, v140, v141
	v_cvt_pk_bf16_f32 v141, v146, v147
	global_store_dwordx4 v[134:135], v[138:141], off
	v_pk_mul_f32 v[134:135], v[118:119], v[186:187] op_sel_hi:[1,0]
	s_nop 0
	v_pk_mul_f32 v[138:139], v[116:117], v[186:187] op_sel_hi:[1,0]
	v_pk_mul_f32 v[140:141], v[114:115], v[186:187] op_sel_hi:[1,0]
	v_mul_f32_e32 v133, 0xbfb8aa3b, v138
	v_exp_f32_e32 v133, v133
	s_nop 0
	v_add_f32_e32 v133, 1.0, v133
	v_rcp_f32_e32 v144, v133
	v_mul_f32_e32 v133, 0xbfb8aa3b, v139
	v_exp_f32_e32 v133, v133
	s_nop 0
	v_add_f32_e32 v133, 1.0, v133
	v_rcp_f32_e32 v145, v133
	v_mul_f32_e32 v133, 0xbfb8aa3b, v134
	v_exp_f32_e32 v133, v133
	v_pk_mul_f32 v[138:139], v[138:139], v[144:145]
	s_nop 0
	v_cvt_pk_bf16_f32 v138, v138, v139
	v_add_f32_e32 v133, 1.0, v133
	v_rcp_f32_e32 v146, v133
	v_mul_f32_e32 v133, 0xbfb8aa3b, v135
	v_exp_f32_e32 v133, v133
	s_nop 0
	v_add_f32_e32 v133, 1.0, v133
	v_rcp_f32_e32 v147, v133
	v_mul_f32_e32 v133, 0xbfb8aa3b, v142
	v_exp_f32_e32 v133, v133
	v_pk_mul_f32 v[134:135], v[134:135], v[146:147]
	s_nop 0
	v_cvt_pk_bf16_f32 v139, v134, v135
	v_add_f32_e32 v133, 1.0, v133
	v_rcp_f32_e32 v144, v133
	v_mul_f32_e32 v133, 0xbfb8aa3b, v143
	v_exp_f32_e32 v133, v133
	v_mov_b32_e32 v134, v187
	v_add_f32_e32 v133, 1.0, v133
	v_rcp_f32_e32 v145, v133
	v_mul_f32_e32 v133, 0xbfb8aa3b, v140
	v_exp_f32_e32 v133, v133
	s_nop 0
	v_add_f32_e32 v133, 1.0, v133
	v_rcp_f32_e32 v146, v133
	v_mul_f32_e32 v133, 0xbfb8aa3b, v141
	v_exp_f32_e32 v133, v133
	s_nop 0
	v_add_f32_e32 v133, 1.0, v133
	v_rcp_f32_e32 v147, v133
	s_nop 0
	v_pk_mul_f32 v[146:147], v[140:141], v[146:147]
	v_pk_mul_f32 v[140:141], v[142:143], v[144:145]
	v_pk_mul_f32 v[144:145], v[104:105], v[134:135] op_sel_hi:[1,0]
	v_cvt_pk_bf16_f32 v140, v140, v141
	v_cvt_pk_bf16_f32 v141, v146, v147
	global_store_dwordx4 v[130:131], v[138:141], off offset:256
	v_pk_mul_f32 v[142:143], v[106:107], v[134:135] op_sel_hi:[1,0]
	v_lshl_add_u64 v[130:131], v[128:129], 0, s[8:9]
	v_pk_mul_f32 v[140:141], v[108:109], v[134:135] op_sel_hi:[1,0]
	v_pk_mul_f32 v[138:139], v[110:111], v[134:135] op_sel_hi:[1,0]
	v_mul_f32_e32 v133, 0xbfb8aa3b, v140
	v_exp_f32_e32 v133, v133
	s_mov_b32 s8, 0x28510000
	v_add_f32_e32 v133, 1.0, v133
	v_rcp_f32_e32 v146, v133
	v_mul_f32_e32 v133, 0xbfb8aa3b, v141
	v_exp_f32_e32 v133, v133
	s_nop 0
	v_add_f32_e32 v133, 1.0, v133
	v_rcp_f32_e32 v147, v133
	v_mul_f32_e32 v133, 0xbfb8aa3b, v138
	v_exp_f32_e32 v133, v133
	s_nop 0
	v_add_f32_e32 v133, 1.0, v133
	v_rcp_f32_e32 v148, v133
	v_mul_f32_e32 v133, 0xbfb8aa3b, v139
	v_exp_f32_e32 v133, v133
	s_nop 0
	v_add_f32_e32 v133, 1.0, v133
	v_rcp_f32_e32 v149, v133
	v_mul_f32_e32 v133, 0xbfb8aa3b, v144
	v_exp_f32_e32 v133, v133
	v_pk_mul_f32 v[148:149], v[138:139], v[148:149]
	v_pk_mul_f32 v[138:139], v[140:141], v[146:147]
	v_add_f32_e32 v133, 1.0, v133
	v_rcp_f32_e32 v140, v133
	v_mul_f32_e32 v133, 0xbfb8aa3b, v145
	v_exp_f32_e32 v133, v133
	v_cvt_pk_bf16_f32 v138, v138, v139
	v_cvt_pk_bf16_f32 v139, v148, v149
	v_add_f32_e32 v133, 1.0, v133
	v_rcp_f32_e32 v141, v133
	v_mul_f32_e32 v133, 0xbfb8aa3b, v142
	v_exp_f32_e32 v133, v133
	v_pk_mul_f32 v[140:141], v[144:145], v[140:141]
	s_nop 0
	v_cvt_pk_bf16_f32 v140, v140, v141
	v_add_f32_e32 v133, 1.0, v133
	v_rcp_f32_e32 v146, v133
	v_mul_f32_e32 v133, 0xbfb8aa3b, v143
	v_exp_f32_e32 v133, v133
	s_nop 0
	v_add_f32_e32 v133, 1.0, v133
	v_rcp_f32_e32 v147, v133
	s_nop 0
	v_pk_mul_f32 v[142:143], v[142:143], v[146:147]
	s_nop 0
	v_cvt_pk_bf16_f32 v141, v142, v143
	v_add_co_u32_e32 v142, vcc, s8, v128
	s_mov_b64 s[8:9], 0x28520000
	s_nop 0
	v_addc_co_u32_e32 v143, vcc, 0, v129, vcc
	global_store_dwordx4 v[142:143], v[138:141], off
	v_pk_mul_f32 v[142:143], v[98:99], v[134:135] op_sel_hi:[1,0]
	s_nop 0
	v_pk_mul_f32 v[140:141], v[100:101], v[134:135] op_sel_hi:[1,0]
	v_pk_mul_f32 v[138:139], v[102:103], v[134:135] op_sel_hi:[1,0]
	v_mul_f32_e32 v133, 0xbfb8aa3b, v140
	v_exp_f32_e32 v133, v133
	v_pk_mul_f32 v[134:135], v[96:97], v[134:135] op_sel_hi:[1,0]
	v_add_f32_e32 v133, 1.0, v133
	v_rcp_f32_e32 v144, v133
	v_mul_f32_e32 v133, 0xbfb8aa3b, v141
	v_exp_f32_e32 v133, v133
	s_nop 0
	v_add_f32_e32 v133, 1.0, v133
	v_rcp_f32_e32 v145, v133
	v_mul_f32_e32 v133, 0xbfb8aa3b, v138
	v_exp_f32_e32 v133, v133
	s_nop 0
	v_add_f32_e32 v133, 1.0, v133
	v_rcp_f32_e32 v146, v133
	v_mul_f32_e32 v133, 0xbfb8aa3b, v139
	v_exp_f32_e32 v133, v133
	s_nop 0
	v_add_f32_e32 v133, 1.0, v133
	v_rcp_f32_e32 v147, v133
	v_mul_f32_e32 v133, 0xbfb8aa3b, v134
	v_exp_f32_e32 v133, v133
	v_pk_mul_f32 v[146:147], v[138:139], v[146:147]
	v_pk_mul_f32 v[138:139], v[140:141], v[144:145]
	v_add_f32_e32 v133, 1.0, v133
	v_rcp_f32_e32 v140, v133
	v_mul_f32_e32 v133, 0xbfb8aa3b, v135
	v_exp_f32_e32 v133, v133
	v_cvt_pk_bf16_f32 v138, v138, v139
	v_cvt_pk_bf16_f32 v139, v146, v147
	v_add_f32_e32 v133, 1.0, v133
	v_rcp_f32_e32 v141, v133
	v_mul_f32_e32 v133, 0xbfb8aa3b, v142
	v_exp_f32_e32 v133, v133
	v_pk_mul_f32 v[134:135], v[134:135], v[140:141]
	s_nop 0
	v_cvt_pk_bf16_f32 v140, v134, v135
	v_add_f32_e32 v133, 1.0, v133
	v_rcp_f32_e32 v144, v133
	v_mul_f32_e32 v133, 0xbfb8aa3b, v143
	v_exp_f32_e32 v133, v133
	v_pk_mul_f32 v[134:135], v[94:95], v[184:185] op_sel_hi:[1,0]
	v_add_f32_e32 v133, 1.0, v133
	v_rcp_f32_e32 v145, v133
	s_nop 0
	v_pk_mul_f32 v[142:143], v[142:143], v[144:145]
	s_nop 0
	v_cvt_pk_bf16_f32 v141, v142, v143
	global_store_dwordx4 v[130:131], v[138:141], off offset:256
	v_pk_mul_f32 v[142:143], v[88:89], v[184:185] op_sel_hi:[1,0]
	v_lshl_add_u64 v[130:131], v[128:129], 0, s[8:9]
	v_pk_mul_f32 v[138:139], v[92:93], v[184:185] op_sel_hi:[1,0]
	v_pk_mul_f32 v[140:141], v[90:91], v[184:185] op_sel_hi:[1,0]
; __device__ __forceinline__ float sigmoid_f(float x) { return __builtin_amdgcn_rcpf(1.f + __expf(-x)); }
; __device__ __forceinline__ f32x4 sigmoid4(f32x4 v) { return (f32x4){sigmoid_f(v[0]), sigmoid_f(v[1]), sigmoid_f(v[2]), sigmoid_f(v[3])}; }
; __device__ __forceinline__ f32x4 silu4(f32x4 v) { return v * sigmoid4(v); }
;     template <int MODE, bool HEADMAJOR>
;     __device__ __forceinline__ void plain(const f32x4 (&acc)[2][2][4][2], const float (&rs)[2][4], bf16_t* base, int row0, int pl, int wc, int fq) const {
; #pragma unroll
;         for (int ai = 0; ai < 2; ++ai)
; #pragma unroll
;             for (int m = 0; m < 4; ++m) { const int row = row0 + ai * 128 + m * 16;
; #pragma unroll
;                 for (int bj = 0; bj < 2; ++bj) { f32x4 v0 = acc[ai][bj][m][0] * rs[ai][m], v1 = acc[ai][bj][m][1] * rs[ai][m];
;                     if (MODE == 1) { v0 = v0 * 0.08838834764831845f; v1 = v1 * 0.08838834764831845f; }
;                     if (MODE == 2) { v0 = silu4(v0); v1 = silu4(v1); }
;                     if (MODE == 3) { v0 = sigmoid4(v0); v1 = sigmoid4(v1); }
;                     bf16_t* ptr = HEADMAJOR ? base + ((size_t)(pl * 2 + bj) * S + row) * 128 + 32 * wc + 8 * fq
;                                             : base + (size_t)row * DM + pl * 256 + bj * 128 + 32 * wc + 8 * fq;
;                     *(u32x4*)ptr = pack8bf(v0, v1); }
;                 asm volatile("" ::: "memory"); }
	v_mul_f32_e32 v133, 0xbfb8aa3b, v138
	v_exp_f32_e32 v133, v133
	s_mov_b32 s8, 0x28520000
	v_add_f32_e32 v133, 1.0, v133
	v_rcp_f32_e32 v144, v133
	v_mul_f32_e32 v133, 0xbfb8aa3b, v139
	v_exp_f32_e32 v133, v133
	s_nop 0
	v_add_f32_e32 v133, 1.0, v133
	v_rcp_f32_e32 v145, v133
	v_mul_f32_e32 v133, 0xbfb8aa3b, v134
	v_exp_f32_e32 v133, v133
	v_pk_mul_f32 v[138:139], v[138:139], v[144:145]
	s_nop 0
	v_cvt_pk_bf16_f32 v138, v138, v139
	v_add_f32_e32 v133, 1.0, v133
	v_rcp_f32_e32 v146, v133
	v_mul_f32_e32 v133, 0xbfb8aa3b, v135
	v_exp_f32_e32 v133, v133
	s_nop 0
	v_add_f32_e32 v133, 1.0, v133
	v_rcp_f32_e32 v147, v133
	v_mul_f32_e32 v133, 0xbfb8aa3b, v142
	v_exp_f32_e32 v133, v133
	v_pk_mul_f32 v[134:135], v[134:135], v[146:147]
	s_nop 0
	v_cvt_pk_bf16_f32 v139, v134, v135
	v_add_f32_e32 v133, 1.0, v133
	v_rcp_f32_e32 v144, v133
	v_mul_f32_e32 v133, 0xbfb8aa3b, v143
	v_exp_f32_e32 v133, v133
	v_add_co_u32_e32 v134, vcc, s8, v128
	s_mov_b64 s[8:9], 0x28530000
	v_add_f32_e32 v133, 1.0, v133
	v_rcp_f32_e32 v145, v133
	v_mul_f32_e32 v133, 0xbfb8aa3b, v140
	v_exp_f32_e32 v133, v133
	v_addc_co_u32_e32 v135, vcc, 0, v129, vcc
	v_add_f32_e32 v133, 1.0, v133
	v_rcp_f32_e32 v146, v133
	v_mul_f32_e32 v133, 0xbfb8aa3b, v141
	v_exp_f32_e32 v133, v133
	s_nop 0
	v_add_f32_e32 v133, 1.0, v133
	v_rcp_f32_e32 v147, v133
	s_nop 0
	v_pk_mul_f32 v[146:147], v[140:141], v[146:147]
	v_pk_mul_f32 v[140:141], v[142:143], v[144:145]
	v_pk_mul_f32 v[142:143], v[80:81], v[184:185] op_sel_hi:[1,0]
	v_cvt_pk_bf16_f32 v140, v140, v141
	v_cvt_pk_bf16_f32 v141, v146, v147
	global_store_dwordx4 v[134:135], v[138:141], off
	v_pk_mul_f32 v[134:135], v[86:87], v[184:185] op_sel_hi:[1,0]
	s_nop 0
	v_pk_mul_f32 v[138:139], v[84:85], v[184:185] op_sel_hi:[1,0]
	v_pk_mul_f32 v[140:141], v[82:83], v[184:185] op_sel_hi:[1,0]
	v_mul_f32_e32 v133, 0xbfb8aa3b, v138
	v_exp_f32_e32 v133, v133
	s_nop 0
	v_add_f32_e32 v133, 1.0, v133
	v_rcp_f32_e32 v144, v133
	v_mul_f32_e32 v133, 0xbfb8aa3b, v139
	v_exp_f32_e32 v133, v133
	s_nop 0
	v_add_f32_e32 v133, 1.0, v133
	v_rcp_f32_e32 v145, v133
	v_mul_f32_e32 v133, 0xbfb8aa3b, v134
	v_exp_f32_e32 v133, v133
	v_pk_mul_f32 v[138:139], v[138:139], v[144:145]
	s_nop 0
	v_cvt_pk_bf16_f32 v138, v138, v139
	v_add_f32_e32 v133, 1.0, v133
	v_rcp_f32_e32 v146, v133
	v_mul_f32_e32 v133, 0xbfb8aa3b, v135
	v_exp_f32_e32 v133, v133
	s_nop 0
	v_add_f32_e32 v133, 1.0, v133
	v_rcp_f32_e32 v147, v133
	v_mul_f32_e32 v133, 0xbfb8aa3b, v142
	v_exp_f32_e32 v133, v133
	v_pk_mul_f32 v[134:135], v[134:135], v[146:147]
	s_nop 0
	v_cvt_pk_bf16_f32 v139, v134, v135
	v_add_f32_e32 v133, 1.0, v133
	v_rcp_f32_e32 v144, v133
	v_mul_f32_e32 v133, 0xbfb8aa3b, v143
	v_exp_f32_e32 v133, v133
	v_mov_b32_e32 v134, v185
	v_add_f32_e32 v133, 1.0, v133
	v_rcp_f32_e32 v145, v133
	v_mul_f32_e32 v133, 0xbfb8aa3b, v140
	v_exp_f32_e32 v133, v133
	s_nop 0
	v_add_f32_e32 v133, 1.0, v133
	v_rcp_f32_e32 v146, v133
	v_mul_f32_e32 v133, 0xbfb8aa3b, v141
	v_exp_f32_e32 v133, v133
	s_nop 0
	v_add_f32_e32 v133, 1.0, v133
	v_rcp_f32_e32 v147, v133
	s_nop 0
	v_pk_mul_f32 v[146:147], v[140:141], v[146:147]
	v_pk_mul_f32 v[140:141], v[142:143], v[144:145]
	v_pk_mul_f32 v[144:145], v[72:73], v[134:135] op_sel_hi:[1,0]
	v_cvt_pk_bf16_f32 v140, v140, v141
	v_cvt_pk_bf16_f32 v141, v146, v147
	global_store_dwordx4 v[130:131], v[138:141], off offset:256
	v_pk_mul_f32 v[142:143], v[74:75], v[134:135] op_sel_hi:[1,0]
	v_lshl_add_u64 v[130:131], v[128:129], 0, s[8:9]
	v_pk_mul_f32 v[140:141], v[76:77], v[134:135] op_sel_hi:[1,0]
	v_pk_mul_f32 v[138:139], v[78:79], v[134:135] op_sel_hi:[1,0]
	v_mul_f32_e32 v133, 0xbfb8aa3b, v140
	v_exp_f32_e32 v133, v133
	s_mov_b32 s8, 0x28530000
	v_add_f32_e32 v133, 1.0, v133
	v_rcp_f32_e32 v146, v133
	v_mul_f32_e32 v133, 0xbfb8aa3b, v141
	v_exp_f32_e32 v133, v133
	s_nop 0
	v_add_f32_e32 v133, 1.0, v133
	v_rcp_f32_e32 v147, v133
	v_mul_f32_e32 v133, 0xbfb8aa3b, v138
	v_exp_f32_e32 v133, v133
	s_nop 0
	v_add_f32_e32 v133, 1.0, v133
	v_rcp_f32_e32 v148, v133
	v_mul_f32_e32 v133, 0xbfb8aa3b, v139
	v_exp_f32_e32 v133, v133
	s_nop 0
	v_add_f32_e32 v133, 1.0, v133
	v_rcp_f32_e32 v149, v133
	v_mul_f32_e32 v133, 0xbfb8aa3b, v144
	v_exp_f32_e32 v133, v133
	v_pk_mul_f32 v[148:149], v[138:139], v[148:149]
	v_pk_mul_f32 v[138:139], v[140:141], v[146:147]
	v_add_f32_e32 v133, 1.0, v133
	v_rcp_f32_e32 v140, v133
	v_mul_f32_e32 v133, 0xbfb8aa3b, v145
	v_exp_f32_e32 v133, v133
	v_cvt_pk_bf16_f32 v138, v138, v139
	v_cvt_pk_bf16_f32 v139, v148, v149
	v_add_f32_e32 v133, 1.0, v133
	v_rcp_f32_e32 v141, v133
	v_mul_f32_e32 v133, 0xbfb8aa3b, v142
	v_exp_f32_e32 v133, v133
	v_pk_mul_f32 v[140:141], v[144:145], v[140:141]
	s_nop 0
	v_cvt_pk_bf16_f32 v140, v140, v141
	v_add_f32_e32 v133, 1.0, v133
	v_rcp_f32_e32 v146, v133
	v_mul_f32_e32 v133, 0xbfb8aa3b, v143
	v_exp_f32_e32 v133, v133
	s_nop 0
	v_add_f32_e32 v133, 1.0, v133
	v_rcp_f32_e32 v147, v133
	s_nop 0
	v_pk_mul_f32 v[142:143], v[142:143], v[146:147]
	s_nop 0
	v_cvt_pk_bf16_f32 v141, v142, v143
	v_add_co_u32_e32 v142, vcc, s8, v128
	s_mov_b64 s[8:9], 0x28580000
	s_nop 0
	v_addc_co_u32_e32 v143, vcc, 0, v129, vcc
	global_store_dwordx4 v[142:143], v[138:141], off
	v_pk_mul_f32 v[142:143], v[66:67], v[134:135] op_sel_hi:[1,0]
	s_nop 0
	v_pk_mul_f32 v[140:141], v[68:69], v[134:135] op_sel_hi:[1,0]
	v_pk_mul_f32 v[138:139], v[70:71], v[134:135] op_sel_hi:[1,0]
	v_mul_f32_e32 v133, 0xbfb8aa3b, v140
	v_exp_f32_e32 v133, v133
	v_pk_mul_f32 v[134:135], v[64:65], v[134:135] op_sel_hi:[1,0]
	v_add_f32_e32 v133, 1.0, v133
	v_rcp_f32_e32 v144, v133
	v_mul_f32_e32 v133, 0xbfb8aa3b, v141
	v_exp_f32_e32 v133, v133
	s_nop 0
	v_add_f32_e32 v133, 1.0, v133
; __device__ __forceinline__ float sigmoid_f(float x) { return __builtin_amdgcn_rcpf(1.f + __expf(-x)); }
; __device__ __forceinline__ f32x4 sigmoid4(f32x4 v) { return (f32x4){sigmoid_f(v[0]), sigmoid_f(v[1]), sigmoid_f(v[2]), sigmoid_f(v[3])}; }
; __device__ __forceinline__ f32x4 silu4(f32x4 v) { return v * sigmoid4(v); }
;     template <int MODE, bool HEADMAJOR>
;     __device__ __forceinline__ void plain(const f32x4 (&acc)[2][2][4][2], const float (&rs)[2][4], bf16_t* base, int row0, int pl, int wc, int fq) const {
; #pragma unroll
;         for (int ai = 0; ai < 2; ++ai)
; #pragma unroll
;             for (int m = 0; m < 4; ++m) { const int row = row0 + ai * 128 + m * 16;
; #pragma unroll
;                 for (int bj = 0; bj < 2; ++bj) { f32x4 v0 = acc[ai][bj][m][0] * rs[ai][m], v1 = acc[ai][bj][m][1] * rs[ai][m];
;                     if (MODE == 1) { v0 = v0 * 0.08838834764831845f; v1 = v1 * 0.08838834764831845f; }
;                     if (MODE == 2) { v0 = silu4(v0); v1 = silu4(v1); }
;                     if (MODE == 3) { v0 = sigmoid4(v0); v1 = sigmoid4(v1); }
;                     bf16_t* ptr = HEADMAJOR ? base + ((size_t)(pl * 2 + bj) * S + row) * 128 + 32 * wc + 8 * fq
;                                             : base + (size_t)row * DM + pl * 256 + bj * 128 + 32 * wc + 8 * fq;
;                     *(u32x4*)ptr = pack8bf(v0, v1); }
;                 asm volatile("" ::: "memory"); }
	v_rcp_f32_e32 v145, v133
	v_mul_f32_e32 v133, 0xbfb8aa3b, v138
	v_exp_f32_e32 v133, v133
	s_nop 0
	v_add_f32_e32 v133, 1.0, v133
	v_rcp_f32_e32 v146, v133
	v_mul_f32_e32 v133, 0xbfb8aa3b, v139
	v_exp_f32_e32 v133, v133
	s_nop 0
	v_add_f32_e32 v133, 1.0, v133
	v_rcp_f32_e32 v147, v133
	v_mul_f32_e32 v133, 0xbfb8aa3b, v134
	v_exp_f32_e32 v133, v133
	v_pk_mul_f32 v[146:147], v[138:139], v[146:147]
	v_pk_mul_f32 v[138:139], v[140:141], v[144:145]
	v_add_f32_e32 v133, 1.0, v133
	v_rcp_f32_e32 v140, v133
	v_mul_f32_e32 v133, 0xbfb8aa3b, v135
	v_exp_f32_e32 v133, v133
	v_cvt_pk_bf16_f32 v138, v138, v139
	v_cvt_pk_bf16_f32 v139, v146, v147
	v_add_f32_e32 v133, 1.0, v133
	v_rcp_f32_e32 v141, v133
	v_mul_f32_e32 v133, 0xbfb8aa3b, v142
	v_exp_f32_e32 v133, v133
	v_pk_mul_f32 v[134:135], v[134:135], v[140:141]
	s_nop 0
	v_cvt_pk_bf16_f32 v140, v134, v135
	v_add_f32_e32 v133, 1.0, v133
	v_rcp_f32_e32 v144, v133
	v_mul_f32_e32 v133, 0xbfb8aa3b, v143
	v_exp_f32_e32 v133, v133
	v_pk_mul_f32 v[134:135], v[62:63], v[180:181] op_sel_hi:[1,0]
	v_add_f32_e32 v133, 1.0, v133
	v_rcp_f32_e32 v145, v133
	s_nop 0
	v_pk_mul_f32 v[142:143], v[142:143], v[144:145]
	s_nop 0
	v_cvt_pk_bf16_f32 v141, v142, v143
	global_store_dwordx4 v[130:131], v[138:141], off offset:256
	v_pk_mul_f32 v[142:143], v[56:57], v[180:181] op_sel_hi:[1,0]
	v_lshl_add_u64 v[130:131], v[128:129], 0, s[8:9]
	v_pk_mul_f32 v[138:139], v[60:61], v[180:181] op_sel_hi:[1,0]
	v_pk_mul_f32 v[140:141], v[58:59], v[180:181] op_sel_hi:[1,0]
	v_mul_f32_e32 v133, 0xbfb8aa3b, v138
	v_exp_f32_e32 v133, v133
	s_mov_b32 s8, 0x28580000
	v_add_f32_e32 v133, 1.0, v133
	v_rcp_f32_e32 v144, v133
	v_mul_f32_e32 v133, 0xbfb8aa3b, v139
	v_exp_f32_e32 v133, v133
	s_nop 0
	v_add_f32_e32 v133, 1.0, v133
	v_rcp_f32_e32 v145, v133
	v_mul_f32_e32 v133, 0xbfb8aa3b, v134
	v_exp_f32_e32 v133, v133
	v_pk_mul_f32 v[138:139], v[138:139], v[144:145]
	s_nop 0
	v_cvt_pk_bf16_f32 v138, v138, v139
	v_add_f32_e32 v133, 1.0, v133
	v_rcp_f32_e32 v146, v133
	v_mul_f32_e32 v133, 0xbfb8aa3b, v135
	v_exp_f32_e32 v133, v133
	s_nop 0
	v_add_f32_e32 v133, 1.0, v133
	v_rcp_f32_e32 v147, v133
	v_mul_f32_e32 v133, 0xbfb8aa3b, v142
	v_exp_f32_e32 v133, v133
	v_pk_mul_f32 v[134:135], v[134:135], v[146:147]
	s_nop 0
	v_cvt_pk_bf16_f32 v139, v134, v135
	v_add_f32_e32 v133, 1.0, v133
	v_rcp_f32_e32 v144, v133
	v_mul_f32_e32 v133, 0xbfb8aa3b, v143
	v_exp_f32_e32 v133, v133
	v_add_co_u32_e32 v134, vcc, s8, v128
	s_mov_b64 s[8:9], 0x28590000
	v_add_f32_e32 v133, 1.0, v133
	v_rcp_f32_e32 v145, v133
	v_mul_f32_e32 v133, 0xbfb8aa3b, v140
	v_exp_f32_e32 v133, v133
	v_addc_co_u32_e32 v135, vcc, 0, v129, vcc
	v_add_f32_e32 v133, 1.0, v133
	v_rcp_f32_e32 v146, v133
	v_mul_f32_e32 v133, 0xbfb8aa3b, v141
	v_exp_f32_e32 v133, v133
	s_nop 0
	v_add_f32_e32 v133, 1.0, v133
	v_rcp_f32_e32 v147, v133
	s_nop 0
	v_pk_mul_f32 v[146:147], v[140:141], v[146:147]
	v_pk_mul_f32 v[140:141], v[142:143], v[144:145]
	v_pk_mul_f32 v[142:143], v[48:49], v[180:181] op_sel_hi:[1,0]
	v_cvt_pk_bf16_f32 v140, v140, v141
	v_cvt_pk_bf16_f32 v141, v146, v147
	global_store_dwordx4 v[134:135], v[138:141], off
	v_pk_mul_f32 v[134:135], v[54:55], v[180:181] op_sel_hi:[1,0]
	s_nop 0
	v_pk_mul_f32 v[138:139], v[52:53], v[180:181] op_sel_hi:[1,0]
	v_pk_mul_f32 v[140:141], v[50:51], v[180:181] op_sel_hi:[1,0]
	v_mul_f32_e32 v133, 0xbfb8aa3b, v138
	v_exp_f32_e32 v133, v133
	s_nop 0
	v_add_f32_e32 v133, 1.0, v133
	v_rcp_f32_e32 v144, v133
	v_mul_f32_e32 v133, 0xbfb8aa3b, v139
	v_exp_f32_e32 v133, v133
	s_nop 0
	v_add_f32_e32 v133, 1.0, v133
	v_rcp_f32_e32 v145, v133
	v_mul_f32_e32 v133, 0xbfb8aa3b, v134
	v_exp_f32_e32 v133, v133
	v_pk_mul_f32 v[138:139], v[138:139], v[144:145]
	s_nop 0
	v_cvt_pk_bf16_f32 v138, v138, v139
	v_add_f32_e32 v133, 1.0, v133
	v_rcp_f32_e32 v146, v133
	v_mul_f32_e32 v133, 0xbfb8aa3b, v135
	v_exp_f32_e32 v133, v133
	s_nop 0
	v_add_f32_e32 v133, 1.0, v133
	v_rcp_f32_e32 v147, v133
	v_mul_f32_e32 v133, 0xbfb8aa3b, v142
	v_exp_f32_e32 v133, v133
	v_pk_mul_f32 v[134:135], v[134:135], v[146:147]
	s_nop 0
	v_cvt_pk_bf16_f32 v139, v134, v135
	v_add_f32_e32 v133, 1.0, v133
	v_rcp_f32_e32 v144, v133
	v_mul_f32_e32 v133, 0xbfb8aa3b, v143
	v_exp_f32_e32 v133, v133
	v_mov_b32_e32 v134, v181
	v_add_f32_e32 v133, 1.0, v133
	v_rcp_f32_e32 v145, v133
	v_mul_f32_e32 v133, 0xbfb8aa3b, v140
	v_exp_f32_e32 v133, v133
	s_nop 0
	v_add_f32_e32 v133, 1.0, v133
	v_rcp_f32_e32 v146, v133
	v_mul_f32_e32 v133, 0xbfb8aa3b, v141
	v_exp_f32_e32 v133, v133
	s_nop 0
	v_add_f32_e32 v133, 1.0, v133
	v_rcp_f32_e32 v147, v133
	s_nop 0
	v_pk_mul_f32 v[146:147], v[140:141], v[146:147]
	v_pk_mul_f32 v[140:141], v[142:143], v[144:145]
	v_pk_mul_f32 v[144:145], v[40:41], v[134:135] op_sel_hi:[1,0]
	v_cvt_pk_bf16_f32 v140, v140, v141
	v_cvt_pk_bf16_f32 v141, v146, v147
	global_store_dwordx4 v[130:131], v[138:141], off offset:256
	v_pk_mul_f32 v[142:143], v[42:43], v[134:135] op_sel_hi:[1,0]
	v_lshl_add_u64 v[130:131], v[128:129], 0, s[8:9]
	v_pk_mul_f32 v[140:141], v[44:45], v[134:135] op_sel_hi:[1,0]
	v_pk_mul_f32 v[138:139], v[46:47], v[134:135] op_sel_hi:[1,0]
	v_mul_f32_e32 v133, 0xbfb8aa3b, v140
	v_exp_f32_e32 v133, v133
	s_mov_b32 s8, 0x28590000
	v_add_f32_e32 v133, 1.0, v133
	v_rcp_f32_e32 v146, v133
	v_mul_f32_e32 v133, 0xbfb8aa3b, v141
	v_exp_f32_e32 v133, v133
	s_nop 0
	v_add_f32_e32 v133, 1.0, v133
	v_rcp_f32_e32 v147, v133
	v_mul_f32_e32 v133, 0xbfb8aa3b, v138
	v_exp_f32_e32 v133, v133
	s_nop 0
	v_add_f32_e32 v133, 1.0, v133
	v_rcp_f32_e32 v148, v133
	v_mul_f32_e32 v133, 0xbfb8aa3b, v139
	v_exp_f32_e32 v133, v133
	s_nop 0
	v_add_f32_e32 v133, 1.0, v133
	v_rcp_f32_e32 v149, v133
	v_mul_f32_e32 v133, 0xbfb8aa3b, v144
; __device__ __forceinline__ float sigmoid_f(float x) { return __builtin_amdgcn_rcpf(1.f + __expf(-x)); }
; __device__ __forceinline__ f32x4 sigmoid4(f32x4 v) { return (f32x4){sigmoid_f(v[0]), sigmoid_f(v[1]), sigmoid_f(v[2]), sigmoid_f(v[3])}; }
; __device__ __forceinline__ f32x4 silu4(f32x4 v) { return v * sigmoid4(v); }
;     template <int MODE, bool HEADMAJOR>
;     __device__ __forceinline__ void plain(const f32x4 (&acc)[2][2][4][2], const float (&rs)[2][4], bf16_t* base, int row0, int pl, int wc, int fq) const {
; #pragma unroll
;         for (int ai = 0; ai < 2; ++ai)
; #pragma unroll
;             for (int m = 0; m < 4; ++m) { const int row = row0 + ai * 128 + m * 16;
; #pragma unroll
;                 for (int bj = 0; bj < 2; ++bj) { f32x4 v0 = acc[ai][bj][m][0] * rs[ai][m], v1 = acc[ai][bj][m][1] * rs[ai][m];
;                     if (MODE == 1) { v0 = v0 * 0.08838834764831845f; v1 = v1 * 0.08838834764831845f; }
;                     if (MODE == 2) { v0 = silu4(v0); v1 = silu4(v1); }
;                     if (MODE == 3) { v0 = sigmoid4(v0); v1 = sigmoid4(v1); }
;                     bf16_t* ptr = HEADMAJOR ? base + ((size_t)(pl * 2 + bj) * S + row) * 128 + 32 * wc + 8 * fq
;                                             : base + (size_t)row * DM + pl * 256 + bj * 128 + 32 * wc + 8 * fq;
;                     *(u32x4*)ptr = pack8bf(v0, v1); }
;                 asm volatile("" ::: "memory"); }
	v_exp_f32_e32 v133, v133
	v_pk_mul_f32 v[148:149], v[138:139], v[148:149]
	v_pk_mul_f32 v[138:139], v[140:141], v[146:147]
	v_add_f32_e32 v133, 1.0, v133
	v_rcp_f32_e32 v140, v133
	v_mul_f32_e32 v133, 0xbfb8aa3b, v145
	v_exp_f32_e32 v133, v133
	v_cvt_pk_bf16_f32 v138, v138, v139
	v_cvt_pk_bf16_f32 v139, v148, v149
	v_add_f32_e32 v133, 1.0, v133
	v_rcp_f32_e32 v141, v133
	v_mul_f32_e32 v133, 0xbfb8aa3b, v142
	v_exp_f32_e32 v133, v133
	v_pk_mul_f32 v[140:141], v[144:145], v[140:141]
	s_nop 0
	v_cvt_pk_bf16_f32 v140, v140, v141
	v_add_f32_e32 v133, 1.0, v133
	v_rcp_f32_e32 v146, v133
	v_mul_f32_e32 v133, 0xbfb8aa3b, v143
	v_exp_f32_e32 v133, v133
	s_nop 0
	v_add_f32_e32 v133, 1.0, v133
	v_rcp_f32_e32 v147, v133
	s_nop 0
	v_pk_mul_f32 v[142:143], v[142:143], v[146:147]
	s_nop 0
	v_cvt_pk_bf16_f32 v141, v142, v143
	v_add_co_u32_e32 v142, vcc, s8, v128
	s_mov_b64 s[8:9], 0x285a0000
	s_nop 0
	v_addc_co_u32_e32 v143, vcc, 0, v129, vcc
	global_store_dwordx4 v[142:143], v[138:141], off
	v_pk_mul_f32 v[142:143], v[34:35], v[134:135] op_sel_hi:[1,0]
	s_nop 0
	v_pk_mul_f32 v[140:141], v[36:37], v[134:135] op_sel_hi:[1,0]
	v_pk_mul_f32 v[138:139], v[38:39], v[134:135] op_sel_hi:[1,0]
	v_mul_f32_e32 v133, 0xbfb8aa3b, v140
	v_exp_f32_e32 v133, v133
	v_pk_mul_f32 v[134:135], v[32:33], v[134:135] op_sel_hi:[1,0]
	v_add_f32_e32 v133, 1.0, v133
	v_rcp_f32_e32 v144, v133
	v_mul_f32_e32 v133, 0xbfb8aa3b, v141
	v_exp_f32_e32 v133, v133
	s_nop 0
	v_add_f32_e32 v133, 1.0, v133
	v_rcp_f32_e32 v145, v133
	v_mul_f32_e32 v133, 0xbfb8aa3b, v138
	v_exp_f32_e32 v133, v133
	s_nop 0
	v_add_f32_e32 v133, 1.0, v133
	v_rcp_f32_e32 v146, v133
	v_mul_f32_e32 v133, 0xbfb8aa3b, v139
	v_exp_f32_e32 v133, v133
	s_nop 0
	v_add_f32_e32 v133, 1.0, v133
	v_rcp_f32_e32 v147, v133
	v_mul_f32_e32 v133, 0xbfb8aa3b, v134
	v_exp_f32_e32 v133, v133
	v_pk_mul_f32 v[146:147], v[138:139], v[146:147]
	v_pk_mul_f32 v[138:139], v[140:141], v[144:145]
	v_add_f32_e32 v133, 1.0, v133
	v_rcp_f32_e32 v140, v133
	v_mul_f32_e32 v133, 0xbfb8aa3b, v135
	v_exp_f32_e32 v133, v133
	v_cvt_pk_bf16_f32 v138, v138, v139
	v_cvt_pk_bf16_f32 v139, v146, v147
	v_add_f32_e32 v133, 1.0, v133
	v_rcp_f32_e32 v141, v133
	v_mul_f32_e32 v133, 0xbfb8aa3b, v142
	v_exp_f32_e32 v133, v133
	v_pk_mul_f32 v[134:135], v[134:135], v[140:141]
	s_nop 0
	v_cvt_pk_bf16_f32 v140, v134, v135
	v_add_f32_e32 v133, 1.0, v133
	v_rcp_f32_e32 v144, v133
	v_mul_f32_e32 v133, 0xbfb8aa3b, v143
	v_exp_f32_e32 v133, v133
	v_pk_mul_f32 v[134:135], v[30:31], v[178:179] op_sel_hi:[1,0]
	v_add_f32_e32 v133, 1.0, v133
	v_rcp_f32_e32 v145, v133
	s_nop 0
	v_pk_mul_f32 v[142:143], v[142:143], v[144:145]
	s_nop 0
	v_cvt_pk_bf16_f32 v141, v142, v143
	global_store_dwordx4 v[130:131], v[138:141], off offset:256
	v_pk_mul_f32 v[142:143], v[24:25], v[178:179] op_sel_hi:[1,0]
	v_lshl_add_u64 v[130:131], v[128:129], 0, s[8:9]
	v_pk_mul_f32 v[138:139], v[28:29], v[178:179] op_sel_hi:[1,0]
	v_pk_mul_f32 v[140:141], v[26:27], v[178:179] op_sel_hi:[1,0]
	v_mul_f32_e32 v133, 0xbfb8aa3b, v138
	v_exp_f32_e32 v133, v133
	s_mov_b32 s8, 0x285a0000
	v_add_f32_e32 v133, 1.0, v133
	v_rcp_f32_e32 v144, v133
	v_mul_f32_e32 v133, 0xbfb8aa3b, v139
	v_exp_f32_e32 v133, v133
	s_nop 0
	v_add_f32_e32 v133, 1.0, v133
	v_rcp_f32_e32 v145, v133
	v_mul_f32_e32 v133, 0xbfb8aa3b, v134
	v_exp_f32_e32 v133, v133
	v_pk_mul_f32 v[138:139], v[138:139], v[144:145]
	s_nop 0
	v_cvt_pk_bf16_f32 v138, v138, v139
	v_add_f32_e32 v133, 1.0, v133
	v_rcp_f32_e32 v146, v133
	v_mul_f32_e32 v133, 0xbfb8aa3b, v135
	v_exp_f32_e32 v133, v133
	s_nop 0
	v_add_f32_e32 v133, 1.0, v133
	v_rcp_f32_e32 v147, v133
	v_mul_f32_e32 v133, 0xbfb8aa3b, v142
	v_exp_f32_e32 v133, v133
	v_pk_mul_f32 v[134:135], v[134:135], v[146:147]
	s_nop 0
	v_cvt_pk_bf16_f32 v139, v134, v135
	v_add_f32_e32 v133, 1.0, v133
	v_rcp_f32_e32 v144, v133
	v_mul_f32_e32 v133, 0xbfb8aa3b, v143
	v_exp_f32_e32 v133, v133
	v_add_co_u32_e32 v134, vcc, s8, v128
	s_mov_b64 s[8:9], 0x285b0000
	v_add_f32_e32 v133, 1.0, v133
	v_rcp_f32_e32 v145, v133
	v_mul_f32_e32 v133, 0xbfb8aa3b, v140
	v_exp_f32_e32 v133, v133
	v_addc_co_u32_e32 v135, vcc, 0, v129, vcc
	v_add_f32_e32 v133, 1.0, v133
	v_rcp_f32_e32 v146, v133
	v_mul_f32_e32 v133, 0xbfb8aa3b, v141
	v_exp_f32_e32 v133, v133
	s_nop 0
	v_add_f32_e32 v133, 1.0, v133
	v_rcp_f32_e32 v147, v133
	s_nop 0
	v_pk_mul_f32 v[146:147], v[140:141], v[146:147]
	v_pk_mul_f32 v[140:141], v[142:143], v[144:145]
	v_pk_mul_f32 v[142:143], v[16:17], v[178:179] op_sel_hi:[1,0]
	v_cvt_pk_bf16_f32 v140, v140, v141
	v_cvt_pk_bf16_f32 v141, v146, v147
	global_store_dwordx4 v[134:135], v[138:141], off
	v_pk_mul_f32 v[134:135], v[22:23], v[178:179] op_sel_hi:[1,0]
	s_nop 0
	v_pk_mul_f32 v[138:139], v[20:21], v[178:179] op_sel_hi:[1,0]
	v_pk_mul_f32 v[140:141], v[18:19], v[178:179] op_sel_hi:[1,0]
	v_mul_f32_e32 v133, 0xbfb8aa3b, v138
	v_exp_f32_e32 v133, v133
	s_nop 0
	v_add_f32_e32 v133, 1.0, v133
; __device__ __forceinline__ float sigmoid_f(float x) { return __builtin_amdgcn_rcpf(1.f + __expf(-x)); }
; __device__ __forceinline__ f32x4 sigmoid4(f32x4 v) { return (f32x4){sigmoid_f(v[0]), sigmoid_f(v[1]), sigmoid_f(v[2]), sigmoid_f(v[3])}; }
; __device__ __forceinline__ f32x4 silu4(f32x4 v) { return v * sigmoid4(v); }
;     template <int MODE, bool HEADMAJOR>
;     __device__ __forceinline__ void plain(const f32x4 (&acc)[2][2][4][2], const float (&rs)[2][4], bf16_t* base, int row0, int pl, int wc, int fq) const {
; #pragma unroll
;         for (int ai = 0; ai < 2; ++ai)
; #pragma unroll
;             for (int m = 0; m < 4; ++m) { const int row = row0 + ai * 128 + m * 16;
; #pragma unroll
;                 for (int bj = 0; bj < 2; ++bj) { f32x4 v0 = acc[ai][bj][m][0] * rs[ai][m], v1 = acc[ai][bj][m][1] * rs[ai][m];
;                     if (MODE == 1) { v0 = v0 * 0.08838834764831845f; v1 = v1 * 0.08838834764831845f; }
;                     if (MODE == 2) { v0 = silu4(v0); v1 = silu4(v1); }
;                     if (MODE == 3) { v0 = sigmoid4(v0); v1 = sigmoid4(v1); }
;                     bf16_t* ptr = HEADMAJOR ? base + ((size_t)(pl * 2 + bj) * S + row) * 128 + 32 * wc + 8 * fq
;                                             : base + (size_t)row * DM + pl * 256 + bj * 128 + 32 * wc + 8 * fq;
;                     *(u32x4*)ptr = pack8bf(v0, v1); }
;                 asm volatile("" ::: "memory"); }
	v_rcp_f32_e32 v144, v133
	v_mul_f32_e32 v133, 0xbfb8aa3b, v139
	v_exp_f32_e32 v133, v133
	s_nop 0
	v_add_f32_e32 v133, 1.0, v133
	v_rcp_f32_e32 v145, v133
	v_mul_f32_e32 v133, 0xbfb8aa3b, v134
	v_exp_f32_e32 v133, v133
	v_pk_mul_f32 v[138:139], v[138:139], v[144:145]
	s_nop 0
	v_cvt_pk_bf16_f32 v138, v138, v139
	v_add_f32_e32 v133, 1.0, v133
	v_rcp_f32_e32 v146, v133
	v_mul_f32_e32 v133, 0xbfb8aa3b, v135
	v_exp_f32_e32 v133, v133
	s_nop 0
	v_add_f32_e32 v133, 1.0, v133
	v_rcp_f32_e32 v147, v133
	v_mul_f32_e32 v133, 0xbfb8aa3b, v142
	v_exp_f32_e32 v133, v133
	v_pk_mul_f32 v[134:135], v[134:135], v[146:147]
	s_nop 0
	v_cvt_pk_bf16_f32 v139, v134, v135
	v_add_f32_e32 v133, 1.0, v133
	v_rcp_f32_e32 v144, v133
	v_mul_f32_e32 v133, 0xbfb8aa3b, v143
	v_exp_f32_e32 v133, v133
	v_mov_b32_e32 v134, v179
	v_add_f32_e32 v133, 1.0, v133
	v_rcp_f32_e32 v145, v133
	v_mul_f32_e32 v133, 0xbfb8aa3b, v140
	v_exp_f32_e32 v133, v133
	s_nop 0
	v_add_f32_e32 v133, 1.0, v133
	v_rcp_f32_e32 v146, v133
	v_mul_f32_e32 v133, 0xbfb8aa3b, v141
	v_exp_f32_e32 v133, v133
	s_nop 0
	v_add_f32_e32 v133, 1.0, v133
	v_rcp_f32_e32 v147, v133
	s_nop 0
	v_pk_mul_f32 v[146:147], v[140:141], v[146:147]
	v_pk_mul_f32 v[140:141], v[142:143], v[144:145]
	v_pk_mul_f32 v[144:145], v[8:9], v[134:135] op_sel_hi:[1,0]
	v_cvt_pk_bf16_f32 v140, v140, v141
	v_cvt_pk_bf16_f32 v141, v146, v147
	global_store_dwordx4 v[130:131], v[138:141], off offset:256
	v_pk_mul_f32 v[142:143], v[10:11], v[134:135] op_sel_hi:[1,0]
	v_lshl_add_u64 v[130:131], v[128:129], 0, s[8:9]
	v_pk_mul_f32 v[140:141], v[12:13], v[134:135] op_sel_hi:[1,0]
	v_pk_mul_f32 v[138:139], v[14:15], v[134:135] op_sel_hi:[1,0]
	v_mul_f32_e32 v133, 0xbfb8aa3b, v140
	v_exp_f32_e32 v133, v133
	s_mov_b32 s8, 0x285b0000
	v_add_co_u32_e32 v128, vcc, s8, v128
	v_add_f32_e32 v133, 1.0, v133
	v_rcp_f32_e32 v146, v133
	v_mul_f32_e32 v133, 0xbfb8aa3b, v141
	v_exp_f32_e32 v133, v133
	v_addc_co_u32_e32 v129, vcc, 0, v129, vcc
	v_add_f32_e32 v133, 1.0, v133
	v_rcp_f32_e32 v147, v133
	v_mul_f32_e32 v133, 0xbfb8aa3b, v138
	v_exp_f32_e32 v133, v133
	s_nop 0
	v_add_f32_e32 v133, 1.0, v133
	v_rcp_f32_e32 v148, v133
	v_mul_f32_e32 v133, 0xbfb8aa3b, v139
	v_exp_f32_e32 v133, v133
	s_nop 0
	v_add_f32_e32 v133, 1.0, v133
	v_rcp_f32_e32 v149, v133
	v_mul_f32_e32 v133, 0xbfb8aa3b, v144
	v_exp_f32_e32 v133, v133
	v_pk_mul_f32 v[148:149], v[138:139], v[148:149]
	v_pk_mul_f32 v[138:139], v[140:141], v[146:147]
	v_add_f32_e32 v133, 1.0, v133
	v_rcp_f32_e32 v140, v133
	v_mul_f32_e32 v133, 0xbfb8aa3b, v145
	v_exp_f32_e32 v133, v133
	v_cvt_pk_bf16_f32 v138, v138, v139
	v_cvt_pk_bf16_f32 v139, v148, v149
	v_add_f32_e32 v133, 1.0, v133
	v_rcp_f32_e32 v141, v133
	v_mul_f32_e32 v133, 0xbfb8aa3b, v142
	v_exp_f32_e32 v133, v133
	v_pk_mul_f32 v[140:141], v[144:145], v[140:141]
	s_nop 0
	v_cvt_pk_bf16_f32 v140, v140, v141
	v_add_f32_e32 v133, 1.0, v133
	v_rcp_f32_e32 v146, v133
	v_mul_f32_e32 v133, 0xbfb8aa3b, v143
	v_exp_f32_e32 v133, v133
	s_nop 0
	v_add_f32_e32 v133, 1.0, v133
	v_rcp_f32_e32 v147, v133
	s_nop 0
	v_pk_mul_f32 v[142:143], v[142:143], v[146:147]
	s_nop 0
	v_cvt_pk_bf16_f32 v141, v142, v143
	global_store_dwordx4 v[128:129], v[138:141], off
	v_pk_mul_f32 v[128:129], v[6:7], v[134:135] op_sel_hi:[1,0]
	s_nop 0
	v_pk_mul_f32 v[138:139], v[4:5], v[134:135] op_sel_hi:[1,0]
	v_pk_mul_f32 v[140:141], v[2:3], v[134:135] op_sel_hi:[1,0]
	v_mul_f32_e32 v133, 0xbfb8aa3b, v138
	v_exp_f32_e32 v133, v133
	v_pk_mul_f32 v[134:135], v[0:1], v[134:135] op_sel_hi:[1,0]
	v_add_f32_e32 v133, 1.0, v133
	v_rcp_f32_e32 v142, v133
	v_mul_f32_e32 v133, 0xbfb8aa3b, v139
	v_exp_f32_e32 v133, v133
	s_nop 0
	v_add_f32_e32 v133, 1.0, v133
	v_rcp_f32_e32 v143, v133
	v_mul_f32_e32 v133, 0xbfb8aa3b, v128
	v_exp_f32_e32 v133, v133
	v_pk_mul_f32 v[138:139], v[138:139], v[142:143]
	s_nop 0
	v_cvt_pk_bf16_f32 v138, v138, v139
	v_add_f32_e32 v133, 1.0, v133
	v_rcp_f32_e32 v144, v133
	v_mul_f32_e32 v133, 0xbfb8aa3b, v129
	v_exp_f32_e32 v133, v133
	s_nop 0
	v_add_f32_e32 v133, 1.0, v133
	v_rcp_f32_e32 v145, v133
	v_mul_f32_e32 v133, 0xbfb8aa3b, v134
	v_exp_f32_e32 v133, v133
	v_pk_mul_f32 v[128:129], v[128:129], v[144:145]
	s_nop 0
	v_cvt_pk_bf16_f32 v139, v128, v129
	v_add_f32_e32 v133, 1.0, v133
	v_rcp_f32_e32 v142, v133
	v_mul_f32_e32 v133, 0xbfb8aa3b, v135
	v_exp_f32_e32 v133, v133
	s_nop 0
	v_add_f32_e32 v133, 1.0, v133
	v_rcp_f32_e32 v143, v133
	v_mul_f32_e32 v133, 0xbfb8aa3b, v140
	v_exp_f32_e32 v133, v133
	v_pk_mul_f32 v[134:135], v[134:135], v[142:143]
	v_add_f32_e32 v133, 1.0, v133
	v_rcp_f32_e32 v144, v133
	v_mul_f32_e32 v133, 0xbfb8aa3b, v141
	v_exp_f32_e32 v133, v133
	s_nop 0
	v_add_f32_e32 v133, 1.0, v133
	v_rcp_f32_e32 v145, v133
	s_nop 0
	v_pk_mul_f32 v[144:145], v[140:141], v[144:145]
	v_cvt_pk_bf16_f32 v140, v134, v135
	v_cvt_pk_bf16_f32 v141, v144, v145
	global_store_dwordx4 v[130:131], v[138:141], off offset:256

; __device__ __forceinline__ f32x4 sigmoid4(f32x4 v) { return (f32x4){sigmoid_f(v[0]), sigmoid_f(v[1]), sigmoid_f(v[2]), sigmoid_f(v[3])}; }
; __device__ __forceinline__ f32x4 silu4(f32x4 v) { return v * sigmoid4(v); }
;     template <int MODE, bool HEADMAJOR>
;     __device__ __forceinline__ void plain(const f32x4 (&acc)[2][2][4][2], const float (&rs)[2][4], bf16_t* base, int row0, int pl, int wc, int fq) const {
; #pragma unroll
;         for (int ai = 0; ai < 2; ++ai)
; #pragma unroll
;             for (int m = 0; m < 4; ++m) { const int row = row0 + ai * 128 + m * 16;
; #pragma unroll
;                 for (int bj = 0; bj < 2; ++bj) { f32x4 v0 = acc[ai][bj][m][0] * rs[ai][m], v1 = acc[ai][bj][m][1] * rs[ai][m];
;                     if (MODE == 1) { v0 = v0 * 0.08838834764831845f; v1 = v1 * 0.08838834764831845f; }
;                     if (MODE == 2) { v0 = silu4(v0); v1 = silu4(v1); }
;                     if (MODE == 3) { v0 = sigmoid4(v0); v1 = sigmoid4(v1); }
;                     bf16_t* ptr = HEADMAJOR ? base + ((size_t)(pl * 2 + bj) * S + row) * 128 + 32 * wc + 8 * fq
;                                             : base + (size_t)row * DM + pl * 256 + bj * 128 + 32 * wc + 8 * fq;
;                     *(u32x4*)ptr = pack8bf(v0, v1); }
;                 asm volatile("" ::: "memory"); }
;     __device__ __forceinline__ void operator()(const f32x4 (&acc)[2][2][4][2], const pg8::Unit& u, int wr, int wc, int fr_, int fq_) const {
;     ...
;             case 2: plain<0, true>(acc, rs, (bf16_t*)(ws + WS_VDA), row0, pl, wc, fq); break;
.LBB0_101:
	s_andn2_b64 vcc, exec, s[8:9]
	s_cbranch_vccnz .LBB0_103
	s_lshl_b32 s22, s25, 14
	s_lshl_b32 s8, s4, 1
	s_add_u32 s8, s6, s8
	v_lshlrev_b32_e32 v128, 3, v136
	s_addc_u32 s9, s7, 0
	v_ashrrev_i32_e32 v129, 31, v128
	v_ashrrev_i32_e32 v183, 31, v182
	v_lshl_add_u64 v[128:129], v[128:129], 1, s[8:9]
	s_mov_b64 s[8:9], 0x20500000
	v_lshl_add_u64 v[138:139], v[182:183], 0, s[22:23]
	v_lshl_add_u64 v[128:129], v[128:129], 0, s[8:9]
	s_waitcnt lgkmcnt(0)
	v_pk_mul_f32 v[130:131], v[126:127], v[186:187] op_sel_hi:[1,0]
	v_pk_mul_f32 v[134:135], v[124:125], v[186:187] op_sel_hi:[1,0]
	v_pk_mul_f32 v[142:143], v[122:123], v[186:187] op_sel_hi:[1,0]
	v_pk_mul_f32 v[140:141], v[120:121], v[186:187] op_sel_hi:[1,0]
	v_lshlrev_b64 v[138:139], 8, v[138:139]
	v_lshl_add_u64 v[144:145], v[128:129], 0, v[138:139]
	v_cvt_pk_bf16_f32 v138, v134, v135
	v_cvt_pk_bf16_f32 v139, v130, v131
	v_cvt_pk_bf16_f32 v140, v140, v141
	v_cvt_pk_bf16_f32 v141, v142, v143
	s_or_b32 s8, s22, 0x2000
	s_mov_b32 s9, s23
	global_store_dwordx4 v[144:145], v[138:141], off
	v_pk_mul_f32 v[130:131], v[118:119], v[186:187] op_sel_hi:[1,0]
	v_pk_mul_f32 v[134:135], v[116:117], v[186:187] op_sel_hi:[1,0]
	v_lshl_add_u64 v[138:139], v[182:183], 0, s[8:9]
	v_lshlrev_b64 v[138:139], 8, v[138:139]
	v_lshl_add_u64 v[144:145], v[128:129], 0, v[138:139]
	v_cvt_pk_bf16_f32 v139, v130, v131
	v_add_u32_e32 v130, 16, v182
	v_pk_mul_f32 v[142:143], v[114:115], v[186:187] op_sel_hi:[1,0]
	v_pk_mul_f32 v[140:141], v[112:113], v[186:187] op_sel_hi:[1,0]
	v_ashrrev_i32_e32 v131, 31, v130
	v_cvt_pk_bf16_f32 v138, v134, v135
	v_cvt_pk_bf16_f32 v140, v140, v141
	v_cvt_pk_bf16_f32 v141, v142, v143
	v_mov_b32_e32 v134, v187
	v_lshl_add_u64 v[146:147], v[130:131], 0, s[22:23]
	global_store_dwordx4 v[144:145], v[138:141], off
	v_pk_mul_f32 v[142:143], v[106:107], v[134:135] op_sel_hi:[1,0]
	v_pk_mul_f32 v[144:145], v[104:105], v[134:135] op_sel_hi:[1,0]
	v_pk_mul_f32 v[140:141], v[110:111], v[134:135] op_sel_hi:[1,0]
	v_pk_mul_f32 v[138:139], v[108:109], v[134:135] op_sel_hi:[1,0]
	v_lshlrev_b64 v[146:147], 8, v[146:147]
	v_lshl_add_u64 v[146:147], v[128:129], 0, v[146:147]
	v_cvt_pk_bf16_f32 v138, v138, v139
	v_cvt_pk_bf16_f32 v139, v140, v141
	v_cvt_pk_bf16_f32 v140, v144, v145
	v_cvt_pk_bf16_f32 v141, v142, v143
	v_lshl_add_u64 v[130:131], v[130:131], 0, s[8:9]
	global_store_dwordx4 v[146:147], v[138:141], off
	v_pk_mul_f32 v[142:143], v[98:99], v[134:135] op_sel_hi:[1,0]
	v_lshlrev_b64 v[130:131], 8, v[130:131]
	v_pk_mul_f32 v[140:141], v[102:103], v[134:135] op_sel_hi:[1,0]
	v_pk_mul_f32 v[138:139], v[100:101], v[134:135] op_sel_hi:[1,0]
	v_pk_mul_f32 v[134:135], v[96:97], v[134:135] op_sel_hi:[1,0]
	v_lshl_add_u64 v[130:131], v[128:129], 0, v[130:131]
	v_cvt_pk_bf16_f32 v138, v138, v139
	v_cvt_pk_bf16_f32 v139, v140, v141
	v_cvt_pk_bf16_f32 v140, v134, v135
	v_cvt_pk_bf16_f32 v141, v142, v143
	global_store_dwordx4 v[130:131], v[138:141], off
	v_add_u32_e32 v130, 32, v182
	v_ashrrev_i32_e32 v131, 31, v130
	v_lshl_add_u64 v[144:145], v[130:131], 0, s[22:23]
	v_pk_mul_f32 v[134:135], v[94:95], v[184:185] op_sel_hi:[1,0]
	v_pk_mul_f32 v[138:139], v[92:93], v[184:185] op_sel_hi:[1,0]
	v_pk_mul_f32 v[142:143], v[90:91], v[184:185] op_sel_hi:[1,0]
	v_pk_mul_f32 v[140:141], v[88:89], v[184:185] op_sel_hi:[1,0]
	v_lshlrev_b64 v[144:145], 8, v[144:145]
	v_lshl_add_u64 v[144:145], v[128:129], 0, v[144:145]
	v_cvt_pk_bf16_f32 v138, v138, v139
	v_cvt_pk_bf16_f32 v139, v134, v135
	v_cvt_pk_bf16_f32 v140, v140, v141
	v_cvt_pk_bf16_f32 v141, v142, v143
	v_lshl_add_u64 v[130:131], v[130:131], 0, s[8:9]
	global_store_dwordx4 v[144:145], v[138:141], off
	v_pk_mul_f32 v[134:135], v[86:87], v[184:185] op_sel_hi:[1,0]
	v_pk_mul_f32 v[142:143], v[82:83], v[184:185] op_sel_hi:[1,0]
	v_pk_mul_f32 v[138:139], v[84:85], v[184:185] op_sel_hi:[1,0]
	v_pk_mul_f32 v[140:141], v[80:81], v[184:185] op_sel_hi:[1,0]
	v_lshlrev_b64 v[130:131], 8, v[130:131]
	v_lshl_add_u64 v[130:131], v[128:129], 0, v[130:131]
	v_cvt_pk_bf16_f32 v138, v138, v139
	v_cvt_pk_bf16_f32 v139, v134, v135
	v_cvt_pk_bf16_f32 v140, v140, v141
	v_cvt_pk_bf16_f32 v141, v142, v143
	global_store_dwordx4 v[130:131], v[138:141], off
	v_add_u32_e32 v130, 48, v182
	v_ashrrev_i32_e32 v131, 31, v130
	v_mov_b32_e32 v134, v185
	v_lshl_add_u64 v[146:147], v[130:131], 0, s[22:23]
	v_pk_mul_f32 v[140:141], v[78:79], v[134:135] op_sel_hi:[1,0]
	v_pk_mul_f32 v[138:139], v[76:77], v[134:135] op_sel_hi:[1,0]
	v_pk_mul_f32 v[142:143], v[74:75], v[134:135] op_sel_hi:[1,0]
	v_pk_mul_f32 v[144:145], v[72:73], v[134:135] op_sel_hi:[1,0]
	v_lshlrev_b64 v[146:147], 8, v[146:147]
	v_lshl_add_u64 v[146:147], v[128:129], 0, v[146:147]
	v_cvt_pk_bf16_f32 v138, v138, v139
	v_cvt_pk_bf16_f32 v139, v140, v141
	v_cvt_pk_bf16_f32 v140, v144, v145
	v_cvt_pk_bf16_f32 v141, v142, v143
	v_lshl_add_u64 v[130:131], v[130:131], 0, s[8:9]
	global_store_dwordx4 v[146:147], v[138:141], off
	v_pk_mul_f32 v[142:143], v[66:67], v[134:135] op_sel_hi:[1,0]
	v_lshlrev_b64 v[130:131], 8, v[130:131]
	v_pk_mul_f32 v[140:141], v[70:71], v[134:135] op_sel_hi:[1,0]
	v_pk_mul_f32 v[138:139], v[68:69], v[134:135] op_sel_hi:[1,0]
	v_pk_mul_f32 v[134:135], v[64:65], v[134:135] op_sel_hi:[1,0]
	v_lshl_add_u64 v[130:131], v[128:129], 0, v[130:131]
; __device__ __forceinline__ f32x4 sigmoid4(f32x4 v) { return (f32x4){sigmoid_f(v[0]), sigmoid_f(v[1]), sigmoid_f(v[2]), sigmoid_f(v[3])}; }
; __device__ __forceinline__ f32x4 silu4(f32x4 v) { return v * sigmoid4(v); }
;     template <int MODE, bool HEADMAJOR>
;     __device__ __forceinline__ void plain(const f32x4 (&acc)[2][2][4][2], const float (&rs)[2][4], bf16_t* base, int row0, int pl, int wc, int fq) const {
; #pragma unroll
;         for (int ai = 0; ai < 2; ++ai)
; #pragma unroll
;             for (int m = 0; m < 4; ++m) { const int row = row0 + ai * 128 + m * 16;
; #pragma unroll
;                 for (int bj = 0; bj < 2; ++bj) { f32x4 v0 = acc[ai][bj][m][0] * rs[ai][m], v1 = acc[ai][bj][m][1] * rs[ai][m];
;                     if (MODE == 1) { v0 = v0 * 0.08838834764831845f; v1 = v1 * 0.08838834764831845f; }
;                     if (MODE == 2) { v0 = silu4(v0); v1 = silu4(v1); }
;                     if (MODE == 3) { v0 = sigmoid4(v0); v1 = sigmoid4(v1); }
;                     bf16_t* ptr = HEADMAJOR ? base + ((size_t)(pl * 2 + bj) * S + row) * 128 + 32 * wc + 8 * fq
;                                             : base + (size_t)row * DM + pl * 256 + bj * 128 + 32 * wc + 8 * fq;
;                     *(u32x4*)ptr = pack8bf(v0, v1); }
;                 asm volatile("" ::: "memory"); }
;     __device__ __forceinline__ void operator()(const f32x4 (&acc)[2][2][4][2], const pg8::Unit& u, int wr, int wc, int fr_, int fq_) const {
;     ...
;             case 2: plain<0, true>(acc, rs, (bf16_t*)(ws + WS_VDA), row0, pl, wc, fq); break;
	v_cvt_pk_bf16_f32 v138, v138, v139
	v_cvt_pk_bf16_f32 v139, v140, v141
	v_cvt_pk_bf16_f32 v140, v134, v135
	v_cvt_pk_bf16_f32 v141, v142, v143
	global_store_dwordx4 v[130:131], v[138:141], off
	v_add_u32_e32 v130, 0x80, v182
	v_ashrrev_i32_e32 v131, 31, v130
	v_lshl_add_u64 v[144:145], v[130:131], 0, s[22:23]
	v_pk_mul_f32 v[134:135], v[62:63], v[180:181] op_sel_hi:[1,0]
	v_pk_mul_f32 v[138:139], v[60:61], v[180:181] op_sel_hi:[1,0]
	v_pk_mul_f32 v[142:143], v[58:59], v[180:181] op_sel_hi:[1,0]
	v_pk_mul_f32 v[140:141], v[56:57], v[180:181] op_sel_hi:[1,0]
	v_lshlrev_b64 v[144:145], 8, v[144:145]
	v_lshl_add_u64 v[144:145], v[128:129], 0, v[144:145]
	v_cvt_pk_bf16_f32 v138, v138, v139
	v_cvt_pk_bf16_f32 v139, v134, v135
	v_cvt_pk_bf16_f32 v140, v140, v141
	v_cvt_pk_bf16_f32 v141, v142, v143
	v_lshl_add_u64 v[130:131], v[130:131], 0, s[8:9]
	global_store_dwordx4 v[144:145], v[138:141], off
	v_pk_mul_f32 v[134:135], v[54:55], v[180:181] op_sel_hi:[1,0]
	v_pk_mul_f32 v[142:143], v[50:51], v[180:181] op_sel_hi:[1,0]
	v_pk_mul_f32 v[138:139], v[52:53], v[180:181] op_sel_hi:[1,0]
	v_pk_mul_f32 v[140:141], v[48:49], v[180:181] op_sel_hi:[1,0]
	v_lshlrev_b64 v[130:131], 8, v[130:131]
	v_lshl_add_u64 v[130:131], v[128:129], 0, v[130:131]
	v_cvt_pk_bf16_f32 v138, v138, v139
	v_cvt_pk_bf16_f32 v139, v134, v135
	v_cvt_pk_bf16_f32 v140, v140, v141
	v_cvt_pk_bf16_f32 v141, v142, v143
	global_store_dwordx4 v[130:131], v[138:141], off
	v_add_u32_e32 v130, 0x90, v182
	v_ashrrev_i32_e32 v131, 31, v130
	v_mov_b32_e32 v134, v181
	v_lshl_add_u64 v[146:147], v[130:131], 0, s[22:23]
	v_pk_mul_f32 v[140:141], v[46:47], v[134:135] op_sel_hi:[1,0]
	v_pk_mul_f32 v[138:139], v[44:45], v[134:135] op_sel_hi:[1,0]
	v_pk_mul_f32 v[142:143], v[42:43], v[134:135] op_sel_hi:[1,0]
	v_pk_mul_f32 v[144:145], v[40:41], v[134:135] op_sel_hi:[1,0]
	v_lshlrev_b64 v[146:147], 8, v[146:147]
	v_lshl_add_u64 v[146:147], v[128:129], 0, v[146:147]
	v_cvt_pk_bf16_f32 v138, v138, v139
	v_cvt_pk_bf16_f32 v139, v140, v141
	v_cvt_pk_bf16_f32 v140, v144, v145
	v_cvt_pk_bf16_f32 v141, v142, v143
	v_lshl_add_u64 v[130:131], v[130:131], 0, s[8:9]
	global_store_dwordx4 v[146:147], v[138:141], off
	v_pk_mul_f32 v[142:143], v[34:35], v[134:135] op_sel_hi:[1,0]
	v_lshlrev_b64 v[130:131], 8, v[130:131]
	v_pk_mul_f32 v[140:141], v[38:39], v[134:135] op_sel_hi:[1,0]
	v_pk_mul_f32 v[138:139], v[36:37], v[134:135] op_sel_hi:[1,0]
	v_pk_mul_f32 v[134:135], v[32:33], v[134:135] op_sel_hi:[1,0]
	v_lshl_add_u64 v[130:131], v[128:129], 0, v[130:131]
	v_cvt_pk_bf16_f32 v138, v138, v139
	v_cvt_pk_bf16_f32 v139, v140, v141
	v_cvt_pk_bf16_f32 v140, v134, v135
	v_cvt_pk_bf16_f32 v141, v142, v143
	global_store_dwordx4 v[130:131], v[138:141], off
	v_add_u32_e32 v130, 0xa0, v182
	v_ashrrev_i32_e32 v131, 31, v130
	v_lshl_add_u64 v[144:145], v[130:131], 0, s[22:23]
	v_pk_mul_f32 v[134:135], v[30:31], v[178:179] op_sel_hi:[1,0]
	v_pk_mul_f32 v[138:139], v[28:29], v[178:179] op_sel_hi:[1,0]
	v_pk_mul_f32 v[142:143], v[26:27], v[178:179] op_sel_hi:[1,0]
	v_pk_mul_f32 v[140:141], v[24:25], v[178:179] op_sel_hi:[1,0]
	v_lshlrev_b64 v[144:145], 8, v[144:145]
	v_lshl_add_u64 v[144:145], v[128:129], 0, v[144:145]
	v_cvt_pk_bf16_f32 v138, v138, v139
	v_cvt_pk_bf16_f32 v139, v134, v135
	v_cvt_pk_bf16_f32 v140, v140, v141
	v_cvt_pk_bf16_f32 v141, v142, v143
	v_lshl_add_u64 v[130:131], v[130:131], 0, s[8:9]
	global_store_dwordx4 v[144:145], v[138:141], off
	v_pk_mul_f32 v[134:135], v[22:23], v[178:179] op_sel_hi:[1,0]
	v_pk_mul_f32 v[142:143], v[18:19], v[178:179] op_sel_hi:[1,0]
	v_pk_mul_f32 v[138:139], v[20:21], v[178:179] op_sel_hi:[1,0]
	v_pk_mul_f32 v[140:141], v[16:17], v[178:179] op_sel_hi:[1,0]
	v_lshlrev_b64 v[130:131], 8, v[130:131]
	v_lshl_add_u64 v[130:131], v[128:129], 0, v[130:131]
	v_cvt_pk_bf16_f32 v138, v138, v139
	v_cvt_pk_bf16_f32 v139, v134, v135
	v_cvt_pk_bf16_f32 v140, v140, v141
	v_cvt_pk_bf16_f32 v141, v142, v143
	global_store_dwordx4 v[130:131], v[138:141], off
	v_add_u32_e32 v130, 0xb0, v182
	v_ashrrev_i32_e32 v131, 31, v130
	v_mov_b32_e32 v134, v179
	v_lshl_add_u64 v[146:147], v[130:131], 0, s[22:23]
	v_pk_mul_f32 v[140:141], v[14:15], v[134:135] op_sel_hi:[1,0]
	v_pk_mul_f32 v[138:139], v[12:13], v[134:135] op_sel_hi:[1,0]
	v_pk_mul_f32 v[142:143], v[10:11], v[134:135] op_sel_hi:[1,0]
	v_pk_mul_f32 v[144:145], v[8:9], v[134:135] op_sel_hi:[1,0]
	v_lshlrev_b64 v[146:147], 8, v[146:147]
	v_lshl_add_u64 v[146:147], v[128:129], 0, v[146:147]
	v_cvt_pk_bf16_f32 v138, v138, v139
	v_cvt_pk_bf16_f32 v139, v140, v141
	v_cvt_pk_bf16_f32 v140, v144, v145
	v_cvt_pk_bf16_f32 v141, v142, v143
	v_lshl_add_u64 v[130:131], v[130:131], 0, s[8:9]
	global_store_dwordx4 v[146:147], v[138:141], off
	v_pk_mul_f32 v[142:143], v[2:3], v[134:135] op_sel_hi:[1,0]
	v_lshlrev_b64 v[130:131], 8, v[130:131]
	v_pk_mul_f32 v[138:139], v[6:7], v[134:135] op_sel_hi:[1,0]
	v_pk_mul_f32 v[140:141], v[4:5], v[134:135] op_sel_hi:[1,0]
	v_pk_mul_f32 v[134:135], v[0:1], v[134:135] op_sel_hi:[1,0]
	v_lshl_add_u64 v[144:145], v[128:129], 0, v[130:131]
	v_cvt_pk_bf16_f32 v128, v140, v141
	v_cvt_pk_bf16_f32 v129, v138, v139
	v_cvt_pk_bf16_f32 v130, v134, v135
	v_cvt_pk_bf16_f32 v131, v142, v143
	global_store_dwordx4 v[144:145], v[128:131], off

; #define LAS __attribute__((address_space(3)))
;     __device__ __forceinline__ void operator()(const f32x4 (&acc)[2][2][4][2], const pg8::Unit& u, int wr, int wc, int fr_, int fq_) const {
;     ...
;         if (seg <= 1) {
;             const float* gain = seg == 0 ? qgain : kgain;
;             bf16_t* base = (bf16_t*)(ws + (seg == 0 ? WS_QDA : WS_KDA));
;             const float* ropec = (const float*)(ws + WS_ROPEC); const float* ropes = (const float*)(ws + WS_ROPES);
;             const int g = 4 * wc + fq;
; #pragma unroll
;             for (int ai = 0; ai < 2; ++ai)
; #pragma unroll
;                 for (int bj = 0; bj < 2; ++bj)
; #pragma unroll
;                     for (int m = 0; m < 4; ++m) { const f32x4 a = acc[ai][bj][m][0] * rs[ai][m], b = acc[ai][bj][m][1] * rs[ai][m];
;                         float s = (a[0] * a[0] + a[1] * a[1]) + (a[2] * a[2] + a[3] * a[3]) + (b[0] * b[0] + b[1] * b[1]) + (b[2] * b[2] + b[3] * b[3]);
;                         s += __shfl_xor(s, 16); s += __shfl_xor(s, 32);
;                         if (fq == 0) xch[((ai * 2 + bj) * 128 + wr * 64 + m * 16 + fr) * 4 + wc] = s; }
;             asm volatile("s_waitcnt lgkmcnt(0)" ::: "memory"); __builtin_amdgcn_s_barrier(); asm volatile("" ::: "memory");
;             const f32x4 g1 = *(const f32x4*)(gain + 4 * g), g2 = *(const f32x4*)(gain + 64 + 4 * g);
; #pragma unroll
;             for (int ai = 0; ai < 2; ++ai) {
;                 f32x4 rc[4], rn[4];
; #pragma unroll
;                 for (int m = 0; m < 4; ++m) { const int row = row0 + ai * 128 + m * 16; rc[m] = *(const f32x4*)(ropec + (size_t)row * 64 + 4 * g); rn[m] = *(const f32x4*)(ropes + (size_t)row * 64 + 4 * g); }
; #pragma unroll
;                 for (int m = 0; m < 4; ++m) { const int row = row0 + ai * 128 + m * 16;
;                     const f32x4 c = rc[m], sn = rn[m];
; #pragma unroll
;                     for (int bj = 0; bj < 2; ++bj) {
;                         const f32x4 t = *(const LAS f32x4*)(xch + ((ai * 2 + bj) * 128 + wr * 64 + m * 16 + fr) * 4);
;                         const float rstd = __builtin_amdgcn_rsqf(((t[0] + t[1]) + (t[2] + t[3])) * (1.0f / 128.0f) + RMS_EPS);
;                         const f32x4 y1 = acc[ai][bj][m][0] * (rs[ai][m] * rstd) * g1, y2 = acc[ai][bj][m][1] * (rs[ai][m] * rstd) * g2;
;                         const f32x4 o1 = y1 * c - y2 * sn, o2 = y2 * c + y1 * sn;
.LBB0_138:
	s_or_b64 exec, exec, s[8:9]
	s_lshl_b64 s[8:9], s[84:85], 2
	s_cmp_lt_u32 s72, 8
	s_cselect_b32 s40, s48, s50
	s_mov_b32 s41, 0x1c500000
	s_cselect_b32 s22, s49, s51
	s_cselect_b32 s41, s41, 0x1e500000
	s_add_u32 s8, s40, s8
	v_lshl_add_u32 v128, v136, 2, s83
	s_addc_u32 s9, s22, s9
	s_waitcnt lgkmcnt(0)
	v_ashrrev_i32_e32 v129, 31, v128
	s_add_u32 s40, s6, s41
	v_lshlrev_b64 v[138:139], 2, v[128:129]
	s_addc_u32 s41, s7, 0
	v_lshl_add_u64 v[128:129], s[8:9], 0, v[138:139]
	v_lshl_add_u64 v[138:139], s[6:7], 0, v[138:139]
	s_mov_b64 s[6:7], 0x1a000000
	v_lshl_add_u64 v[190:191], v[138:139], 0, s[6:7]
	s_mov_b64 s[6:7], 0x1a200000
	v_lshl_add_u64 v[192:193], v[138:139], 0, s[6:7]
	s_lshl_b32 s22, s25, 14
	s_lshl_b32 s6, s4, 1
	s_add_u32 s6, s40, s6
	v_lshlrev_b32_e32 v136, 3, v136
	s_addc_u32 s7, s41, 0
	v_ashrrev_i32_e32 v137, 31, v136
	v_ashrrev_i32_e32 v183, 31, v182
	s_waitcnt lgkmcnt(0)
	s_barrier
	v_lshl_add_u64 v[188:189], v[136:137], 1, s[6:7]
	v_lshlrev_b64 v[136:137], 8, v[182:183]
	global_load_dwordx4 v[132:135], v[128:129], off
	s_nop 0
	global_load_dwordx4 v[128:131], v[128:129], off offset:256
	v_lshl_add_u64 v[138:139], v[190:191], 0, v[136:137]
	v_lshl_add_u64 v[136:137], v[192:193], 0, v[136:137]
	global_load_dwordx4 v[160:163], v[138:139], off
	global_load_dwordx4 v[164:167], v[136:137], off
	v_add_u32_e32 v198, 16, v182
	v_ashrrev_i32_e32 v199, 31, v198
	v_lshlrev_b64 v[136:137], 8, v[198:199]
	v_lshl_add_u64 v[138:139], v[190:191], 0, v[136:137]
	v_lshl_add_u64 v[136:137], v[192:193], 0, v[136:137]
	global_load_dwordx4 v[152:155], v[138:139], off
	global_load_dwordx4 v[156:159], v[136:137], off
	s_add_i32 s8, 0, 0x20000
	v_add_u32_e32 v215, s8, v214
	ds_read_b128 v[216:219], v215
	v_add_u32_e32 v196, 32, v182
	v_ashrrev_i32_e32 v197, 31, v196
	v_add_u32_e32 v194, 48, v182
	v_lshlrev_b64 v[136:137], 8, v[196:197]
	s_waitcnt lgkmcnt(0)
	v_mov_b32_e32 v220, v217
	v_mov_b32_e32 v221, v218
	v_mov_b32_e32 v217, v219
	v_pk_add_f32 v[216:217], v[220:221], v[216:217]
	v_ashrrev_i32_e32 v195, 31, v194
	v_add_f32_e32 v215, v216, v217
	v_fmamk_f32 v215, v215, 0x3c000000, v232
	v_rsq_f32_e32 v215, v215
	v_lshl_add_u64 v[138:139], v[190:191], 0, v[136:137]
	v_lshl_add_u64 v[136:137], v[192:193], 0, v[136:137]
	v_lshlrev_b64 v[140:141], 8, v[194:195]
	v_mul_f32_e32 v216, v186, v215
	v_pk_mul_f32 v[120:121], v[120:121], v[216:217] op_sel_hi:[1,0]
	v_pk_mul_f32 v[122:123], v[122:123], v[216:217] op_sel_hi:[1,0]
	v_pk_mul_f32 v[124:125], v[124:125], v[216:217] op_sel_hi:[1,0]
	v_pk_mul_f32 v[126:127], v[126:127], v[216:217] op_sel_hi:[1,0]
	global_load_dwordx4 v[144:147], v[138:139], off
	global_load_dwordx4 v[148:151], v[136:137], off
	v_lshl_add_u64 v[136:137], v[190:191], 0, v[140:141]
	v_lshl_add_u64 v[140:141], v[192:193], 0, v[140:141]
	global_load_dwordx4 v[136:139], v[136:137], off
	s_or_b32 s6, s22, 0x2000
	global_load_dwordx4 v[140:143], v[140:141], off
	s_mov_b32 s7, s23
	s_waitcnt vmcnt(0)
	v_pk_mul_f32 v[126:127], v[134:135], v[126:127]
	v_pk_mul_f32 v[122:123], v[130:131], v[122:123]
	v_pk_mul_f32 v[120:121], v[128:129], v[120:121]
	v_pk_mul_f32 v[124:125], v[132:133], v[124:125]
	v_pk_mul_f32 v[216:217], v[166:167], v[122:123]
	v_pk_mul_f32 v[218:219], v[164:165], v[120:121]
	v_pk_fma_f32 v[216:217], v[162:163], v[126:127], v[216:217] neg_lo:[0,0,1] neg_hi:[0,0,1]
	v_pk_fma_f32 v[218:219], v[160:161], v[124:125], v[218:219] neg_lo:[0,0,1] neg_hi:[0,0,1]
	v_pk_mul_f32 v[126:127], v[166:167], v[126:127]
	v_pk_mul_f32 v[124:125], v[164:165], v[124:125]
	v_pk_fma_f32 v[126:127], v[162:163], v[122:123], v[126:127]
	v_pk_fma_f32 v[122:123], v[160:161], v[120:121], v[124:125]
	v_lshl_add_u64 v[120:121], v[182:183], 0, s[22:23]
	v_lshlrev_b64 v[120:121], 8, v[120:121]
	v_lshl_add_u64 v[124:125], v[188:189], 0, v[120:121]
	v_cvt_pk_bf16_f32 v120, v218, v219
	v_cvt_pk_bf16_f32 v121, v216, v217
	v_cvt_pk_bf16_f32 v122, v122, v123
	v_cvt_pk_bf16_f32 v123, v126, v127
	global_store_dwordx4 v[124:125], v[120:123], off
	s_nop 1
	v_add_u32_e32 v120, s64, v214
	ds_read_b128 v[120:123], v120
	s_waitcnt lgkmcnt(0)
	v_mov_b32_e32 v124, v121
	v_mov_b32_e32 v125, v122
	v_mov_b32_e32 v121, v123
	v_pk_add_f32 v[120:121], v[124:125], v[120:121]
	s_nop 0
	v_add_f32_e32 v120, v120, v121
	v_fmamk_f32 v120, v120, 0x3c000000, v232
	v_rsq_f32_e32 v120, v120
	s_nop 0
	v_mul_f32_e32 v120, v186, v120
	v_pk_mul_f32 v[112:113], v[112:113], v[120:121] op_sel_hi:[1,0]
	v_pk_mul_f32 v[114:115], v[114:115], v[120:121] op_sel_hi:[1,0]
	v_pk_mul_f32 v[116:117], v[116:117], v[120:121] op_sel_hi:[1,0]
	v_pk_mul_f32 v[118:119], v[118:119], v[120:121] op_sel_hi:[1,0]
	v_pk_mul_f32 v[114:115], v[130:131], v[114:115]
	v_pk_mul_f32 v[112:113], v[128:129], v[112:113]
	v_pk_mul_f32 v[118:119], v[134:135], v[118:119]
	v_pk_mul_f32 v[116:117], v[132:133], v[116:117]
	v_pk_mul_f32 v[120:121], v[166:167], v[114:115]
	v_pk_mul_f32 v[122:123], v[164:165], v[112:113]
	v_pk_fma_f32 v[120:121], v[162:163], v[118:119], v[120:121] neg_lo:[0,0,1] neg_hi:[0,0,1]
	v_pk_fma_f32 v[122:123], v[160:161], v[116:117], v[122:123] neg_lo:[0,0,1] neg_hi:[0,0,1]
	v_pk_mul_f32 v[118:119], v[166:167], v[118:119]
	v_pk_mul_f32 v[116:117], v[164:165], v[116:117]
	v_pk_fma_f32 v[118:119], v[162:163], v[114:115], v[118:119]
	v_pk_fma_f32 v[114:115], v[160:161], v[112:113], v[116:117]
	v_lshl_add_u64 v[112:113], v[182:183], 0, s[6:7]
	v_lshlrev_b64 v[112:113], 8, v[112:113]
	v_lshl_add_u64 v[116:117], v[188:189], 0, v[112:113]
	v_cvt_pk_bf16_f32 v112, v122, v123
	v_cvt_pk_bf16_f32 v113, v120, v121
	v_cvt_pk_bf16_f32 v114, v114, v115
	v_cvt_pk_bf16_f32 v115, v118, v119
	v_add_u32_e32 v118, 0x100, v214
	global_store_dwordx4 v[116:117], v[112:115], off
	s_nop 1
	v_add_u32_e32 v112, s8, v118
	ds_read_b128 v[112:115], v112
	s_waitcnt lgkmcnt(0)
; #define LAS __attribute__((address_space(3)))
;     __device__ __forceinline__ void operator()(const f32x4 (&acc)[2][2][4][2], const pg8::Unit& u, int wr, int wc, int fr_, int fq_) const {
;     ...
;                 for (int m = 0; m < 4; ++m) { const int row = row0 + ai * 128 + m * 16;
;                     const f32x4 c = rc[m], sn = rn[m];
; #pragma unroll
;                     for (int bj = 0; bj < 2; ++bj) {
;                         const f32x4 t = *(const LAS f32x4*)(xch + ((ai * 2 + bj) * 128 + wr * 64 + m * 16 + fr) * 4);
;                         const float rstd = __builtin_amdgcn_rsqf(((t[0] + t[1]) + (t[2] + t[3])) * (1.0f / 128.0f) + RMS_EPS);
;                         const f32x4 y1 = acc[ai][bj][m][0] * (rs[ai][m] * rstd) * g1, y2 = acc[ai][bj][m][1] * (rs[ai][m] * rstd) * g2;
;                         const f32x4 o1 = y1 * c - y2 * sn, o2 = y2 * c + y1 * sn;
;                         bf16_t* ptr = base + ((size_t)(pl * 2 + bj) * S + row) * 128 + 32 * wc + 8 * fq;
;                         *(u32x4*)ptr = pack8bf(o1, o2); }
	v_mov_b32_e32 v116, v113
	v_mov_b32_e32 v117, v114
	v_mov_b32_e32 v113, v115
	v_pk_add_f32 v[112:113], v[116:117], v[112:113]
	s_nop 0
	v_add_f32_e32 v112, v112, v113
	v_fmamk_f32 v112, v112, 0x3c000000, v232
	v_rsq_f32_e32 v112, v112
	s_nop 0
	v_mul_f32_e32 v112, v187, v112
	v_pk_mul_f32 v[104:105], v[104:105], v[112:113] op_sel_hi:[1,0]
	v_pk_mul_f32 v[106:107], v[106:107], v[112:113] op_sel_hi:[1,0]
	v_pk_mul_f32 v[110:111], v[110:111], v[112:113] op_sel_hi:[1,0]
	v_pk_mul_f32 v[108:109], v[108:109], v[112:113] op_sel_hi:[1,0]
	v_pk_mul_f32 v[106:107], v[130:131], v[106:107]
	v_pk_mul_f32 v[104:105], v[128:129], v[104:105]
	v_pk_mul_f32 v[108:109], v[132:133], v[108:109]
	v_pk_mul_f32 v[110:111], v[134:135], v[110:111]
	v_pk_mul_f32 v[112:113], v[156:157], v[104:105]
	v_pk_mul_f32 v[114:115], v[158:159], v[106:107]
	v_pk_fma_f32 v[112:113], v[152:153], v[108:109], v[112:113] neg_lo:[0,0,1] neg_hi:[0,0,1]
	v_pk_fma_f32 v[114:115], v[154:155], v[110:111], v[114:115] neg_lo:[0,0,1] neg_hi:[0,0,1]
	v_pk_mul_f32 v[108:109], v[156:157], v[108:109]
	v_pk_mul_f32 v[110:111], v[158:159], v[110:111]
	s_nop 0
	v_pk_fma_f32 v[110:111], v[154:155], v[106:107], v[110:111]
	v_pk_fma_f32 v[106:107], v[152:153], v[104:105], v[108:109]
	v_lshl_add_u64 v[104:105], v[198:199], 0, s[22:23]
	v_lshlrev_b64 v[104:105], 8, v[104:105]
	v_lshl_add_u64 v[108:109], v[188:189], 0, v[104:105]
	v_cvt_pk_bf16_f32 v104, v112, v113
	v_cvt_pk_bf16_f32 v105, v114, v115
	v_cvt_pk_bf16_f32 v106, v106, v107
	v_cvt_pk_bf16_f32 v107, v110, v111
	global_store_dwordx4 v[108:109], v[104:107], off
	v_add_u32_e32 v110, 0x1000, v214
	s_nop 0
	v_add_u32_e32 v104, s64, v118
	ds_read_b128 v[104:107], v104
	s_waitcnt lgkmcnt(0)
	v_mov_b32_e32 v108, v105
	v_mov_b32_e32 v109, v106
	v_mov_b32_e32 v105, v107
	v_pk_add_f32 v[104:105], v[108:109], v[104:105]
	s_nop 0
	v_add_f32_e32 v104, v104, v105
	v_fmamk_f32 v104, v104, 0x3c000000, v232
	v_rsq_f32_e32 v104, v104
	s_nop 0
	v_mul_f32_e32 v104, v187, v104
	v_pk_mul_f32 v[96:97], v[96:97], v[104:105] op_sel_hi:[1,0]
	v_pk_mul_f32 v[98:99], v[98:99], v[104:105] op_sel_hi:[1,0]
	v_pk_mul_f32 v[102:103], v[102:103], v[104:105] op_sel_hi:[1,0]
	v_pk_mul_f32 v[100:101], v[100:101], v[104:105] op_sel_hi:[1,0]
	v_pk_mul_f32 v[98:99], v[130:131], v[98:99]
	v_pk_mul_f32 v[96:97], v[128:129], v[96:97]
	v_pk_mul_f32 v[100:101], v[132:133], v[100:101]
	v_pk_mul_f32 v[102:103], v[134:135], v[102:103]
	v_pk_mul_f32 v[104:105], v[156:157], v[96:97]
	v_pk_mul_f32 v[106:107], v[158:159], v[98:99]
	v_pk_fma_f32 v[104:105], v[152:153], v[100:101], v[104:105] neg_lo:[0,0,1] neg_hi:[0,0,1]
	v_pk_fma_f32 v[106:107], v[154:155], v[102:103], v[106:107] neg_lo:[0,0,1] neg_hi:[0,0,1]
	v_pk_mul_f32 v[100:101], v[156:157], v[100:101]
	v_pk_mul_f32 v[102:103], v[158:159], v[102:103]
	s_nop 0
	v_pk_fma_f32 v[102:103], v[154:155], v[98:99], v[102:103]
	v_pk_fma_f32 v[98:99], v[152:153], v[96:97], v[100:101]
	v_lshl_add_u64 v[96:97], v[198:199], 0, s[6:7]
	v_lshlrev_b64 v[96:97], 8, v[96:97]
	v_lshl_add_u64 v[100:101], v[188:189], 0, v[96:97]
	v_cvt_pk_bf16_f32 v96, v104, v105
	v_cvt_pk_bf16_f32 v97, v106, v107
	v_cvt_pk_bf16_f32 v98, v98, v99
	v_cvt_pk_bf16_f32 v99, v102, v103
	v_add_u32_e32 v102, 0x200, v214
	global_store_dwordx4 v[100:101], v[96:99], off
	v_add_u32_e32 v106, 0x80, v182
	v_ashrrev_i32_e32 v107, 31, v106
	v_add_u32_e32 v96, s8, v102
	ds_read_b128 v[96:99], v96
	s_waitcnt lgkmcnt(0)
	v_mov_b32_e32 v100, v97
	v_mov_b32_e32 v101, v98
	v_mov_b32_e32 v97, v99
	v_pk_add_f32 v[96:97], v[100:101], v[96:97]
	s_nop 0
	v_add_f32_e32 v96, v96, v97
	v_fmamk_f32 v96, v96, 0x3c000000, v232
	v_rsq_f32_e32 v96, v96
	s_nop 0
	v_mul_f32_e32 v96, v184, v96
	v_pk_mul_f32 v[88:89], v[88:89], v[96:97] op_sel_hi:[1,0]
	v_pk_mul_f32 v[90:91], v[90:91], v[96:97] op_sel_hi:[1,0]
	v_pk_mul_f32 v[94:95], v[94:95], v[96:97] op_sel_hi:[1,0]
	v_pk_mul_f32 v[92:93], v[92:93], v[96:97] op_sel_hi:[1,0]
	v_pk_mul_f32 v[90:91], v[130:131], v[90:91]
	v_pk_mul_f32 v[88:89], v[128:129], v[88:89]
	v_pk_mul_f32 v[92:93], v[132:133], v[92:93]
	v_pk_mul_f32 v[94:95], v[134:135], v[94:95]
	v_pk_mul_f32 v[96:97], v[148:149], v[88:89]
	v_pk_mul_f32 v[98:99], v[150:151], v[90:91]
	v_pk_fma_f32 v[96:97], v[144:145], v[92:93], v[96:97] neg_lo:[0,0,1] neg_hi:[0,0,1]
	v_pk_fma_f32 v[98:99], v[146:147], v[94:95], v[98:99] neg_lo:[0,0,1] neg_hi:[0,0,1]
	v_pk_mul_f32 v[92:93], v[148:149], v[92:93]
	v_pk_mul_f32 v[94:95], v[150:151], v[94:95]
	s_nop 0
	v_pk_fma_f32 v[94:95], v[146:147], v[90:91], v[94:95]
	v_pk_fma_f32 v[90:91], v[144:145], v[88:89], v[92:93]
	v_lshl_add_u64 v[88:89], v[196:197], 0, s[22:23]
	v_lshlrev_b64 v[88:89], 8, v[88:89]
	v_lshl_add_u64 v[92:93], v[188:189], 0, v[88:89]
	v_cvt_pk_bf16_f32 v88, v96, v97
	v_cvt_pk_bf16_f32 v89, v98, v99
	v_cvt_pk_bf16_f32 v90, v90, v91
	v_cvt_pk_bf16_f32 v91, v94, v95
	global_store_dwordx4 v[92:93], v[88:91], off
	s_nop 1
	v_add_u32_e32 v88, s64, v102
	ds_read_b128 v[88:91], v88
	v_add_u32_e32 v102, s8, v110
	s_waitcnt lgkmcnt(0)
; #define LAS __attribute__((address_space(3)))
;     __device__ __forceinline__ void operator()(const f32x4 (&acc)[2][2][4][2], const pg8::Unit& u, int wr, int wc, int fr_, int fq_) const {
;     ...
;                 for (int m = 0; m < 4; ++m) { const int row = row0 + ai * 128 + m * 16; rc[m] = *(const f32x4*)(ropec + (size_t)row * 64 + 4 * g); rn[m] = *(const f32x4*)(ropes + (size_t)row * 64 + 4 * g); }
; #pragma unroll
;                 for (int m = 0; m < 4; ++m) { const int row = row0 + ai * 128 + m * 16;
;                     const f32x4 c = rc[m], sn = rn[m];
; #pragma unroll
;                     for (int bj = 0; bj < 2; ++bj) {
;                         const f32x4 t = *(const LAS f32x4*)(xch + ((ai * 2 + bj) * 128 + wr * 64 + m * 16 + fr) * 4);
;                         const float rstd = __builtin_amdgcn_rsqf(((t[0] + t[1]) + (t[2] + t[3])) * (1.0f / 128.0f) + RMS_EPS);
;                         const f32x4 y1 = acc[ai][bj][m][0] * (rs[ai][m] * rstd) * g1, y2 = acc[ai][bj][m][1] * (rs[ai][m] * rstd) * g2;
;                         const f32x4 o1 = y1 * c - y2 * sn, o2 = y2 * c + y1 * sn;
;                         bf16_t* ptr = base + ((size_t)(pl * 2 + bj) * S + row) * 128 + 32 * wc + 8 * fq;
;                         *(u32x4*)ptr = pack8bf(o1, o2); }
	v_mov_b32_e32 v92, v89
	v_mov_b32_e32 v93, v90
	v_mov_b32_e32 v89, v91
	v_pk_add_f32 v[88:89], v[92:93], v[88:89]
	v_add_u32_e32 v92, 0x90, v182
	v_add_f32_e32 v88, v88, v89
	v_fmamk_f32 v88, v88, 0x3c000000, v232
	v_rsq_f32_e32 v88, v88
	v_ashrrev_i32_e32 v93, 31, v92
	v_mul_f32_e32 v88, v184, v88
	v_pk_mul_f32 v[80:81], v[80:81], v[88:89] op_sel_hi:[1,0]
	v_pk_mul_f32 v[82:83], v[82:83], v[88:89] op_sel_hi:[1,0]
	v_pk_mul_f32 v[86:87], v[86:87], v[88:89] op_sel_hi:[1,0]
	v_pk_mul_f32 v[84:85], v[84:85], v[88:89] op_sel_hi:[1,0]
	v_pk_mul_f32 v[82:83], v[130:131], v[82:83]
	v_pk_mul_f32 v[80:81], v[128:129], v[80:81]
	v_pk_mul_f32 v[84:85], v[132:133], v[84:85]
	v_pk_mul_f32 v[86:87], v[134:135], v[86:87]
	v_pk_mul_f32 v[88:89], v[148:149], v[80:81]
	v_pk_mul_f32 v[90:91], v[150:151], v[82:83]
	v_pk_fma_f32 v[88:89], v[144:145], v[84:85], v[88:89] neg_lo:[0,0,1] neg_hi:[0,0,1]
	v_pk_fma_f32 v[90:91], v[146:147], v[86:87], v[90:91] neg_lo:[0,0,1] neg_hi:[0,0,1]
	v_pk_mul_f32 v[84:85], v[148:149], v[84:85]
	v_pk_mul_f32 v[86:87], v[150:151], v[86:87]
	s_nop 0
	v_pk_fma_f32 v[86:87], v[146:147], v[82:83], v[86:87]
	v_pk_fma_f32 v[82:83], v[144:145], v[80:81], v[84:85]
	v_lshl_add_u64 v[80:81], v[196:197], 0, s[6:7]
	v_lshlrev_b64 v[80:81], 8, v[80:81]
	v_lshl_add_u64 v[84:85], v[188:189], 0, v[80:81]
	v_cvt_pk_bf16_f32 v80, v88, v89
	v_cvt_pk_bf16_f32 v81, v90, v91
	v_cvt_pk_bf16_f32 v82, v82, v83
	v_cvt_pk_bf16_f32 v83, v86, v87
	v_add_u32_e32 v86, 0x300, v214
	global_store_dwordx4 v[84:85], v[80:83], off
	v_add_u32_e32 v90, 0xa0, v182
	v_ashrrev_i32_e32 v91, 31, v90
	v_add_u32_e32 v80, s8, v86
	ds_read_b128 v[80:83], v80
	v_add_u32_e32 v88, 0xb0, v182
	v_ashrrev_i32_e32 v89, 31, v88
	s_waitcnt lgkmcnt(0)
	v_mov_b32_e32 v84, v81
	v_mov_b32_e32 v85, v82
	v_mov_b32_e32 v81, v83
	v_pk_add_f32 v[80:81], v[84:85], v[80:81]
	s_nop 0
	v_add_f32_e32 v80, v80, v81
	v_fmamk_f32 v80, v80, 0x3c000000, v232
	v_rsq_f32_e32 v80, v80
	s_nop 0
	v_mul_f32_e32 v80, v185, v80
	v_pk_mul_f32 v[72:73], v[72:73], v[80:81] op_sel_hi:[1,0]
	v_pk_mul_f32 v[74:75], v[74:75], v[80:81] op_sel_hi:[1,0]
	v_pk_mul_f32 v[78:79], v[78:79], v[80:81] op_sel_hi:[1,0]
	v_pk_mul_f32 v[76:77], v[76:77], v[80:81] op_sel_hi:[1,0]
	v_pk_mul_f32 v[74:75], v[130:131], v[74:75]
	v_pk_mul_f32 v[72:73], v[128:129], v[72:73]
	v_pk_mul_f32 v[76:77], v[132:133], v[76:77]
	v_pk_mul_f32 v[78:79], v[134:135], v[78:79]
	v_pk_mul_f32 v[80:81], v[140:141], v[72:73]
	v_pk_mul_f32 v[82:83], v[142:143], v[74:75]
	v_pk_fma_f32 v[80:81], v[136:137], v[76:77], v[80:81] neg_lo:[0,0,1] neg_hi:[0,0,1]
	v_pk_fma_f32 v[82:83], v[138:139], v[78:79], v[82:83] neg_lo:[0,0,1] neg_hi:[0,0,1]
	v_pk_mul_f32 v[76:77], v[140:141], v[76:77]
	v_pk_mul_f32 v[78:79], v[142:143], v[78:79]
	s_nop 0
	v_pk_fma_f32 v[78:79], v[138:139], v[74:75], v[78:79]
	v_pk_fma_f32 v[74:75], v[136:137], v[72:73], v[76:77]
	v_lshl_add_u64 v[72:73], v[194:195], 0, s[22:23]
	v_lshlrev_b64 v[72:73], 8, v[72:73]
	v_lshl_add_u64 v[76:77], v[188:189], 0, v[72:73]
	v_cvt_pk_bf16_f32 v72, v80, v81
	v_cvt_pk_bf16_f32 v73, v82, v83
	v_cvt_pk_bf16_f32 v74, v74, v75
	v_cvt_pk_bf16_f32 v75, v78, v79
	global_store_dwordx4 v[76:77], v[72:75], off
	s_nop 1
	v_add_u32_e32 v72, s64, v86
	ds_read_b128 v[72:75], v72
	s_waitcnt lgkmcnt(0)
	v_mov_b32_e32 v76, v73
	v_mov_b32_e32 v77, v74
	v_mov_b32_e32 v73, v75
	v_pk_add_f32 v[72:73], v[76:77], v[72:73]
	s_nop 0
	v_add_f32_e32 v72, v72, v73
	v_fmamk_f32 v72, v72, 0x3c000000, v232
	v_rsq_f32_e32 v72, v72
	s_nop 0
	v_mul_f32_e32 v72, v185, v72
	v_pk_mul_f32 v[64:65], v[64:65], v[72:73] op_sel_hi:[1,0]
	v_pk_mul_f32 v[66:67], v[66:67], v[72:73] op_sel_hi:[1,0]
	v_pk_mul_f32 v[70:71], v[70:71], v[72:73] op_sel_hi:[1,0]
	v_pk_mul_f32 v[68:69], v[68:69], v[72:73] op_sel_hi:[1,0]
	v_pk_mul_f32 v[66:67], v[130:131], v[66:67]
	v_pk_mul_f32 v[64:65], v[128:129], v[64:65]
	v_pk_mul_f32 v[68:69], v[132:133], v[68:69]
	v_pk_mul_f32 v[70:71], v[134:135], v[70:71]
	v_pk_mul_f32 v[72:73], v[140:141], v[64:65]
	v_pk_mul_f32 v[74:75], v[142:143], v[66:67]
	v_pk_fma_f32 v[72:73], v[136:137], v[68:69], v[72:73] neg_lo:[0,0,1] neg_hi:[0,0,1]
	v_pk_fma_f32 v[74:75], v[138:139], v[70:71], v[74:75] neg_lo:[0,0,1] neg_hi:[0,0,1]
	v_pk_mul_f32 v[68:69], v[140:141], v[68:69]
	v_pk_mul_f32 v[70:71], v[142:143], v[70:71]
	s_nop 0
	v_pk_fma_f32 v[70:71], v[138:139], v[66:67], v[70:71]
	v_pk_fma_f32 v[66:67], v[136:137], v[64:65], v[68:69]
	v_lshl_add_u64 v[64:65], v[194:195], 0, s[6:7]
	v_lshlrev_b64 v[64:65], 8, v[64:65]
	v_lshl_add_u64 v[68:69], v[188:189], 0, v[64:65]
	v_cvt_pk_bf16_f32 v64, v72, v73
	v_cvt_pk_bf16_f32 v65, v74, v75
	v_cvt_pk_bf16_f32 v66, v66, v67
	v_cvt_pk_bf16_f32 v67, v70, v71
	global_store_dwordx4 v[68:69], v[64:67], off
	ds_read_b128 v[102:105], v102
	v_lshlrev_b64 v[68:69], 8, v[88:89]
	v_lshlrev_b64 v[64:65], 8, v[106:107]
	v_lshl_add_u64 v[66:67], v[190:191], 0, v[64:65]
	v_lshl_add_u64 v[64:65], v[192:193], 0, v[64:65]
	global_load_dwordx4 v[94:97], v[66:67], off
	global_load_dwordx4 v[98:101], v[64:65], off
	v_lshlrev_b64 v[64:65], 8, v[92:93]
	v_lshl_add_u64 v[66:67], v[190:191], 0, v[64:65]
	v_lshl_add_u64 v[64:65], v[192:193], 0, v[64:65]
	global_load_dwordx4 v[80:83], v[66:67], off
	global_load_dwordx4 v[84:87], v[64:65], off
	s_waitcnt lgkmcnt(0)
; #define LAS __attribute__((address_space(3)))
;     __device__ __forceinline__ void operator()(const f32x4 (&acc)[2][2][4][2], const pg8::Unit& u, int wr, int wc, int fr_, int fq_) const {
;     ...
;                 for (int m = 0; m < 4; ++m) { const int row = row0 + ai * 128 + m * 16; rc[m] = *(const f32x4*)(ropec + (size_t)row * 64 + 4 * g); rn[m] = *(const f32x4*)(ropes + (size_t)row * 64 + 4 * g); }
; #pragma unroll
;                 for (int m = 0; m < 4; ++m) { const int row = row0 + ai * 128 + m * 16;
;                     const f32x4 c = rc[m], sn = rn[m];
; #pragma unroll
;                     for (int bj = 0; bj < 2; ++bj) {
;                         const f32x4 t = *(const LAS f32x4*)(xch + ((ai * 2 + bj) * 128 + wr * 64 + m * 16 + fr) * 4);
;                         const float rstd = __builtin_amdgcn_rsqf(((t[0] + t[1]) + (t[2] + t[3])) * (1.0f / 128.0f) + RMS_EPS);
;                         const f32x4 y1 = acc[ai][bj][m][0] * (rs[ai][m] * rstd) * g1, y2 = acc[ai][bj][m][1] * (rs[ai][m] * rstd) * g2;
;                         const f32x4 o1 = y1 * c - y2 * sn, o2 = y2 * c + y1 * sn;
;                         bf16_t* ptr = base + ((size_t)(pl * 2 + bj) * S + row) * 128 + 32 * wc + 8 * fq;
;                         *(u32x4*)ptr = pack8bf(o1, o2); }
	v_mov_b32_e32 v108, v103
	v_mov_b32_e32 v109, v104
	v_mov_b32_e32 v103, v105
	v_pk_add_f32 v[102:103], v[108:109], v[102:103]
	v_lshlrev_b64 v[64:65], 8, v[90:91]
	v_add_f32_e32 v102, v102, v103
	v_fmamk_f32 v102, v102, 0x3c000000, v232
	v_rsq_f32_e32 v102, v102
	v_lshl_add_u64 v[66:67], v[190:191], 0, v[64:65]
	v_lshl_add_u64 v[64:65], v[192:193], 0, v[64:65]
	global_load_dwordx4 v[72:75], v[66:67], off
	global_load_dwordx4 v[76:79], v[64:65], off
	v_mul_f32_e32 v102, v180, v102
	v_pk_mul_f32 v[56:57], v[56:57], v[102:103] op_sel_hi:[1,0]
	v_pk_mul_f32 v[58:59], v[58:59], v[102:103] op_sel_hi:[1,0]
	v_pk_mul_f32 v[62:63], v[62:63], v[102:103] op_sel_hi:[1,0]
	v_pk_mul_f32 v[60:61], v[60:61], v[102:103] op_sel_hi:[1,0]
	v_pk_mul_f32 v[58:59], v[130:131], v[58:59]
	v_pk_mul_f32 v[56:57], v[128:129], v[56:57]
	v_pk_mul_f32 v[60:61], v[132:133], v[60:61]
	v_pk_mul_f32 v[62:63], v[134:135], v[62:63]
	v_lshl_add_u64 v[64:65], v[190:191], 0, v[68:69]
	v_lshl_add_u64 v[68:69], v[192:193], 0, v[68:69]
	global_load_dwordx4 v[64:67], v[64:65], off
	s_waitcnt vmcnt(0)
	v_pk_mul_f32 v[102:103], v[98:99], v[56:57]
	v_pk_mul_f32 v[104:105], v[100:101], v[58:59]
	v_pk_fma_f32 v[102:103], v[94:95], v[60:61], v[102:103] neg_lo:[0,0,1] neg_hi:[0,0,1]
	v_pk_fma_f32 v[104:105], v[96:97], v[62:63], v[104:105] neg_lo:[0,0,1] neg_hi:[0,0,1]
	v_pk_mul_f32 v[60:61], v[98:99], v[60:61]
	v_pk_mul_f32 v[62:63], v[100:101], v[62:63]
	global_load_dwordx4 v[68:71], v[68:69], off
	v_pk_fma_f32 v[62:63], v[96:97], v[58:59], v[62:63]
	v_pk_fma_f32 v[58:59], v[94:95], v[56:57], v[60:61]
	v_lshl_add_u64 v[56:57], v[106:107], 0, s[22:23]
	v_lshlrev_b64 v[56:57], 8, v[56:57]
	v_lshl_add_u64 v[60:61], v[188:189], 0, v[56:57]
	v_cvt_pk_bf16_f32 v56, v102, v103
	v_cvt_pk_bf16_f32 v57, v104, v105
	v_cvt_pk_bf16_f32 v58, v58, v59
	v_cvt_pk_bf16_f32 v59, v62, v63
	global_store_dwordx4 v[60:61], v[56:59], off
	s_nop 1
	v_add_u32_e32 v56, s64, v110
	ds_read_b128 v[56:59], v56
	s_waitcnt lgkmcnt(0)
	v_mov_b32_e32 v60, v57
	v_mov_b32_e32 v61, v58
	v_mov_b32_e32 v57, v59
	v_pk_add_f32 v[56:57], v[60:61], v[56:57]
	s_nop 0
	v_add_f32_e32 v56, v56, v57
	v_fmamk_f32 v56, v56, 0x3c000000, v232
	v_rsq_f32_e32 v56, v56
	s_nop 0
	v_mul_f32_e32 v56, v180, v56
	v_pk_mul_f32 v[48:49], v[48:49], v[56:57] op_sel_hi:[1,0]
	v_pk_mul_f32 v[50:51], v[50:51], v[56:57] op_sel_hi:[1,0]
	v_pk_mul_f32 v[54:55], v[54:55], v[56:57] op_sel_hi:[1,0]
	v_pk_mul_f32 v[52:53], v[52:53], v[56:57] op_sel_hi:[1,0]
	v_pk_mul_f32 v[50:51], v[130:131], v[50:51]
	v_pk_mul_f32 v[48:49], v[128:129], v[48:49]
	v_pk_mul_f32 v[52:53], v[132:133], v[52:53]
	v_pk_mul_f32 v[54:55], v[134:135], v[54:55]
	v_pk_mul_f32 v[56:57], v[98:99], v[48:49]
	v_pk_mul_f32 v[58:59], v[100:101], v[50:51]
	v_pk_fma_f32 v[56:57], v[94:95], v[52:53], v[56:57] neg_lo:[0,0,1] neg_hi:[0,0,1]
	v_pk_fma_f32 v[58:59], v[96:97], v[54:55], v[58:59] neg_lo:[0,0,1] neg_hi:[0,0,1]
	v_pk_mul_f32 v[52:53], v[98:99], v[52:53]
	v_pk_mul_f32 v[54:55], v[100:101], v[54:55]
	s_nop 0
	v_pk_fma_f32 v[54:55], v[96:97], v[50:51], v[54:55]
	v_pk_fma_f32 v[50:51], v[94:95], v[48:49], v[52:53]
	v_lshl_add_u64 v[48:49], v[106:107], 0, s[6:7]
	v_lshlrev_b64 v[48:49], 8, v[48:49]
	v_lshl_add_u64 v[52:53], v[188:189], 0, v[48:49]
	v_cvt_pk_bf16_f32 v48, v56, v57
	v_cvt_pk_bf16_f32 v49, v58, v59
	v_cvt_pk_bf16_f32 v50, v50, v51
	v_cvt_pk_bf16_f32 v51, v54, v55
	v_add_u32_e32 v54, 0x1100, v214
	global_store_dwordx4 v[52:53], v[48:51], off
	s_nop 1
	v_add_u32_e32 v48, s8, v54
	ds_read_b128 v[48:51], v48
	s_waitcnt lgkmcnt(0)
	v_mov_b32_e32 v52, v49
	v_mov_b32_e32 v53, v50
	v_mov_b32_e32 v49, v51
	v_pk_add_f32 v[48:49], v[52:53], v[48:49]
	s_nop 0
	v_add_f32_e32 v48, v48, v49
	v_fmamk_f32 v48, v48, 0x3c000000, v232
	v_rsq_f32_e32 v48, v48
	s_nop 0
	v_mul_f32_e32 v48, v181, v48
	v_pk_mul_f32 v[40:41], v[40:41], v[48:49] op_sel_hi:[1,0]
	v_pk_mul_f32 v[42:43], v[42:43], v[48:49] op_sel_hi:[1,0]
	v_pk_mul_f32 v[46:47], v[46:47], v[48:49] op_sel_hi:[1,0]
	v_pk_mul_f32 v[44:45], v[44:45], v[48:49] op_sel_hi:[1,0]
	v_pk_mul_f32 v[42:43], v[130:131], v[42:43]
	v_pk_mul_f32 v[40:41], v[128:129], v[40:41]
	v_pk_mul_f32 v[44:45], v[132:133], v[44:45]
	v_pk_mul_f32 v[46:47], v[134:135], v[46:47]
	v_pk_mul_f32 v[48:49], v[84:85], v[40:41]
	v_pk_mul_f32 v[50:51], v[86:87], v[42:43]
	v_pk_fma_f32 v[48:49], v[80:81], v[44:45], v[48:49] neg_lo:[0,0,1] neg_hi:[0,0,1]
	v_pk_fma_f32 v[50:51], v[82:83], v[46:47], v[50:51] neg_lo:[0,0,1] neg_hi:[0,0,1]
	v_pk_mul_f32 v[44:45], v[84:85], v[44:45]
	v_pk_mul_f32 v[46:47], v[86:87], v[46:47]
	s_nop 0
	v_pk_fma_f32 v[46:47], v[82:83], v[42:43], v[46:47]
	v_pk_fma_f32 v[42:43], v[80:81], v[40:41], v[44:45]
	v_lshl_add_u64 v[40:41], v[92:93], 0, s[22:23]
	v_lshlrev_b64 v[40:41], 8, v[40:41]
	v_lshl_add_u64 v[44:45], v[188:189], 0, v[40:41]
	v_cvt_pk_bf16_f32 v40, v48, v49
	v_cvt_pk_bf16_f32 v41, v50, v51
	v_cvt_pk_bf16_f32 v42, v42, v43
	v_cvt_pk_bf16_f32 v43, v46, v47
	global_store_dwordx4 v[44:45], v[40:43], off
	s_nop 1
	v_add_u32_e32 v40, s64, v54
	ds_read_b128 v[40:43], v40
	s_waitcnt lgkmcnt(0)
; #define LAS __attribute__((address_space(3)))
;     __device__ __forceinline__ void operator()(const f32x4 (&acc)[2][2][4][2], const pg8::Unit& u, int wr, int wc, int fr_, int fq_) const {
;     ...
;                 for (int m = 0; m < 4; ++m) { const int row = row0 + ai * 128 + m * 16;
;                     const f32x4 c = rc[m], sn = rn[m];
; #pragma unroll
;                     for (int bj = 0; bj < 2; ++bj) {
;                         const f32x4 t = *(const LAS f32x4*)(xch + ((ai * 2 + bj) * 128 + wr * 64 + m * 16 + fr) * 4);
;                         const float rstd = __builtin_amdgcn_rsqf(((t[0] + t[1]) + (t[2] + t[3])) * (1.0f / 128.0f) + RMS_EPS);
;                         const f32x4 y1 = acc[ai][bj][m][0] * (rs[ai][m] * rstd) * g1, y2 = acc[ai][bj][m][1] * (rs[ai][m] * rstd) * g2;
;                         const f32x4 o1 = y1 * c - y2 * sn, o2 = y2 * c + y1 * sn;
;                         bf16_t* ptr = base + ((size_t)(pl * 2 + bj) * S + row) * 128 + 32 * wc + 8 * fq;
;                         *(u32x4*)ptr = pack8bf(o1, o2); }
	v_mov_b32_e32 v44, v41
	v_mov_b32_e32 v45, v42
	v_mov_b32_e32 v41, v43
	v_pk_add_f32 v[40:41], v[44:45], v[40:41]
	s_nop 0
	v_add_f32_e32 v40, v40, v41
	v_fmamk_f32 v40, v40, 0x3c000000, v232
	v_rsq_f32_e32 v40, v40
	s_nop 0
	v_mul_f32_e32 v40, v181, v40
	v_pk_mul_f32 v[32:33], v[32:33], v[40:41] op_sel_hi:[1,0]
	v_pk_mul_f32 v[34:35], v[34:35], v[40:41] op_sel_hi:[1,0]
	v_pk_mul_f32 v[38:39], v[38:39], v[40:41] op_sel_hi:[1,0]
	v_pk_mul_f32 v[36:37], v[36:37], v[40:41] op_sel_hi:[1,0]
	v_pk_mul_f32 v[34:35], v[130:131], v[34:35]
	v_pk_mul_f32 v[32:33], v[128:129], v[32:33]
	v_pk_mul_f32 v[36:37], v[132:133], v[36:37]
	v_pk_mul_f32 v[38:39], v[134:135], v[38:39]
	v_pk_mul_f32 v[40:41], v[84:85], v[32:33]
	v_pk_mul_f32 v[42:43], v[86:87], v[34:35]
	v_pk_fma_f32 v[40:41], v[80:81], v[36:37], v[40:41] neg_lo:[0,0,1] neg_hi:[0,0,1]
	v_pk_fma_f32 v[42:43], v[82:83], v[38:39], v[42:43] neg_lo:[0,0,1] neg_hi:[0,0,1]
	v_pk_mul_f32 v[36:37], v[84:85], v[36:37]
	v_pk_mul_f32 v[38:39], v[86:87], v[38:39]
	s_nop 0
	v_pk_fma_f32 v[38:39], v[82:83], v[34:35], v[38:39]
	v_pk_fma_f32 v[34:35], v[80:81], v[32:33], v[36:37]
	v_lshl_add_u64 v[32:33], v[92:93], 0, s[6:7]
	v_lshlrev_b64 v[32:33], 8, v[32:33]
	v_lshl_add_u64 v[36:37], v[188:189], 0, v[32:33]
	v_cvt_pk_bf16_f32 v32, v40, v41
	v_cvt_pk_bf16_f32 v33, v42, v43
	v_cvt_pk_bf16_f32 v34, v34, v35
	v_cvt_pk_bf16_f32 v35, v38, v39
	v_add_u32_e32 v38, 0x1200, v214
	global_store_dwordx4 v[36:37], v[32:35], off
	s_nop 1
	v_add_u32_e32 v32, s8, v38
	ds_read_b128 v[32:35], v32
	s_waitcnt lgkmcnt(0)
	v_mov_b32_e32 v36, v33
	v_mov_b32_e32 v37, v34
	v_mov_b32_e32 v33, v35
	v_pk_add_f32 v[32:33], v[36:37], v[32:33]
	s_nop 0
	v_add_f32_e32 v32, v32, v33
	v_fmamk_f32 v32, v32, 0x3c000000, v232
	v_rsq_f32_e32 v32, v32
	s_nop 0
	v_mul_f32_e32 v32, v178, v32
	v_pk_mul_f32 v[24:25], v[24:25], v[32:33] op_sel_hi:[1,0]
	v_pk_mul_f32 v[26:27], v[26:27], v[32:33] op_sel_hi:[1,0]
	v_pk_mul_f32 v[30:31], v[30:31], v[32:33] op_sel_hi:[1,0]
	v_pk_mul_f32 v[28:29], v[28:29], v[32:33] op_sel_hi:[1,0]
	v_pk_mul_f32 v[26:27], v[130:131], v[26:27]
	v_pk_mul_f32 v[24:25], v[128:129], v[24:25]
	v_pk_mul_f32 v[28:29], v[132:133], v[28:29]
	v_pk_mul_f32 v[30:31], v[134:135], v[30:31]
	v_pk_mul_f32 v[32:33], v[76:77], v[24:25]
	v_pk_mul_f32 v[34:35], v[78:79], v[26:27]
	v_pk_fma_f32 v[32:33], v[72:73], v[28:29], v[32:33] neg_lo:[0,0,1] neg_hi:[0,0,1]
	v_pk_fma_f32 v[34:35], v[74:75], v[30:31], v[34:35] neg_lo:[0,0,1] neg_hi:[0,0,1]
	v_pk_mul_f32 v[28:29], v[76:77], v[28:29]
	v_pk_mul_f32 v[30:31], v[78:79], v[30:31]
	s_nop 0
	v_pk_fma_f32 v[30:31], v[74:75], v[26:27], v[30:31]
	v_pk_fma_f32 v[26:27], v[72:73], v[24:25], v[28:29]
	v_lshl_add_u64 v[24:25], v[90:91], 0, s[22:23]
	v_lshlrev_b64 v[24:25], 8, v[24:25]
	v_lshl_add_u64 v[28:29], v[188:189], 0, v[24:25]
	v_cvt_pk_bf16_f32 v24, v32, v33
	v_cvt_pk_bf16_f32 v25, v34, v35
	v_cvt_pk_bf16_f32 v26, v26, v27
	v_cvt_pk_bf16_f32 v27, v30, v31
	global_store_dwordx4 v[28:29], v[24:27], off
	s_nop 1
	v_add_u32_e32 v24, s64, v38
	ds_read_b128 v[24:27], v24
	s_waitcnt lgkmcnt(0)
; #define LAS __attribute__((address_space(3)))
;     __device__ __forceinline__ void operator()(const f32x4 (&acc)[2][2][4][2], const pg8::Unit& u, int wr, int wc, int fr_, int fq_) const {
;     ...
;                 for (int m = 0; m < 4; ++m) { const int row = row0 + ai * 128 + m * 16;
;                     const f32x4 c = rc[m], sn = rn[m];
; #pragma unroll
;                     for (int bj = 0; bj < 2; ++bj) {
;                         const f32x4 t = *(const LAS f32x4*)(xch + ((ai * 2 + bj) * 128 + wr * 64 + m * 16 + fr) * 4);
;                         const float rstd = __builtin_amdgcn_rsqf(((t[0] + t[1]) + (t[2] + t[3])) * (1.0f / 128.0f) + RMS_EPS);
;                         const f32x4 y1 = acc[ai][bj][m][0] * (rs[ai][m] * rstd) * g1, y2 = acc[ai][bj][m][1] * (rs[ai][m] * rstd) * g2;
;                         const f32x4 o1 = y1 * c - y2 * sn, o2 = y2 * c + y1 * sn;
;                         bf16_t* ptr = base + ((size_t)(pl * 2 + bj) * S + row) * 128 + 32 * wc + 8 * fq;
;                         *(u32x4*)ptr = pack8bf(o1, o2); }
;                     }
	v_mov_b32_e32 v28, v25
	v_mov_b32_e32 v29, v26
	v_mov_b32_e32 v25, v27
	v_pk_add_f32 v[24:25], v[28:29], v[24:25]
	s_nop 0
	v_add_f32_e32 v24, v24, v25
	v_fmamk_f32 v24, v24, 0x3c000000, v232
	v_rsq_f32_e32 v24, v24
	s_nop 0
	v_mul_f32_e32 v24, v178, v24
	v_pk_mul_f32 v[16:17], v[16:17], v[24:25] op_sel_hi:[1,0]
	v_pk_mul_f32 v[18:19], v[18:19], v[24:25] op_sel_hi:[1,0]
	v_pk_mul_f32 v[22:23], v[22:23], v[24:25] op_sel_hi:[1,0]
	v_pk_mul_f32 v[20:21], v[20:21], v[24:25] op_sel_hi:[1,0]
	v_pk_mul_f32 v[18:19], v[130:131], v[18:19]
	v_pk_mul_f32 v[16:17], v[128:129], v[16:17]
	v_pk_mul_f32 v[20:21], v[132:133], v[20:21]
	v_pk_mul_f32 v[22:23], v[134:135], v[22:23]
	v_pk_mul_f32 v[24:25], v[76:77], v[16:17]
	v_pk_mul_f32 v[26:27], v[78:79], v[18:19]
	v_pk_fma_f32 v[24:25], v[72:73], v[20:21], v[24:25] neg_lo:[0,0,1] neg_hi:[0,0,1]
	v_pk_fma_f32 v[26:27], v[74:75], v[22:23], v[26:27] neg_lo:[0,0,1] neg_hi:[0,0,1]
	v_pk_mul_f32 v[20:21], v[76:77], v[20:21]
	v_pk_mul_f32 v[22:23], v[78:79], v[22:23]
	s_nop 0
	v_pk_fma_f32 v[22:23], v[74:75], v[18:19], v[22:23]
	v_pk_fma_f32 v[18:19], v[72:73], v[16:17], v[20:21]
	v_lshl_add_u64 v[16:17], v[90:91], 0, s[6:7]
	v_lshlrev_b64 v[16:17], 8, v[16:17]
	v_lshl_add_u64 v[20:21], v[188:189], 0, v[16:17]
	v_cvt_pk_bf16_f32 v16, v24, v25
	v_cvt_pk_bf16_f32 v17, v26, v27
	v_cvt_pk_bf16_f32 v18, v18, v19
	v_cvt_pk_bf16_f32 v19, v22, v23
	v_add_u32_e32 v22, 0x1300, v214
	global_store_dwordx4 v[20:21], v[16:19], off
	s_nop 1
	v_add_u32_e32 v16, s8, v22
	ds_read_b128 v[16:19], v16
	s_waitcnt lgkmcnt(0)
	v_mov_b32_e32 v20, v17
	v_mov_b32_e32 v21, v18
	v_mov_b32_e32 v17, v19
	v_pk_add_f32 v[16:17], v[20:21], v[16:17]
	s_nop 0
	v_add_f32_e32 v16, v16, v17
	v_fmamk_f32 v16, v16, 0x3c000000, v232
	v_rsq_f32_e32 v16, v16
	s_nop 0
	v_mul_f32_e32 v16, v179, v16
	v_pk_mul_f32 v[8:9], v[8:9], v[16:17] op_sel_hi:[1,0]
	v_pk_mul_f32 v[10:11], v[10:11], v[16:17] op_sel_hi:[1,0]
	v_pk_mul_f32 v[14:15], v[14:15], v[16:17] op_sel_hi:[1,0]
	v_pk_mul_f32 v[12:13], v[12:13], v[16:17] op_sel_hi:[1,0]
	v_pk_mul_f32 v[10:11], v[130:131], v[10:11]
	v_pk_mul_f32 v[8:9], v[128:129], v[8:9]
	v_pk_mul_f32 v[12:13], v[132:133], v[12:13]
	v_pk_mul_f32 v[14:15], v[134:135], v[14:15]
	s_waitcnt vmcnt(0)
	v_pk_mul_f32 v[16:17], v[68:69], v[8:9]
	v_pk_mul_f32 v[18:19], v[70:71], v[10:11]
	v_pk_fma_f32 v[16:17], v[64:65], v[12:13], v[16:17] neg_lo:[0,0,1] neg_hi:[0,0,1]
	v_pk_fma_f32 v[18:19], v[66:67], v[14:15], v[18:19] neg_lo:[0,0,1] neg_hi:[0,0,1]
	v_pk_mul_f32 v[12:13], v[68:69], v[12:13]
	v_pk_mul_f32 v[14:15], v[70:71], v[14:15]
	s_nop 0
	v_pk_fma_f32 v[14:15], v[66:67], v[10:11], v[14:15]
	v_pk_fma_f32 v[10:11], v[64:65], v[8:9], v[12:13]
	v_lshl_add_u64 v[8:9], v[88:89], 0, s[22:23]
	v_lshlrev_b64 v[8:9], 8, v[8:9]
	v_lshl_add_u64 v[12:13], v[188:189], 0, v[8:9]
	v_cvt_pk_bf16_f32 v8, v16, v17
	v_cvt_pk_bf16_f32 v9, v18, v19
	v_cvt_pk_bf16_f32 v10, v10, v11
	v_cvt_pk_bf16_f32 v11, v14, v15
	global_store_dwordx4 v[12:13], v[8:11], off
	s_nop 1
	v_add_u32_e32 v8, s64, v22
	ds_read_b128 v[8:11], v8
	s_waitcnt lgkmcnt(0)
	v_mov_b32_e32 v12, v9
	v_mov_b32_e32 v13, v10
	v_mov_b32_e32 v9, v11
	v_pk_add_f32 v[8:9], v[12:13], v[8:9]
	s_nop 0
	v_add_f32_e32 v8, v8, v9
	v_fmamk_f32 v8, v8, 0x3c000000, v232
	v_rsq_f32_e32 v8, v8
	s_nop 0
	v_mul_f32_e32 v8, v179, v8
	v_pk_mul_f32 v[0:1], v[0:1], v[8:9] op_sel_hi:[1,0]
	v_pk_mul_f32 v[2:3], v[2:3], v[8:9] op_sel_hi:[1,0]
	v_pk_mul_f32 v[6:7], v[6:7], v[8:9] op_sel_hi:[1,0]
	v_pk_mul_f32 v[4:5], v[4:5], v[8:9] op_sel_hi:[1,0]
	v_pk_mul_f32 v[2:3], v[130:131], v[2:3]
	v_pk_mul_f32 v[0:1], v[128:129], v[0:1]
	v_pk_mul_f32 v[4:5], v[132:133], v[4:5]
	v_pk_mul_f32 v[6:7], v[134:135], v[6:7]
	v_pk_mul_f32 v[8:9], v[68:69], v[0:1]
	v_pk_mul_f32 v[10:11], v[70:71], v[2:3]
	v_pk_fma_f32 v[8:9], v[64:65], v[4:5], v[8:9] neg_lo:[0,0,1] neg_hi:[0,0,1]
	v_pk_fma_f32 v[10:11], v[66:67], v[6:7], v[10:11] neg_lo:[0,0,1] neg_hi:[0,0,1]
	v_pk_mul_f32 v[4:5], v[68:69], v[4:5]
	v_pk_mul_f32 v[6:7], v[70:71], v[6:7]
	s_nop 0
	v_pk_fma_f32 v[6:7], v[66:67], v[2:3], v[6:7]
	v_pk_fma_f32 v[2:3], v[64:65], v[0:1], v[4:5]
	v_lshl_add_u64 v[0:1], v[88:89], 0, s[6:7]
	v_lshlrev_b64 v[0:1], 8, v[0:1]
	v_lshl_add_u64 v[4:5], v[188:189], 0, v[0:1]
	v_cvt_pk_bf16_f32 v0, v8, v9
	v_cvt_pk_bf16_f32 v1, v10, v11
	v_cvt_pk_bf16_f32 v2, v2, v3
	v_cvt_pk_bf16_f32 v3, v6, v7
	global_store_dwordx4 v[4:5], v[0:3], off
	s_andn2_b64 vcc, exec, s[38:39]
	s_mov_b64 s[6:7], -1
	s_cbranch_vccnz .LBB0_61
